# decode stream: next-block index read back late (vmcnt(1) at loop top, vmcnt(17) before the page lookup), on top of v37
# baseline (speedup 1.0000x reference)
; __device__ __forceinline__ void sb_decode_stream(Frame& F, unsigned* qctr, int base, int limit) {
;     ...
;         const int bh = ((it >> 11) << 3) | (it & 7), blk = (it >> 3) & 255, h = it & 7;
;         const unsigned vn = __hip_atomic_fetch_add(qctr, 1u, __ATOMIC_RELAXED, __HIP_MEMORY_SCOPE_AGENT);
;         const float k2 = kin(12)[h] * 1.4426950408889634f;
;         int zi = 0;
;     ...
;         DEC_SCORES(A, 0);
.LBB0_1126:
	s_mov_b64 s[56:57], exec
	v_mbcnt_lo_u32_b32 v134, s56, 0
	v_mbcnt_hi_u32_b32 v134, s57, v134
	v_cmp_eq_u32_e32 vcc, 0, v134
	s_and_saveexec_b64 s[54:55], vcc
	s_cbranch_execz .LBB0_1128
	s_bcnt1_i32_b64 s2, s[56:57]
	v_mov_b32_e32 v135, s2
	global_atomic_add v253, v1, v135, s[40:41] sc0
.LBB0_1128:
	s_or_b64 exec, exec, s[54:55]
	s_waitcnt vmcnt(31)
	v_mul_f32_e32 v131, v131, v3
	v_fmac_f32_e32 v131, v130, v2
	v_mul_f32_e32 v130, v133, v5
	v_fmac_f32_e32 v130, v132, v4
	v_add_f32_e32 v130, v131, v130
	s_waitcnt vmcnt(30)
	v_mul_f32_e32 v127, v127, v3
	v_fmac_f32_e32 v127, v126, v2
	v_add_f32_dpp v130, v130, v130 quad_perm:[1,0,3,2] row_mask:0xf bank_mask:0xf bound_ctrl:1
	v_mul_f32_e32 v126, v129, v5
	v_fmac_f32_e32 v126, v128, v4
	v_add_f32_dpp v130, v130, v130 quad_perm:[2,3,0,1] row_mask:0xf bank_mask:0xf bound_ctrl:1
	s_waitcnt vmcnt(29)
	v_mul_f32_e32 v123, v123, v3
	v_add_f32_e32 v126, v127, v126
	v_add_f32_dpp v130, v130, v130 row_half_mirror row_mask:0xf bank_mask:0xf bound_ctrl:1
	v_fmac_f32_e32 v123, v122, v2
	v_mul_f32_e32 v122, v125, v5
	s_movk_i32 s56, 0x60
	v_add_f32_dpp v131, v130, v130 row_mirror row_mask:0xf bank_mask:0xf bound_ctrl:1
	v_add_f32_dpp v126, v126, v126 quad_perm:[1,0,3,2] row_mask:0xf bank_mask:0xf bound_ctrl:1
	v_fmac_f32_e32 v122, v124, v4
	s_waitcnt vmcnt(28)
	v_mul_f32_e32 v119, v119, v3
	ds_swizzle_b32 v132, v131 offset:swizzle(SWAP,16)
	v_add_f32_dpp v126, v126, v126 quad_perm:[2,3,0,1] row_mask:0xf bank_mask:0xf bound_ctrl:1
	v_add_f32_e32 v122, v123, v122
	v_fmac_f32_e32 v119, v118, v2
	v_mul_f32_e32 v118, v121, v5
	s_load_dwordx2 s[56:57], s[0:1], s56 offset:0x0
	v_add_f32_dpp v126, v126, v126 row_half_mirror row_mask:0xf bank_mask:0xf bound_ctrl:1
	v_add_f32_dpp v122, v122, v122 quad_perm:[1,0,3,2] row_mask:0xf bank_mask:0xf bound_ctrl:1
	v_fmac_f32_e32 v118, v120, v4
	s_waitcnt vmcnt(27)
	v_mul_f32_e32 v115, v115, v3
	v_add_f32_dpp v126, v126, v126 row_mirror row_mask:0xf bank_mask:0xf bound_ctrl:1
	v_add_f32_dpp v122, v122, v122 quad_perm:[2,3,0,1] row_mask:0xf bank_mask:0xf bound_ctrl:1
	v_add_f32_e32 v118, v119, v118
	v_fmac_f32_e32 v115, v114, v2
	v_mul_f32_e32 v114, v117, v5
	s_and_b32 s54, s50, 7
	s_waitcnt vmcnt(1)
	ds_swizzle_b32 v127, v126 offset:swizzle(SWAP,16)
	v_add_f32_dpp v122, v122, v122 row_half_mirror row_mask:0xf bank_mask:0xf bound_ctrl:1
	v_add_f32_dpp v118, v118, v118 quad_perm:[1,0,3,2] row_mask:0xf bank_mask:0xf bound_ctrl:1
	v_fmac_f32_e32 v114, v116, v4
	v_mul_f32_e32 v111, v111, v3
	s_lshl_b32 s2, s54, 2
	v_add_f32_dpp v122, v122, v122 row_mirror row_mask:0xf bank_mask:0xf bound_ctrl:1
	v_add_f32_dpp v118, v118, v118 quad_perm:[2,3,0,1] row_mask:0xf bank_mask:0xf bound_ctrl:1
	v_add_f32_e32 v114, v115, v114
	v_fmac_f32_e32 v111, v110, v2
	v_mul_f32_e32 v110, v113, v5
	v_mov_b32_e32 v130, s2
	s_waitcnt lgkmcnt(0)
	v_add_f32_e32 v131, v131, v132
	ds_swizzle_b32 v123, v122 offset:swizzle(SWAP,16)
	v_add_f32_dpp v118, v118, v118 row_half_mirror row_mask:0xf bank_mask:0xf bound_ctrl:1
	v_add_f32_dpp v114, v114, v114 quad_perm:[1,0,3,2] row_mask:0xf bank_mask:0xf bound_ctrl:1
	v_fmac_f32_e32 v110, v112, v4
	v_mul_f32_e32 v107, v107, v3
	global_load_dword v130, v130, s[56:57]
	v_readlane_b32 s2, v131, 0
	v_readlane_b32 s56, v131, 32
	v_mov_b32_e32 v131, 0
	v_add_f32_dpp v118, v118, v118 row_mirror row_mask:0xf bank_mask:0xf bound_ctrl:1
	v_add_f32_dpp v114, v114, v114 quad_perm:[2,3,0,1] row_mask:0xf bank_mask:0xf bound_ctrl:1
	v_add_f32_e32 v110, v111, v110
	v_fmac_f32_e32 v107, v106, v2
	v_mul_f32_e32 v106, v109, v5
	s_nop 3
	v_writelane_b32 v131, s2, 0
	ds_swizzle_b32 v119, v118 offset:swizzle(SWAP,16)
	v_add_f32_dpp v114, v114, v114 row_half_mirror row_mask:0xf bank_mask:0xf bound_ctrl:1
	v_add_f32_dpp v110, v110, v110 quad_perm:[1,0,3,2] row_mask:0xf bank_mask:0xf bound_ctrl:1
	v_fmac_f32_e32 v106, v108, v4
	v_mul_f32_e32 v103, v103, v3
	v_writelane_b32 v131, s56, 1
	v_add_f32_e32 v126, v126, v127
	v_add_f32_dpp v114, v114, v114 row_mirror row_mask:0xf bank_mask:0xf bound_ctrl:1
	v_add_f32_dpp v110, v110, v110 quad_perm:[2,3,0,1] row_mask:0xf bank_mask:0xf bound_ctrl:1
	v_add_f32_e32 v106, v107, v106
	v_fmac_f32_e32 v103, v102, v2
	v_mul_f32_e32 v102, v105, v5
	v_readlane_b32 s2, v126, 0
	s_nop 3
	v_writelane_b32 v131, s2, 2
	ds_swizzle_b32 v115, v114 offset:swizzle(SWAP,16)
	v_add_f32_dpp v110, v110, v110 row_half_mirror row_mask:0xf bank_mask:0xf bound_ctrl:1
	v_add_f32_dpp v106, v106, v106 quad_perm:[1,0,3,2] row_mask:0xf bank_mask:0xf bound_ctrl:1
	v_fmac_f32_e32 v102, v104, v4
	v_mul_f32_e32 v99, v99, v3
	v_readlane_b32 s56, v126, 32
	v_writelane_b32 v131, s56, 3
	s_waitcnt lgkmcnt(2)
	v_add_f32_e32 v122, v122, v123
	v_add_f32_dpp v110, v110, v110 row_mirror row_mask:0xf bank_mask:0xf bound_ctrl:1
	v_add_f32_dpp v106, v106, v106 quad_perm:[2,3,0,1] row_mask:0xf bank_mask:0xf bound_ctrl:1
	v_add_f32_e32 v102, v103, v102
	v_fmac_f32_e32 v99, v98, v2
	v_mul_f32_e32 v98, v101, v5
	v_readlane_b32 s2, v122, 0
	s_nop 3
	v_writelane_b32 v131, s2, 4
	ds_swizzle_b32 v111, v110 offset:swizzle(SWAP,16)
	v_add_f32_dpp v106, v106, v106 row_half_mirror row_mask:0xf bank_mask:0xf bound_ctrl:1
	v_add_f32_dpp v102, v102, v102 quad_perm:[1,0,3,2] row_mask:0xf bank_mask:0xf bound_ctrl:1
	v_fmac_f32_e32 v98, v100, v4
	v_mul_f32_e32 v95, v95, v3
	v_readlane_b32 s56, v122, 32
	v_writelane_b32 v131, s56, 5
	s_waitcnt lgkmcnt(2)
; __device__ __forceinline__ void sb_decode_stream(Frame& F, unsigned* qctr, int base, int limit) {
;     ...
;         DEC_SCORES(A, 0);
	v_add_f32_e32 v118, v118, v119
	v_add_f32_dpp v106, v106, v106 row_mirror row_mask:0xf bank_mask:0xf bound_ctrl:1
	v_add_f32_dpp v102, v102, v102 quad_perm:[2,3,0,1] row_mask:0xf bank_mask:0xf bound_ctrl:1
	v_add_f32_e32 v98, v99, v98
	v_fmac_f32_e32 v95, v94, v2
	v_mul_f32_e32 v94, v97, v5
	v_readlane_b32 s2, v118, 0
	s_nop 3
	v_writelane_b32 v131, s2, 6
	ds_swizzle_b32 v107, v106 offset:swizzle(SWAP,16)
	v_add_f32_dpp v102, v102, v102 row_half_mirror row_mask:0xf bank_mask:0xf bound_ctrl:1
	v_add_f32_dpp v98, v98, v98 quad_perm:[1,0,3,2] row_mask:0xf bank_mask:0xf bound_ctrl:1
	v_fmac_f32_e32 v94, v96, v4
	v_mul_f32_e32 v91, v91, v3
	v_readlane_b32 s56, v118, 32
	v_writelane_b32 v131, s56, 7
	s_waitcnt lgkmcnt(2)
	v_add_f32_e32 v114, v114, v115
	v_add_f32_dpp v102, v102, v102 row_mirror row_mask:0xf bank_mask:0xf bound_ctrl:1
	v_add_f32_dpp v98, v98, v98 quad_perm:[2,3,0,1] row_mask:0xf bank_mask:0xf bound_ctrl:1
	v_add_f32_e32 v94, v95, v94
	v_fmac_f32_e32 v91, v90, v2
	v_mul_f32_e32 v90, v93, v5
	v_readlane_b32 s2, v114, 0
	s_nop 3
	v_writelane_b32 v131, s2, 8
	ds_swizzle_b32 v103, v102 offset:swizzle(SWAP,16)
	v_add_f32_dpp v98, v98, v98 row_half_mirror row_mask:0xf bank_mask:0xf bound_ctrl:1
	v_add_f32_dpp v94, v94, v94 quad_perm:[1,0,3,2] row_mask:0xf bank_mask:0xf bound_ctrl:1
	v_fmac_f32_e32 v90, v92, v4
	v_mul_f32_e32 v87, v87, v3
	v_readlane_b32 s56, v114, 32
	v_writelane_b32 v131, s56, 9
	s_waitcnt lgkmcnt(2)
	v_add_f32_e32 v110, v110, v111
	v_add_f32_dpp v98, v98, v98 row_mirror row_mask:0xf bank_mask:0xf bound_ctrl:1
	v_add_f32_dpp v94, v94, v94 quad_perm:[2,3,0,1] row_mask:0xf bank_mask:0xf bound_ctrl:1
	v_add_f32_e32 v90, v91, v90
	v_fmac_f32_e32 v87, v86, v2
	v_mul_f32_e32 v86, v89, v5
	v_readlane_b32 s2, v110, 0
	s_nop 3
	v_writelane_b32 v131, s2, 10
	ds_swizzle_b32 v99, v98 offset:swizzle(SWAP,16)
	v_add_f32_dpp v94, v94, v94 row_half_mirror row_mask:0xf bank_mask:0xf bound_ctrl:1
	v_add_f32_dpp v90, v90, v90 quad_perm:[1,0,3,2] row_mask:0xf bank_mask:0xf bound_ctrl:1
	v_fmac_f32_e32 v86, v88, v4
	v_mul_f32_e32 v83, v83, v3
	v_readlane_b32 s56, v110, 32
	v_writelane_b32 v131, s56, 11
	s_waitcnt lgkmcnt(2)
	v_add_f32_e32 v106, v106, v107
	v_add_f32_dpp v94, v94, v94 row_mirror row_mask:0xf bank_mask:0xf bound_ctrl:1
	v_add_f32_dpp v90, v90, v90 quad_perm:[2,3,0,1] row_mask:0xf bank_mask:0xf bound_ctrl:1
	v_add_f32_e32 v86, v87, v86
	v_fmac_f32_e32 v83, v82, v2
	v_mul_f32_e32 v82, v85, v5
	v_readlane_b32 s2, v106, 0
	s_nop 3
	v_writelane_b32 v131, s2, 12
	ds_swizzle_b32 v95, v94 offset:swizzle(SWAP,16)
	v_add_f32_dpp v90, v90, v90 row_half_mirror row_mask:0xf bank_mask:0xf bound_ctrl:1
	v_add_f32_dpp v86, v86, v86 quad_perm:[1,0,3,2] row_mask:0xf bank_mask:0xf bound_ctrl:1
	v_fmac_f32_e32 v82, v84, v4
	v_mul_f32_e32 v75, v75, v3
	v_readlane_b32 s56, v106, 32
	v_writelane_b32 v131, s56, 13
	s_waitcnt lgkmcnt(2)
	v_add_f32_e32 v102, v102, v103
	v_add_f32_dpp v90, v90, v90 row_mirror row_mask:0xf bank_mask:0xf bound_ctrl:1
	v_add_f32_dpp v86, v86, v86 quad_perm:[2,3,0,1] row_mask:0xf bank_mask:0xf bound_ctrl:1
	v_add_f32_e32 v82, v83, v82
	v_fmac_f32_e32 v75, v74, v2
	v_mul_f32_e32 v74, v77, v5
	v_readlane_b32 s2, v102, 0
	s_nop 3
	v_writelane_b32 v131, s2, 14
	ds_swizzle_b32 v91, v90 offset:swizzle(SWAP,16)
	v_add_f32_dpp v86, v86, v86 row_half_mirror row_mask:0xf bank_mask:0xf bound_ctrl:1
	v_add_f32_dpp v82, v82, v82 quad_perm:[1,0,3,2] row_mask:0xf bank_mask:0xf bound_ctrl:1
	v_fmac_f32_e32 v74, v76, v4
	v_mul_f32_e32 v71, v71, v3
	v_readlane_b32 s56, v102, 32
	v_writelane_b32 v131, s56, 15
	s_waitcnt lgkmcnt(2)
	v_add_f32_e32 v98, v98, v99
	v_add_f32_dpp v86, v86, v86 row_mirror row_mask:0xf bank_mask:0xf bound_ctrl:1
	v_add_f32_dpp v82, v82, v82 quad_perm:[2,3,0,1] row_mask:0xf bank_mask:0xf bound_ctrl:1
	v_add_f32_e32 v74, v75, v74
	v_fmac_f32_e32 v71, v70, v2
	v_mul_f32_e32 v70, v73, v5
	v_mul_f32_e32 v63, v63, v3
	v_readlane_b32 s2, v98, 0
	s_nop 3
	v_writelane_b32 v131, s2, 16
	ds_swizzle_b32 v87, v86 offset:swizzle(SWAP,16)
	v_add_f32_dpp v82, v82, v82 row_half_mirror row_mask:0xf bank_mask:0xf bound_ctrl:1
	v_add_f32_dpp v74, v74, v74 quad_perm:[1,0,3,2] row_mask:0xf bank_mask:0xf bound_ctrl:1
	v_fmac_f32_e32 v70, v72, v4
	v_fmac_f32_e32 v63, v62, v2
	v_mul_f32_e32 v62, v65, v5
	v_readlane_b32 s56, v98, 32
	v_writelane_b32 v131, s56, 17
	s_waitcnt lgkmcnt(2)
	v_add_f32_e32 v94, v94, v95
	v_add_f32_dpp v82, v82, v82 row_mirror row_mask:0xf bank_mask:0xf bound_ctrl:1
	v_add_f32_dpp v74, v74, v74 quad_perm:[2,3,0,1] row_mask:0xf bank_mask:0xf bound_ctrl:1
	v_add_f32_e32 v70, v71, v70
	v_fmac_f32_e32 v62, v64, v4
	v_readlane_b32 s2, v94, 0
	s_nop 3
	v_writelane_b32 v131, s2, 18
	ds_swizzle_b32 v83, v82 offset:swizzle(SWAP,16)
	v_add_f32_dpp v74, v74, v74 row_half_mirror row_mask:0xf bank_mask:0xf bound_ctrl:1
	v_add_f32_dpp v70, v70, v70 quad_perm:[1,0,3,2] row_mask:0xf bank_mask:0xf bound_ctrl:1
	v_add_f32_e32 v62, v63, v62
	v_readlane_b32 s56, v94, 32
	v_writelane_b32 v131, s56, 19
	s_waitcnt lgkmcnt(2)
	v_add_f32_e32 v90, v90, v91
	v_add_f32_dpp v74, v74, v74 row_mirror row_mask:0xf bank_mask:0xf bound_ctrl:1
	v_add_f32_dpp v70, v70, v70 quad_perm:[2,3,0,1] row_mask:0xf bank_mask:0xf bound_ctrl:1
	v_add_f32_dpp v62, v62, v62 quad_perm:[1,0,3,2] row_mask:0xf bank_mask:0xf bound_ctrl:1
	v_readlane_b32 s2, v90, 0
	s_nop 3
	v_writelane_b32 v131, s2, 20
	ds_swizzle_b32 v75, v74 offset:swizzle(SWAP,16)
	v_add_f32_dpp v70, v70, v70 row_half_mirror row_mask:0xf bank_mask:0xf bound_ctrl:1
	v_add_f32_dpp v62, v62, v62 quad_perm:[2,3,0,1] row_mask:0xf bank_mask:0xf bound_ctrl:1
	v_readlane_b32 s56, v90, 32
	v_writelane_b32 v131, s56, 21
	s_waitcnt lgkmcnt(2)
; __device__ __forceinline__ void sb_decode_stream(Frame& F, unsigned* qctr, int base, int limit) {
;     ...
;         DEC_SCORES(A, 0);
; #pragma unroll
;         for (int i = 0; i < 16; ++i) A[i] = __builtin_nontemporal_load((const f32x4*)(CV + cb + (size_t)(2 * i) * (NH * HD)));
;         DEC_SCORES(B, 1);
	v_add_f32_e32 v86, v86, v87
	v_add_f32_dpp v70, v70, v70 row_mirror row_mask:0xf bank_mask:0xf bound_ctrl:1
	v_add_f32_dpp v62, v62, v62 row_half_mirror row_mask:0xf bank_mask:0xf bound_ctrl:1
	v_readlane_b32 s2, v86, 0
	s_nop 3
	v_writelane_b32 v131, s2, 22
	ds_swizzle_b32 v71, v70 offset:swizzle(SWAP,16)
	v_add_f32_dpp v62, v62, v62 row_mirror row_mask:0xf bank_mask:0xf bound_ctrl:1
	v_readlane_b32 s56, v86, 32
	v_writelane_b32 v131, s56, 23
	s_waitcnt lgkmcnt(2)
	v_add_f32_e32 v82, v82, v83
	ds_swizzle_b32 v63, v62 offset:swizzle(SWAP,16)
	v_readlane_b32 s2, v82, 0
	s_nop 3
	v_writelane_b32 v131, s2, 24
	v_readlane_b32 s56, v82, 32
	v_writelane_b32 v131, s56, 25
	s_waitcnt lgkmcnt(2)
	v_add_f32_e32 v74, v74, v75
	s_waitcnt lgkmcnt(1)
	v_add_f32_e32 v70, v70, v71
	v_readlane_b32 s2, v74, 0
	s_nop 3
	v_writelane_b32 v131, s2, 26
	v_readlane_b32 s56, v74, 32
	v_writelane_b32 v131, s56, 27
	v_readlane_b32 s2, v70, 0
	v_readlane_b32 s56, v70, 32
	s_nop 3
	v_writelane_b32 v131, s2, 28
	s_waitcnt lgkmcnt(0)
	v_add_f32_e32 v62, v62, v63
	v_lshl_add_u64 v[132:133], v[184:185], 2, s[46:47]
	v_writelane_b32 v131, s56, 29
	v_readlane_b32 s2, v62, 0
	v_readlane_b32 s56, v62, 32
	v_add_co_u32_e32 v62, vcc, s5, v132
	s_nop 3
	v_writelane_b32 v131, s2, 30
	v_mul_f32_e32 v79, v79, v3
	s_nop 0
	v_addc_co_u32_e32 v63, vcc, 0, v133, vcc
	v_writelane_b32 v131, s56, 31
	global_load_dwordx4 v[126:129], v[132:133], off nt
	global_load_dwordx4 v[114:117], v[62:63], off nt
	v_add_co_u32_e32 v62, vcc, s22, v132
	v_fmac_f32_e32 v79, v78, v2
	s_nop 0
	v_addc_co_u32_e32 v63, vcc, 0, v133, vcc
	v_add_co_u32_e32 v64, vcc, s23, v132
	v_mul_f32_e32 v78, v81, v5
	s_nop 0
	v_addc_co_u32_e32 v65, vcc, 0, v133, vcc
	global_load_dwordx4 v[122:125], v[62:63], off nt
	global_load_dwordx4 v[118:121], v[64:65], off nt
	v_add_co_u32_e32 v62, vcc, s28, v132
	v_fmac_f32_e32 v78, v80, v4
	s_nop 0
	v_addc_co_u32_e32 v63, vcc, 0, v133, vcc
	v_add_co_u32_e32 v64, vcc, s29, v132
	v_mul_f32_e32 v67, v67, v3
	s_nop 0
	v_addc_co_u32_e32 v65, vcc, 0, v133, vcc
	global_load_dwordx4 v[102:105], v[62:63], off nt
	global_load_dwordx4 v[106:109], v[64:65], off nt
	v_add_co_u32_e32 v62, vcc, s30, v132
	v_add_f32_e32 v78, v79, v78
	s_nop 0
	v_addc_co_u32_e32 v63, vcc, 0, v133, vcc
	v_add_co_u32_e32 v64, vcc, s31, v132
	v_fmac_f32_e32 v67, v66, v2
	s_nop 0
	v_addc_co_u32_e32 v65, vcc, 0, v133, vcc
	global_load_dwordx4 v[110:113], v[62:63], off nt
	global_load_dwordx4 v[86:89], v[64:65], off nt
	v_add_co_u32_e32 v62, vcc, s33, v132
	v_mul_f32_e32 v66, v69, v5
	s_nop 0
	v_addc_co_u32_e32 v63, vcc, 0, v133, vcc
	v_add_co_u32_e32 v64, vcc, s35, v132
	v_add_f32_dpp v78, v78, v78 quad_perm:[1,0,3,2] row_mask:0xf bank_mask:0xf bound_ctrl:1
	s_nop 0
	v_addc_co_u32_e32 v65, vcc, 0, v133, vcc
	global_load_dwordx4 v[98:101], v[62:63], off nt
	global_load_dwordx4 v[94:97], v[64:65], off nt
	v_add_co_u32_e32 v62, vcc, s36, v132
	v_fmac_f32_e32 v66, v68, v4
	s_nop 0
	v_addc_co_u32_e32 v63, vcc, 0, v133, vcc
	v_add_co_u32_e32 v64, vcc, s37, v132
	v_mul_f32_e32 v59, v59, v3
	s_nop 0
	v_addc_co_u32_e32 v65, vcc, 0, v133, vcc
	v_add_f32_dpp v78, v78, v78 quad_perm:[2,3,0,1] row_mask:0xf bank_mask:0xf bound_ctrl:1
	v_add_f32_e32 v66, v67, v66
	v_fmac_f32_e32 v59, v58, v2
	v_mul_f32_e32 v58, v61, v5
	global_load_dwordx4 v[70:73], v[62:63], off nt
	global_load_dwordx4 v[74:77], v[64:65], off nt
	v_add_co_u32_e32 v62, vcc, s60, v132
	v_add_f32_dpp v78, v78, v78 row_half_mirror row_mask:0xf bank_mask:0xf bound_ctrl:1
	v_add_f32_dpp v66, v66, v66 quad_perm:[1,0,3,2] row_mask:0xf bank_mask:0xf bound_ctrl:1
	v_fmac_f32_e32 v58, v60, v4
	v_mul_f32_e32 v55, v55, v3
	v_addc_co_u32_e32 v63, vcc, 0, v133, vcc
	v_add_f32_dpp v134, v78, v78 row_mirror row_mask:0xf bank_mask:0xf bound_ctrl:1
	v_add_f32_dpp v66, v66, v66 quad_perm:[2,3,0,1] row_mask:0xf bank_mask:0xf bound_ctrl:1
	v_add_f32_e32 v58, v59, v58
	v_fmac_f32_e32 v55, v54, v2
	v_mul_f32_e32 v54, v57, v5
	v_add_co_u32_e32 v64, vcc, s61, v132
	ds_swizzle_b32 v135, v134 offset:swizzle(SWAP,16)
	v_add_f32_dpp v66, v66, v66 row_half_mirror row_mask:0xf bank_mask:0xf bound_ctrl:1
	v_add_f32_dpp v58, v58, v58 quad_perm:[1,0,3,2] row_mask:0xf bank_mask:0xf bound_ctrl:1
	v_fmac_f32_e32 v54, v56, v4
	v_mul_f32_e32 v51, v51, v3
	v_addc_co_u32_e32 v65, vcc, 0, v133, vcc
	v_add_f32_dpp v66, v66, v66 row_mirror row_mask:0xf bank_mask:0xf bound_ctrl:1
	v_add_f32_dpp v58, v58, v58 quad_perm:[2,3,0,1] row_mask:0xf bank_mask:0xf bound_ctrl:1
	v_add_f32_e32 v54, v55, v54
	v_fmac_f32_e32 v51, v50, v2
	v_mul_f32_e32 v50, v53, v5
	v_add_co_u32_e32 v90, vcc, s62, v132
	ds_swizzle_b32 v67, v66 offset:swizzle(SWAP,16)
	v_add_f32_dpp v58, v58, v58 row_half_mirror row_mask:0xf bank_mask:0xf bound_ctrl:1
	v_add_f32_dpp v54, v54, v54 quad_perm:[1,0,3,2] row_mask:0xf bank_mask:0xf bound_ctrl:1
	v_fmac_f32_e32 v50, v52, v4
	v_mul_f32_e32 v47, v47, v3
	v_addc_co_u32_e32 v91, vcc, 0, v133, vcc
	v_add_f32_dpp v58, v58, v58 row_mirror row_mask:0xf bank_mask:0xf bound_ctrl:1
	v_add_f32_dpp v54, v54, v54 quad_perm:[2,3,0,1] row_mask:0xf bank_mask:0xf bound_ctrl:1
	v_add_f32_e32 v50, v51, v50
	v_fmac_f32_e32 v47, v46, v2
	v_mul_f32_e32 v46, v49, v5
	s_ashr_i32 s55, s50, 8
	v_add_co_u32_e32 v78, vcc, s63, v132
	ds_swizzle_b32 v59, v58 offset:swizzle(SWAP,16)
	v_add_f32_dpp v54, v54, v54 row_half_mirror row_mask:0xf bank_mask:0xf bound_ctrl:1
	v_add_f32_dpp v50, v50, v50 quad_perm:[1,0,3,2] row_mask:0xf bank_mask:0xf bound_ctrl:1
	v_fmac_f32_e32 v46, v48, v4
	v_mul_f32_e32 v43, v43, v3
	s_and_b32 s2, s55, -8
	v_addc_co_u32_e32 v79, vcc, 0, v133, vcc
	s_waitcnt lgkmcnt(2)
; __device__ __forceinline__ void sb_decode_stream(Frame& F, unsigned* qctr, int base, int limit) {
;     ...
;         DEC_SCORES(A, 0);
; #pragma unroll
;         for (int i = 0; i < 16; ++i) A[i] = __builtin_nontemporal_load((const f32x4*)(CV + cb + (size_t)(2 * i) * (NH * HD)));
;         DEC_SCORES(B, 1);
	v_add_f32_e32 v134, v134, v135
	v_add_f32_dpp v54, v54, v54 row_mirror row_mask:0xf bank_mask:0xf bound_ctrl:1
	v_add_f32_dpp v50, v50, v50 quad_perm:[2,3,0,1] row_mask:0xf bank_mask:0xf bound_ctrl:1
	v_add_f32_e32 v46, v47, v46
	v_fmac_f32_e32 v43, v42, v2
	v_mul_f32_e32 v42, v45, v5
	global_load_dwordx4 v[82:85], v[62:63], off nt
	s_nop 0
	global_load_dwordx4 v[62:65], v[64:65], off nt
	s_nop 0
	global_load_dwordx4 v[90:93], v[90:91], off nt
	s_nop 0
	global_load_dwordx4 v[78:81], v[78:79], off nt
	s_or_b32 s54, s2, s54
	v_readlane_b32 s2, v134, 0
	s_nop 3
	v_writelane_b32 v131, s2, 32
	ds_swizzle_b32 v55, v54 offset:swizzle(SWAP,16)
	v_add_f32_dpp v50, v50, v50 row_half_mirror row_mask:0xf bank_mask:0xf bound_ctrl:1
	v_add_f32_dpp v46, v46, v46 quad_perm:[1,0,3,2] row_mask:0xf bank_mask:0xf bound_ctrl:1
	v_fmac_f32_e32 v42, v44, v4
	v_mul_f32_e32 v39, v39, v3
	v_readlane_b32 s55, v134, 32
	v_writelane_b32 v131, s55, 33
	s_waitcnt lgkmcnt(2)
	v_add_f32_e32 v66, v66, v67
	v_add_f32_dpp v50, v50, v50 row_mirror row_mask:0xf bank_mask:0xf bound_ctrl:1
	v_add_f32_dpp v46, v46, v46 quad_perm:[2,3,0,1] row_mask:0xf bank_mask:0xf bound_ctrl:1
	v_add_f32_e32 v42, v43, v42
	v_fmac_f32_e32 v39, v38, v2
	v_mul_f32_e32 v38, v41, v5
	v_readlane_b32 s2, v66, 0
	s_nop 3
	v_writelane_b32 v131, s2, 34
	ds_swizzle_b32 v51, v50 offset:swizzle(SWAP,16)
	v_add_f32_dpp v46, v46, v46 row_half_mirror row_mask:0xf bank_mask:0xf bound_ctrl:1
	v_add_f32_dpp v42, v42, v42 quad_perm:[1,0,3,2] row_mask:0xf bank_mask:0xf bound_ctrl:1
	v_fmac_f32_e32 v38, v40, v4
	v_mul_f32_e32 v35, v35, v3
	v_readlane_b32 s55, v66, 32
	v_writelane_b32 v131, s55, 35
	s_waitcnt lgkmcnt(2)
	v_add_f32_e32 v58, v58, v59
	v_add_f32_dpp v46, v46, v46 row_mirror row_mask:0xf bank_mask:0xf bound_ctrl:1
	v_add_f32_dpp v42, v42, v42 quad_perm:[2,3,0,1] row_mask:0xf bank_mask:0xf bound_ctrl:1
	v_add_f32_e32 v38, v39, v38
	v_fmac_f32_e32 v35, v34, v2
	v_mul_f32_e32 v34, v37, v5
	v_readlane_b32 s2, v58, 0
	s_nop 3
	v_writelane_b32 v131, s2, 36
	ds_swizzle_b32 v47, v46 offset:swizzle(SWAP,16)
	v_add_f32_dpp v42, v42, v42 row_half_mirror row_mask:0xf bank_mask:0xf bound_ctrl:1
	v_add_f32_dpp v38, v38, v38 quad_perm:[1,0,3,2] row_mask:0xf bank_mask:0xf bound_ctrl:1
	v_fmac_f32_e32 v34, v36, v4
	v_mul_f32_e32 v31, v31, v3
	v_readlane_b32 s55, v58, 32
	v_writelane_b32 v131, s55, 37
	s_waitcnt lgkmcnt(2)
	v_add_f32_e32 v54, v54, v55
	v_add_f32_dpp v42, v42, v42 row_mirror row_mask:0xf bank_mask:0xf bound_ctrl:1
	v_add_f32_dpp v38, v38, v38 quad_perm:[2,3,0,1] row_mask:0xf bank_mask:0xf bound_ctrl:1
	v_add_f32_e32 v34, v35, v34
	v_fmac_f32_e32 v31, v30, v2
	v_mul_f32_e32 v30, v33, v5
	v_readlane_b32 s2, v54, 0
	s_nop 3
	v_writelane_b32 v131, s2, 38
	ds_swizzle_b32 v43, v42 offset:swizzle(SWAP,16)
	v_add_f32_dpp v38, v38, v38 row_half_mirror row_mask:0xf bank_mask:0xf bound_ctrl:1
	v_add_f32_dpp v34, v34, v34 quad_perm:[1,0,3,2] row_mask:0xf bank_mask:0xf bound_ctrl:1
	v_fmac_f32_e32 v30, v32, v4
	v_mul_f32_e32 v27, v27, v3
	v_readlane_b32 s55, v54, 32
	v_writelane_b32 v131, s55, 39
	s_waitcnt lgkmcnt(2)
	v_add_f32_e32 v50, v50, v51
	v_add_f32_dpp v38, v38, v38 row_mirror row_mask:0xf bank_mask:0xf bound_ctrl:1
	v_add_f32_dpp v34, v34, v34 quad_perm:[2,3,0,1] row_mask:0xf bank_mask:0xf bound_ctrl:1
	v_add_f32_e32 v30, v31, v30
	v_fmac_f32_e32 v27, v26, v2
	v_mul_f32_e32 v26, v29, v5
	v_readlane_b32 s2, v50, 0
	s_nop 3
	v_writelane_b32 v131, s2, 40
	ds_swizzle_b32 v39, v38 offset:swizzle(SWAP,16)
	v_add_f32_dpp v34, v34, v34 row_half_mirror row_mask:0xf bank_mask:0xf bound_ctrl:1
	v_add_f32_dpp v30, v30, v30 quad_perm:[1,0,3,2] row_mask:0xf bank_mask:0xf bound_ctrl:1
	v_fmac_f32_e32 v26, v28, v4
	v_mul_f32_e32 v23, v23, v3
	v_readlane_b32 s55, v50, 32
	v_writelane_b32 v131, s55, 41
	s_waitcnt lgkmcnt(2)
	v_add_f32_e32 v46, v46, v47
	v_add_f32_dpp v34, v34, v34 row_mirror row_mask:0xf bank_mask:0xf bound_ctrl:1
	v_add_f32_dpp v30, v30, v30 quad_perm:[2,3,0,1] row_mask:0xf bank_mask:0xf bound_ctrl:1
	v_add_f32_e32 v26, v27, v26
	v_fmac_f32_e32 v23, v22, v2
	v_mul_f32_e32 v22, v25, v5
	v_readlane_b32 s2, v46, 0
	s_nop 3
	v_writelane_b32 v131, s2, 42
	ds_swizzle_b32 v35, v34 offset:swizzle(SWAP,16)
	v_add_f32_dpp v30, v30, v30 row_half_mirror row_mask:0xf bank_mask:0xf bound_ctrl:1
	v_add_f32_dpp v26, v26, v26 quad_perm:[1,0,3,2] row_mask:0xf bank_mask:0xf bound_ctrl:1
	v_fmac_f32_e32 v22, v24, v4
	v_mul_f32_e32 v19, v19, v3
	v_readlane_b32 s55, v46, 32
	v_writelane_b32 v131, s55, 43
	s_waitcnt lgkmcnt(2)
	v_add_f32_e32 v42, v42, v43
	v_add_f32_dpp v30, v30, v30 row_mirror row_mask:0xf bank_mask:0xf bound_ctrl:1
	v_add_f32_dpp v26, v26, v26 quad_perm:[2,3,0,1] row_mask:0xf bank_mask:0xf bound_ctrl:1
	v_add_f32_e32 v22, v23, v22
	v_fmac_f32_e32 v19, v18, v2
	v_mul_f32_e32 v18, v21, v5
	v_readlane_b32 s2, v42, 0
	s_nop 3
	v_writelane_b32 v131, s2, 44
	ds_swizzle_b32 v31, v30 offset:swizzle(SWAP,16)
	v_add_f32_dpp v26, v26, v26 row_half_mirror row_mask:0xf bank_mask:0xf bound_ctrl:1
	v_add_f32_dpp v22, v22, v22 quad_perm:[1,0,3,2] row_mask:0xf bank_mask:0xf bound_ctrl:1
	v_fmac_f32_e32 v18, v20, v4
	v_mul_f32_e32 v15, v15, v3
	v_readlane_b32 s55, v42, 32
	v_writelane_b32 v131, s55, 45
	s_waitcnt lgkmcnt(2)
	v_add_f32_e32 v38, v38, v39
	v_add_f32_dpp v26, v26, v26 row_mirror row_mask:0xf bank_mask:0xf bound_ctrl:1
	v_add_f32_dpp v22, v22, v22 quad_perm:[2,3,0,1] row_mask:0xf bank_mask:0xf bound_ctrl:1
	v_add_f32_e32 v18, v19, v18
	v_fmac_f32_e32 v15, v14, v2
	v_mul_f32_e32 v14, v17, v5
	v_mul_f32_e32 v11, v11, v3
	v_readlane_b32 s2, v38, 0
	s_nop 3
	v_writelane_b32 v131, s2, 46
	ds_swizzle_b32 v27, v26 offset:swizzle(SWAP,16)
	v_add_f32_dpp v22, v22, v22 row_half_mirror row_mask:0xf bank_mask:0xf bound_ctrl:1
	v_add_f32_dpp v18, v18, v18 quad_perm:[1,0,3,2] row_mask:0xf bank_mask:0xf bound_ctrl:1
	v_fmac_f32_e32 v14, v16, v4
	v_fmac_f32_e32 v11, v10, v2
	v_mul_f32_e32 v10, v13, v5
	v_readlane_b32 s55, v38, 32
	v_writelane_b32 v131, s55, 47
	s_waitcnt lgkmcnt(2)
; __device__ __forceinline__ void sb_decode_stream(Frame& F, unsigned* qctr, int base, int limit) {
;     ...
;         DEC_SCORES(B, 1);
;     ...
; #pragma unroll
;         for (int i = 0; i < 16; ++i) B[i] = __builtin_nontemporal_load((const f32x4*)(CV + cb + (size_t)(32 + 2 * i) * (NH * HD)));
;         const float z = __builtin_bit_cast(float, zi);
;         const float e = __builtin_amdgcn_exp2f(-(z * k1 + k2));
;         const float be = __builtin_amdgcn_rcpf(1.0f + e), m = 1.0f - be;
;         float s = m;
; #pragma unroll
;         for (int o = 1; o < 64; o <<= 1) { const float t = __shfl_down(s, o); if (lane + o < 64) s *= t; }
;         const float tot = __shfl(s, 0);
;         const float sx = __shfl_down(s, 1);
;         const float a = be * (lane < 63 ? sx : 1.0f);
;         int itn = (int)(__builtin_amdgcn_readfirstlane(vn) >> 6); const bool more = itn < limit; itn = more ? itn + base : it;
;         const int bn = itn >> 11, hn = itn & 7, p0n = ((itn >> 3) & 255) * 64;
;         const int pagen = PT[bn * NPAGES + (p0n >> 7)];
	v_add_f32_e32 v34, v34, v35
	v_add_f32_dpp v22, v22, v22 row_mirror row_mask:0xf bank_mask:0xf bound_ctrl:1
	v_add_f32_dpp v18, v18, v18 quad_perm:[2,3,0,1] row_mask:0xf bank_mask:0xf bound_ctrl:1
	v_add_f32_e32 v14, v15, v14
	v_fmac_f32_e32 v10, v12, v4
	v_pk_mul_f32 v[4:5], v[8:9], v[4:5]
	v_pk_mul_f32 v[2:3], v[6:7], v[2:3]
	v_readlane_b32 s2, v34, 0
	s_nop 3
	v_writelane_b32 v131, s2, 48
	ds_swizzle_b32 v23, v22 offset:swizzle(SWAP,16)
	v_add_f32_dpp v18, v18, v18 row_half_mirror row_mask:0xf bank_mask:0xf bound_ctrl:1
	v_add_f32_dpp v14, v14, v14 quad_perm:[1,0,3,2] row_mask:0xf bank_mask:0xf bound_ctrl:1
	v_pk_mov_b32 v[6:7], v[2:3], v[4:5] op_sel:[1,0]
	v_mov_b32_e32 v3, v5
	v_readlane_b32 s55, v34, 32
	v_writelane_b32 v131, s55, 49
	s_waitcnt lgkmcnt(2)
	v_add_f32_e32 v30, v30, v31
	v_add_f32_dpp v18, v18, v18 row_mirror row_mask:0xf bank_mask:0xf bound_ctrl:1
	v_add_f32_dpp v14, v14, v14 quad_perm:[2,3,0,1] row_mask:0xf bank_mask:0xf bound_ctrl:1
	v_add_f32_e32 v10, v11, v10
	v_pk_add_f32 v[2:3], v[6:7], v[2:3]
	v_readlane_b32 s2, v30, 0
	s_nop 3
	v_writelane_b32 v131, s2, 50
	ds_swizzle_b32 v19, v18 offset:swizzle(SWAP,16)
	v_add_f32_dpp v14, v14, v14 row_half_mirror row_mask:0xf bank_mask:0xf bound_ctrl:1
	v_add_f32_dpp v10, v10, v10 quad_perm:[1,0,3,2] row_mask:0xf bank_mask:0xf bound_ctrl:1
	v_add_f32_e32 v2, v2, v3
	v_readlane_b32 s55, v30, 32
	v_writelane_b32 v131, s55, 51
	s_waitcnt lgkmcnt(2)
	v_add_f32_e32 v26, v26, v27
	v_add_f32_dpp v14, v14, v14 row_mirror row_mask:0xf bank_mask:0xf bound_ctrl:1
	v_add_f32_dpp v10, v10, v10 quad_perm:[2,3,0,1] row_mask:0xf bank_mask:0xf bound_ctrl:1
	v_add_f32_dpp v2, v2, v2 quad_perm:[1,0,3,2] row_mask:0xf bank_mask:0xf bound_ctrl:1
	v_readlane_b32 s2, v26, 0
	s_nop 3
	v_writelane_b32 v131, s2, 52
	ds_swizzle_b32 v15, v14 offset:swizzle(SWAP,16)
	v_add_f32_dpp v10, v10, v10 row_half_mirror row_mask:0xf bank_mask:0xf bound_ctrl:1
	v_add_f32_dpp v2, v2, v2 quad_perm:[2,3,0,1] row_mask:0xf bank_mask:0xf bound_ctrl:1
	v_readlane_b32 s55, v26, 32
	v_writelane_b32 v131, s55, 53
	s_waitcnt lgkmcnt(2)
	v_add_f32_e32 v22, v22, v23
	v_add_f32_dpp v10, v10, v10 row_mirror row_mask:0xf bank_mask:0xf bound_ctrl:1
	v_add_f32_dpp v2, v2, v2 row_half_mirror row_mask:0xf bank_mask:0xf bound_ctrl:1
	v_readlane_b32 s2, v22, 0
	s_nop 3
	v_writelane_b32 v131, s2, 54
	ds_swizzle_b32 v11, v10 offset:swizzle(SWAP,16)
	v_add_f32_dpp v2, v2, v2 row_mirror row_mask:0xf bank_mask:0xf bound_ctrl:1
	v_readlane_b32 s55, v22, 32
	v_writelane_b32 v131, s55, 55
	s_waitcnt lgkmcnt(2)
	v_add_f32_e32 v18, v18, v19
	ds_swizzle_b32 v3, v2 offset:swizzle(SWAP,16)
	v_readlane_b32 s2, v18, 0
	s_nop 3
	v_writelane_b32 v131, s2, 56
	v_readlane_b32 s55, v18, 32
	v_writelane_b32 v131, s55, 57
	s_waitcnt lgkmcnt(2)
	v_add_f32_e32 v14, v14, v15
	s_waitcnt lgkmcnt(1)
	v_add_f32_e32 v10, v10, v11
	v_readlane_b32 s2, v14, 0
	s_nop 3
	v_writelane_b32 v131, s2, 58
	v_readlane_b32 s55, v14, 32
	v_writelane_b32 v131, s55, 59
	v_readlane_b32 s2, v10, 0
	v_readlane_b32 s55, v10, 32
	s_nop 3
	v_writelane_b32 v131, s2, 60
	s_waitcnt lgkmcnt(0)
	v_add_f32_e32 v2, v2, v3
	v_writelane_b32 v131, s55, 61
	s_bfe_u32 s80, s50, 0x80003
	v_readlane_b32 s2, v2, 0
	v_readlane_b32 s55, v2, 32
	v_add_co_u32_e32 v2, vcc, s64, v132
	s_nop 3
	v_writelane_b32 v131, s2, 62
	s_waitcnt vmcnt(17)
	v_readfirstlane_b32 s2, v253
	s_nop 0
	v_addc_co_u32_e32 v3, vcc, 0, v133, vcc
	v_add_co_u32_e32 v4, vcc, s65, v132
	v_writelane_b32 v131, s55, 63
	s_ashr_i32 s81, s2, 6
	s_nop 0
	v_addc_co_u32_e32 v5, vcc, 0, v133, vcc
	global_load_dwordx4 v[18:21], v[2:3], off nt
	global_load_dwordx4 v[6:9], v[4:5], off nt
	v_add_co_u32_e32 v2, vcc, s66, v132
	s_cmpk_lt_i32 s81, 0x1800
	s_nop 0
	v_addc_co_u32_e32 v3, vcc, 0, v133, vcc
	v_add_co_u32_e32 v4, vcc, s67, v132
	s_cselect_b64 s[58:59], -1, 0
	s_nop 0
	v_addc_co_u32_e32 v5, vcc, 0, v133, vcc
	global_load_dwordx4 v[14:17], v[2:3], off nt
	global_load_dwordx4 v[10:13], v[4:5], off nt
	v_add_co_u32_e32 v2, vcc, s68, v132
	s_cmpk_gt_i32 s81, 0x17ff
	s_nop 0
	v_addc_co_u32_e32 v3, vcc, 0, v133, vcc
	s_cselect_b64 s[56:57], -1, 0
	s_and_b64 s[82:83], s[58:59], exec
	v_add_co_u32_e32 v4, vcc, s69, v132
	s_cselect_b32 s55, s81, s50
	s_nop 0
	v_addc_co_u32_e32 v5, vcc, 0, v133, vcc
	s_ashr_i32 s50, s55, 11
	global_load_dwordx4 v[138:141], v[2:3], off nt
	global_load_dwordx4 v[142:145], v[4:5], off nt
	v_add_co_u32_e32 v2, vcc, s70, v132
	s_lshl_b32 s82, s50, 7
	s_bfe_u32 s83, s55, 0x70004
	v_addc_co_u32_e32 v3, vcc, 0, v133, vcc
	s_or_b32 s82, s82, s83
	v_add_co_u32_e32 v4, vcc, s71, v132
	s_ashr_i32 s83, s82, 31
	s_nop 0
	v_addc_co_u32_e32 v5, vcc, 0, v133, vcc
	s_and_b32 s2, s55, 7
	s_lshl_b64 s[82:83], s[82:83], 2
	global_load_dwordx4 v[146:149], v[2:3], off nt
	global_load_dwordx4 v[134:137], v[4:5], off nt
	s_waitcnt vmcnt(24)
	v_pk_mul_f32 v[4:5], v[130:131], s[52:53]
	s_add_u32 s82, s48, s82
	v_add_f32_e32 v4, v4, v5
	s_addc_u32 s83, s49, s83
	v_exp_f32_e64 v5, -v4
	global_load_dword v4, v1, s[82:83]
	v_add_co_u32_e32 v2, vcc, s72, v132
	v_add_f32_e32 v5, 1.0, v5
	s_nop 0
	v_addc_co_u32_e32 v3, vcc, 0, v133, vcc
	v_rcp_f32_e32 v5, v5
	v_add_co_u32_e32 v22, vcc, s73, v132
	v_and_b32_e32 v24, 63, v221
	s_nop 0
	v_addc_co_u32_e32 v23, vcc, 0, v133, vcc
	v_cmp_ne_u32_e32 vcc, 63, v24
	global_load_dwordx4 v[154:157], v[2:3], off nt
	global_load_dwordx4 v[150:153], v[22:23], off nt
	v_addc_co_u32_e32 v2, vcc, 0, v221, vcc
	v_sub_f32_e32 v22, 1.0, v5
	v_lshlrev_b32_e32 v25, 2, v2
	ds_bpermute_b32 v23, v25, v22
	v_add_co_u32_e32 v2, vcc, s74, v132
	v_and_b32_e32 v229, 64, v221
	s_nop 0
	v_addc_co_u32_e32 v3, vcc, 0, v133, vcc
	s_waitcnt lgkmcnt(0)
; __device__ __forceinline__ void sb_decode_stream(Frame& F, unsigned* qctr, int base, int limit) {
;     ...
;         const float z = __builtin_bit_cast(float, zi);
;         const float e = __builtin_amdgcn_exp2f(-(z * k1 + k2));
;         const float be = __builtin_amdgcn_rcpf(1.0f + e), m = 1.0f - be;
;         float s = m;
; #pragma unroll
;         for (int o = 1; o < 64; o <<= 1) { const float t = __shfl_down(s, o); if (lane + o < 64) s *= t; }
;         const float tot = __shfl(s, 0);
;         const float sx = __shfl_down(s, 1);
;         const float a = be * (lane < 63 ? sx : 1.0f);
;         int itn = (int)(__builtin_amdgcn_readfirstlane(vn) >> 6); const bool more = itn < limit; itn = more ? itn + base : it;
;         const int bn = itn >> 11, hn = itn & 7, p0n = ((itn >> 3) & 255) * 64;
;         const int pagen = PT[bn * NPAGES + (p0n >> 7)];
;         const size_t cbn = (((size_t)pagen * PAGE + (p0n & 127)) * NH + hn) * HD + lo;
;         const size_t stepn = more ? (size_t)(NH * HD) : 0;
;         f32x4 o4 = {0.f, 0.f, 0.f, 0.f};
; #pragma unroll
;         for (int i = 0; i < 16; ++i) { const float aj = __shfl(a, 2 * i + half); o4 += aj * A[i]; }
;         const f32x4 q4n = *(const f32x4*)(SSP(S_PROJ) + (size_t)bn * IN_COLS + hn * HD + 4 * l32);
	v_mul_f32_e32 v23, v22, v23
	v_cmp_gt_u32_e32 vcc, 62, v24
	v_cndmask_b32_e64 v26, v22, v23, s[6:7]
	s_lshl_b32 s55, s55, 6
	v_cndmask_b32_e64 v22, 0, 2, vcc
	v_add_lshl_u32 v22, v22, v221, 2
	ds_bpermute_b32 v27, v22, v26
	v_add_co_u32_e32 v22, vcc, s75, v132
	s_and_b32 s55, s55, 0x200
	s_nop 0
	v_addc_co_u32_e32 v23, vcc, 0, v133, vcc
	global_load_dwordx4 v[162:165], v[2:3], off nt
	global_load_dwordx4 v[158:161], v[22:23], off nt
	s_waitcnt lgkmcnt(0)
	v_mul_f32_e32 v2, v26, v27
	v_cmp_gt_u32_e32 vcc, 60, v24
	v_cndmask_b32_e64 v22, v26, v2, s[12:13]
	s_mulk_i32 s50, 0x7040
	v_cndmask_b32_e64 v2, 0, 4, vcc
	v_add_lshl_u32 v2, v2, v221, 2
	ds_bpermute_b32 v23, v2, v22
	v_add_co_u32_e32 v2, vcc, s76, v132
	v_or_b32_e32 v228, v229, v207
	s_nop 0
	v_addc_co_u32_e32 v3, vcc, 0, v133, vcc
	s_waitcnt lgkmcnt(0)
	v_mul_f32_e32 v23, v22, v23
	v_cmp_gt_u32_e32 vcc, 56, v24
	v_cndmask_b32_e64 v26, v22, v23, s[14:15]
	v_lshlrev_b32_e32 v228, 2, v228
	v_cndmask_b32_e64 v22, 0, 8, vcc
	v_add_lshl_u32 v22, v22, v221, 2
	ds_bpermute_b32 v27, v22, v26
	v_add_co_u32_e32 v22, vcc, s77, v132
	v_or_b32_e32 v230, v229, v208
	s_nop 0
	v_addc_co_u32_e32 v23, vcc, 0, v133, vcc
	global_load_dwordx4 v[170:173], v[2:3], off nt
	global_load_dwordx4 v[166:169], v[22:23], off nt
	s_waitcnt lgkmcnt(0)
	v_mul_f32_e32 v2, v26, v27
	v_cmp_gt_u32_e32 vcc, 48, v24
	v_cndmask_b32_e64 v22, v26, v2, s[16:17]
	v_lshlrev_b32_e32 v230, 2, v230
	v_cndmask_b32_e64 v2, 0, 16, vcc
	v_add_lshl_u32 v2, v2, v221, 2
	ds_bpermute_b32 v23, v2, v22
	v_add_co_u32_e32 v2, vcc, s78, v132
	v_lshlrev_b32_e32 v231, 2, v229
	s_nop 0
	v_addc_co_u32_e32 v3, vcc, 0, v133, vcc
	s_waitcnt lgkmcnt(0)
	v_mul_f32_e32 v23, v22, v23
	v_cndmask_b32_e64 v24, v22, v23, s[18:19]
	ds_bpermute_b32 v26, v222, v24
	v_add_co_u32_e32 v22, vcc, s79, v132
	v_or_b32_e32 v232, v229, v209
	s_nop 0
	v_addc_co_u32_e32 v23, vcc, 0, v133, vcc
	s_waitcnt lgkmcnt(0)
	v_mul_f32_e32 v26, v24, v26
	v_cndmask_b32_e64 v223, v24, v26, s[20:21]
	ds_bpermute_b32 v24, v25, v223
	global_load_dwordx4 v[178:181], v[2:3], off nt
	global_load_dwordx4 v[174:177], v[22:23], off nt
	v_or_b32_e32 v22, v229, v187
	v_lshlrev_b32_e32 v22, 2, v22
	v_or_b32_e32 v23, v229, v188
	s_waitcnt lgkmcnt(0)
	v_cndmask_b32_e64 v2, 1.0, v24, s[6:7]
	v_mul_f32_e32 v233, v5, v2
	s_waitcnt vmcnt(8)
	v_ashrrev_i32_e32 v5, 31, v4
	v_lshlrev_b64 v[2:3], 10, v[4:5]
	v_or_b32_e32 v4, v229, v186
	v_lshlrev_b32_e32 v4, 2, v4
	ds_bpermute_b32 v4, v4, v233
	ds_bpermute_b32 v22, v22, v233
	v_or_b32_e32 v2, s55, v2
	v_or_b32_e32 v2, s2, v2
	v_lshlrev_b32_e32 v23, 2, v23
	v_lshlrev_b64 v[2:3], 7, v[2:3]
	ds_bpermute_b32 v24, v23, v233
	v_or_b32_e32 v23, v229, v189
	v_lshl_add_u64 v[184:185], v[2:3], 0, v[182:183]
	s_waitcnt lgkmcnt(2)
	v_pk_fma_f32 v[2:3], v[126:127], v[4:5], 0 op_sel_hi:[1,0,0]
	v_pk_fma_f32 v[4:5], v[128:129], v[4:5], 0 op_sel_hi:[1,0,0]
	v_lshlrev_b32_e32 v23, 2, v23
	s_waitcnt lgkmcnt(1)
	v_pk_fma_f32 v[4:5], v[116:117], v[22:23], v[4:5] op_sel_hi:[1,0,1]
	v_pk_fma_f32 v[2:3], v[114:115], v[22:23], v[2:3] op_sel_hi:[1,0,1]
	v_or_b32_e32 v22, v229, v190
	ds_bpermute_b32 v26, v23, v233
	v_lshlrev_b32_e32 v22, 2, v22
	ds_bpermute_b32 v22, v22, v233
	v_or_b32_e32 v23, v229, v191
	v_lshlrev_b32_e32 v23, 2, v23
	s_waitcnt lgkmcnt(2)
	v_pk_fma_f32 v[2:3], v[122:123], v[24:25], v[2:3] op_sel_hi:[1,0,1]
	v_pk_fma_f32 v[4:5], v[124:125], v[24:25], v[4:5] op_sel_hi:[1,0,1]
	ds_bpermute_b32 v24, v23, v233
	v_or_b32_e32 v23, v229, v192
	s_waitcnt lgkmcnt(2)
	v_pk_fma_f32 v[4:5], v[120:121], v[26:27], v[4:5] op_sel_hi:[1,0,1]
	v_pk_fma_f32 v[2:3], v[118:119], v[26:27], v[2:3] op_sel_hi:[1,0,1]
	v_lshlrev_b32_e32 v23, 2, v23
	s_waitcnt lgkmcnt(1)
	v_pk_fma_f32 v[2:3], v[102:103], v[22:23], v[2:3] op_sel_hi:[1,0,1]
	v_pk_fma_f32 v[4:5], v[104:105], v[22:23], v[4:5] op_sel_hi:[1,0,1]
	v_or_b32_e32 v22, v229, v193
	ds_bpermute_b32 v26, v23, v233
	v_lshlrev_b32_e32 v22, 2, v22
	ds_bpermute_b32 v22, v22, v233
	v_or_b32_e32 v23, v229, v194
	v_lshlrev_b32_e32 v23, 2, v23
	s_waitcnt lgkmcnt(2)
	v_pk_fma_f32 v[4:5], v[108:109], v[24:25], v[4:5] op_sel_hi:[1,0,1]
	v_pk_fma_f32 v[2:3], v[106:107], v[24:25], v[2:3] op_sel_hi:[1,0,1]
	ds_bpermute_b32 v24, v23, v233
	v_or_b32_e32 v23, v229, v195
	s_waitcnt lgkmcnt(2)
	v_pk_fma_f32 v[2:3], v[110:111], v[26:27], v[2:3] op_sel_hi:[1,0,1]
	v_pk_fma_f32 v[4:5], v[112:113], v[26:27], v[4:5] op_sel_hi:[1,0,1]
	v_lshlrev_b32_e32 v23, 2, v23
	s_waitcnt lgkmcnt(1)
	v_pk_fma_f32 v[4:5], v[88:89], v[22:23], v[4:5] op_sel_hi:[1,0,1]
	v_pk_fma_f32 v[2:3], v[86:87], v[22:23], v[2:3] op_sel_hi:[1,0,1]
	v_or_b32_e32 v22, v229, v196
	ds_bpermute_b32 v26, v23, v233
	v_lshlrev_b32_e32 v22, 2, v22
	ds_bpermute_b32 v22, v22, v233
	v_or_b32_e32 v23, v229, v197
	v_lshlrev_b32_e32 v23, 2, v23
	s_waitcnt lgkmcnt(2)
	v_pk_fma_f32 v[2:3], v[98:99], v[24:25], v[2:3] op_sel_hi:[1,0,1]
	v_pk_fma_f32 v[4:5], v[100:101], v[24:25], v[4:5] op_sel_hi:[1,0,1]
	ds_bpermute_b32 v24, v23, v233
	v_or_b32_e32 v23, v229, v198
	v_lshlrev_b32_e32 v23, 2, v23
	s_waitcnt lgkmcnt(2)
	v_pk_fma_f32 v[4:5], v[96:97], v[26:27], v[4:5] op_sel_hi:[1,0,1]
	v_pk_fma_f32 v[2:3], v[94:95], v[26:27], v[2:3] op_sel_hi:[1,0,1]
	ds_bpermute_b32 v26, v23, v233
	s_waitcnt lgkmcnt(2)
	v_pk_fma_f32 v[2:3], v[70:71], v[22:23], v[2:3] op_sel_hi:[1,0,1]
	v_pk_fma_f32 v[4:5], v[72:73], v[22:23], v[4:5] op_sel_hi:[1,0,1]
	v_or_b32_e32 v22, v229, v200
	v_or_b32_e32 v23, v229, v201
	v_lshlrev_b32_e32 v22, 2, v22
	v_lshlrev_b32_e32 v23, 2, v23
	s_waitcnt lgkmcnt(1)
; __device__ __forceinline__ void sb_decode_stream(Frame& F, unsigned* qctr, int base, int limit) {
;     ...
;         for (int i = 0; i < 16; ++i) { const float aj = __shfl(a, 2 * i + half); o4 += aj * A[i]; }
;         const f32x4 q4n = *(const f32x4*)(SSP(S_PROJ) + (size_t)bn * IN_COLS + hn * HD + 4 * l32);
; #pragma unroll
;         for (int i = 0; i < 16; ++i) A[i] = __builtin_nontemporal_load((const f32x4*)(CK + cbn + (size_t)(2 * i) * stepn));
; #pragma unroll
;         for (int i = 0; i < 16; ++i) { const float aj = __shfl(a, 32 + 2 * i + half); o4 += aj * B[i]; }
; #pragma unroll
;         for (int i = 0; i < 16; ++i) B[i] = __builtin_nontemporal_load((const f32x4*)(CK + cbn + (size_t)(32 + 2 * i) * stepn));
	v_pk_fma_f32 v[4:5], v[76:77], v[24:25], v[4:5] op_sel_hi:[1,0,1]
	v_pk_fma_f32 v[2:3], v[74:75], v[24:25], v[2:3] op_sel_hi:[1,0,1]
	ds_bpermute_b32 v22, v22, v233
	ds_bpermute_b32 v24, v23, v233
	v_or_b32_e32 v23, v229, v202
	v_lshlrev_b32_e32 v23, 2, v23
	s_ashr_i32 s55, s50, 31
	s_waitcnt lgkmcnt(2)
	v_pk_fma_f32 v[2:3], v[82:83], v[26:27], v[2:3] op_sel_hi:[1,0,1]
	v_pk_fma_f32 v[4:5], v[84:85], v[26:27], v[4:5] op_sel_hi:[1,0,1]
	ds_bpermute_b32 v26, v23, v233
	s_add_u32 s50, s38, s50
	s_addc_u32 s55, s39, s55
	s_lshl_b32 s2, s2, 9
	s_add_u32 s82, s50, s2
	s_waitcnt lgkmcnt(2)
	v_pk_fma_f32 v[4:5], v[64:65], v[22:23], v[4:5] op_sel_hi:[1,0,1]
	v_pk_fma_f32 v[2:3], v[62:63], v[22:23], v[2:3] op_sel_hi:[1,0,1]
	s_addc_u32 s83, s55, 0
	s_waitcnt lgkmcnt(1)
	v_pk_fma_f32 v[2:3], v[90:91], v[24:25], v[2:3] op_sel_hi:[1,0,1]
	v_pk_fma_f32 v[4:5], v[92:93], v[24:25], v[4:5] op_sel_hi:[1,0,1]
	s_and_b64 s[58:59], s[58:59], exec
	s_waitcnt lgkmcnt(0)
	v_pk_fma_f32 v[22:23], v[80:81], v[26:27], v[4:5] op_sel_hi:[1,0,1]
	v_pk_fma_f32 v[24:25], v[78:79], v[26:27], v[2:3] op_sel_hi:[1,0,1]
	v_lshl_add_u64 v[26:27], v[184:185], 2, s[44:45]
	s_cselect_b32 s50, 0x2000, 0
	v_lshl_add_u64 v[28:29], v[26:27], 0, s[50:51]
	global_load_dwordx4 v[2:5], v220, s[82:83]
	global_load_dwordx4 v[130:133], v[26:27], off nt
	global_load_dwordx4 v[126:129], v[28:29], off nt
	v_lshl_add_u64 v[26:27], v[28:29], 0, s[50:51]
	v_lshl_add_u64 v[28:29], v[26:27], 0, s[50:51]
	global_load_dwordx4 v[122:125], v[26:27], off nt
	global_load_dwordx4 v[118:121], v[28:29], off nt
	v_lshl_add_u64 v[26:27], v[28:29], 0, s[50:51]
	v_lshl_add_u64 v[28:29], v[26:27], 0, s[50:51]
	global_load_dwordx4 v[114:117], v[26:27], off nt
	global_load_dwordx4 v[110:113], v[28:29], off nt
	v_lshl_add_u64 v[26:27], v[28:29], 0, s[50:51]
	v_lshl_add_u64 v[28:29], v[26:27], 0, s[50:51]
	global_load_dwordx4 v[106:109], v[26:27], off nt
	global_load_dwordx4 v[102:105], v[28:29], off nt
	v_lshl_add_u64 v[26:27], v[28:29], 0, s[50:51]
	v_or_b32_e32 v28, v229, v203
	v_lshlrev_b32_e32 v28, 2, v28
	ds_bpermute_b32 v28, v28, v233
	global_load_dwordx4 v[98:101], v[26:27], off nt
	v_lshl_add_u64 v[26:27], v[26:27], 0, s[50:51]
	global_load_dwordx4 v[94:97], v[26:27], off nt
	v_lshl_add_u64 v[26:27], v[26:27], 0, s[50:51]
	s_waitcnt lgkmcnt(0)
	v_pk_fma_f32 v[20:21], v[20:21], v[28:29], v[22:23] op_sel_hi:[1,0,1]
	v_or_b32_e32 v22, v229, v204
	v_or_b32_e32 v23, v229, v205
	v_lshlrev_b32_e32 v22, 2, v22
	v_lshlrev_b32_e32 v23, 2, v23
	v_pk_fma_f32 v[18:19], v[18:19], v[28:29], v[24:25] op_sel_hi:[1,0,1]
	ds_bpermute_b32 v22, v22, v233
	ds_bpermute_b32 v24, v23, v233
	v_or_b32_e32 v23, v229, v206
	v_lshlrev_b32_e32 v23, 2, v23
	global_load_dwordx4 v[90:93], v[26:27], off nt
	v_lshl_add_u64 v[26:27], v[26:27], 0, s[50:51]
	ds_bpermute_b32 v28, v23, v233
	global_load_dwordx4 v[86:89], v[26:27], off nt
	v_lshl_add_u64 v[26:27], v[26:27], 0, s[50:51]
	global_load_dwordx4 v[82:85], v[26:27], off nt
	v_lshl_add_u64 v[26:27], v[26:27], 0, s[50:51]
	global_load_dwordx4 v[74:77], v[26:27], off nt
	v_lshl_add_u64 v[26:27], v[26:27], 0, s[50:51]
	s_waitcnt lgkmcnt(2)
	v_pk_fma_f32 v[6:7], v[6:7], v[22:23], v[18:19] op_sel_hi:[1,0,1]
	global_load_dwordx4 v[70:73], v[26:27], off nt
	v_lshl_add_u64 v[26:27], v[26:27], 0, s[50:51]
	s_waitcnt lgkmcnt(1)
	v_pk_fma_f32 v[6:7], v[14:15], v[24:25], v[6:7] op_sel_hi:[1,0,1]
	v_pk_fma_f32 v[8:9], v[8:9], v[22:23], v[20:21] op_sel_hi:[1,0,1]
	s_waitcnt lgkmcnt(0)
	v_pk_fma_f32 v[226:227], v[10:11], v[28:29], v[6:7] op_sel_hi:[1,0,1]
	v_lshl_add_u64 v[6:7], v[26:27], 0, s[50:51]
	global_load_dwordx4 v[78:81], v[6:7], off nt
	v_lshl_add_u64 v[6:7], v[6:7], 0, s[50:51]
	global_load_dwordx4 v[66:69], v[6:7], off nt
	v_lshl_add_u64 v[6:7], v[6:7], 0, s[50:51]
	global_load_dwordx4 v[58:61], v[6:7], off nt
	v_lshl_add_u64 v[6:7], v[6:7], 0, s[50:51]
	global_load_dwordx4 v[54:57], v[6:7], off nt
	v_lshl_add_u64 v[6:7], v[6:7], 0, s[50:51]
	global_load_dwordx4 v[50:53], v[6:7], off nt
	v_lshl_add_u64 v[6:7], v[6:7], 0, s[50:51]
	global_load_dwordx4 v[46:49], v[6:7], off nt
	v_lshl_add_u64 v[6:7], v[6:7], 0, s[50:51]
	global_load_dwordx4 v[42:45], v[6:7], off nt
	v_lshl_add_u64 v[6:7], v[6:7], 0, s[50:51]
	global_load_dwordx4 v[38:41], v[6:7], off nt
	v_lshl_add_u64 v[6:7], v[6:7], 0, s[50:51]
	global_load_dwordx4 v[34:37], v[6:7], off nt
	v_lshl_add_u64 v[6:7], v[6:7], 0, s[50:51]
	v_pk_fma_f32 v[8:9], v[16:17], v[24:25], v[8:9] op_sel_hi:[1,0,1]
	global_load_dwordx4 v[30:33], v[6:7], off nt
	v_lshl_add_u64 v[6:7], v[6:7], 0, s[50:51]
	global_load_dwordx4 v[62:65], v[26:27], off nt
	v_pk_fma_f32 v[224:225], v[12:13], v[28:29], v[8:9] op_sel_hi:[1,0,1]
	global_load_dwordx4 v[26:29], v[6:7], off nt
	v_lshl_add_u64 v[6:7], v[6:7], 0, s[50:51]
	global_load_dwordx4 v[22:25], v[6:7], off nt
	v_lshl_add_u64 v[6:7], v[6:7], 0, s[50:51]
	global_load_dwordx4 v[18:21], v[6:7], off nt
	v_lshl_add_u64 v[6:7], v[6:7], 0, s[50:51]
	global_load_dwordx4 v[14:17], v[6:7], off nt
	v_lshl_add_u64 v[6:7], v[6:7], 0, s[50:51]
	global_load_dwordx4 v[10:13], v[6:7], off nt
	v_lshl_add_u64 v[6:7], v[6:7], 0, s[50:51]
	global_load_dwordx4 v[6:9], v[6:7], off nt
	ds_bpermute_b32 v228, v228, v233
	ds_bpermute_b32 v230, v230, v233
	v_lshlrev_b32_e32 v232, 2, v232
	ds_bpermute_b32 v232, v232, v233
	s_ashr_i32 s55, s54, 31
	s_waitcnt lgkmcnt(2)
; __device__ __forceinline__ void sb_decode_stream(Frame& F, unsigned* qctr, int base, int limit) {
;     ...
;         for (int i = 0; i < 16; ++i) { const float aj = __shfl(a, 32 + 2 * i + half); o4 += aj * B[i]; }
; #pragma unroll
;         for (int i = 0; i < 16; ++i) B[i] = __builtin_nontemporal_load((const f32x4*)(CK + cbn + (size_t)(32 + 2 * i) * stepn));
;         o4.x += __shfl_xor(o4.x, 32); o4.y += __shfl_xor(o4.y, 32); o4.z += __shfl_xor(o4.z, 32); o4.w += __shfl_xor(o4.w, 32);
;         float* P = SSP(S_PART) + ((size_t)bh * DSEG + blk) * DPART;
;         if (half == 0) *(f32x4*)(P + 4 * l32) = o4; if (lane == 0) P[128] = tot;
;         if (!more) break;
	v_pk_fma_f32 v[138:139], v[138:139], v[228:229], v[226:227] op_sel_hi:[1,0,1]
	v_pk_fma_f32 v[140:141], v[140:141], v[228:229], v[224:225] op_sel_hi:[1,0,1]
	s_waitcnt lgkmcnt(1)
	v_pk_fma_f32 v[138:139], v[142:143], v[230:231], v[138:139] op_sel_hi:[1,0,1]
	v_or_b32_e32 v142, v229, v210
	v_lshlrev_b32_e32 v142, 2, v142
	ds_bpermute_b32 v142, v142, v233
	v_or_b32_e32 v143, v229, v211
	v_lshlrev_b32_e32 v143, 2, v143
	v_pk_fma_f32 v[140:141], v[144:145], v[230:231], v[140:141] op_sel_hi:[1,0,1]
	ds_bpermute_b32 v144, v143, v233
	v_or_b32_e32 v143, v229, v212
	s_waitcnt lgkmcnt(2)
	v_pk_fma_f32 v[138:139], v[146:147], v[232:233], v[138:139] op_sel_hi:[1,0,1]
	v_lshlrev_b32_e32 v143, 2, v143
	s_waitcnt lgkmcnt(1)
	v_pk_fma_f32 v[134:135], v[134:135], v[142:143], v[138:139] op_sel_hi:[1,0,1]
	v_or_b32_e32 v138, v229, v213
	ds_bpermute_b32 v146, v143, v233
	v_lshlrev_b32_e32 v138, 2, v138
	ds_bpermute_b32 v138, v138, v233
	v_pk_fma_f32 v[140:141], v[148:149], v[232:233], v[140:141] op_sel_hi:[1,0,1]
	v_or_b32_e32 v139, v229, v214
	v_pk_fma_f32 v[136:137], v[136:137], v[142:143], v[140:141] op_sel_hi:[1,0,1]
	v_lshlrev_b32_e32 v139, 2, v139
	s_waitcnt vmcnt(40) lgkmcnt(2)
	v_pk_fma_f32 v[134:135], v[154:155], v[144:145], v[134:135] op_sel_hi:[1,0,1]
	v_pk_fma_f32 v[136:137], v[156:157], v[144:145], v[136:137] op_sel_hi:[1,0,1]
	ds_bpermute_b32 v140, v139, v233
	v_or_b32_e32 v139, v229, v215
	s_waitcnt vmcnt(39) lgkmcnt(2)
	v_pk_fma_f32 v[136:137], v[152:153], v[146:147], v[136:137] op_sel_hi:[1,0,1]
	v_pk_fma_f32 v[134:135], v[150:151], v[146:147], v[134:135] op_sel_hi:[1,0,1]
	v_lshlrev_b32_e32 v139, 2, v139
	ds_bpermute_b32 v142, v139, v233
	s_waitcnt vmcnt(38) lgkmcnt(2)
	v_pk_fma_f32 v[134:135], v[162:163], v[138:139], v[134:135] op_sel_hi:[1,0,1]
	v_pk_fma_f32 v[136:137], v[164:165], v[138:139], v[136:137] op_sel_hi:[1,0,1]
	v_or_b32_e32 v138, v229, v216
	v_lshlrev_b32_e32 v138, 2, v138
	v_or_b32_e32 v139, v229, v218
	ds_bpermute_b32 v138, v138, v233
	v_lshlrev_b32_e32 v139, 2, v139
	s_waitcnt vmcnt(37) lgkmcnt(2)
	v_pk_fma_f32 v[136:137], v[160:161], v[140:141], v[136:137] op_sel_hi:[1,0,1]
	v_pk_fma_f32 v[134:135], v[158:159], v[140:141], v[134:135] op_sel_hi:[1,0,1]
	ds_bpermute_b32 v140, v139, v233
	v_or_b32_e32 v139, v229, v219
	v_lshlrev_b32_e32 v139, 2, v139
	s_waitcnt vmcnt(36) lgkmcnt(2)
	v_pk_fma_f32 v[134:135], v[170:171], v[142:143], v[134:135] op_sel_hi:[1,0,1]
	v_pk_fma_f32 v[136:137], v[172:173], v[142:143], v[136:137] op_sel_hi:[1,0,1]
	ds_bpermute_b32 v142, v139, v233
	s_waitcnt vmcnt(35) lgkmcnt(2)
	v_pk_fma_f32 v[136:137], v[168:169], v[138:139], v[136:137] op_sel_hi:[1,0,1]
	v_pk_fma_f32 v[134:135], v[166:167], v[138:139], v[134:135] op_sel_hi:[1,0,1]
	v_xor_b32_e32 v138, 32, v221
	v_add_u32_e32 v139, 64, v229
	v_cmp_lt_i32_e32 vcc, v138, v139
	s_waitcnt vmcnt(34) lgkmcnt(1)
	v_pk_fma_f32 v[134:135], v[178:179], v[140:141], v[134:135] op_sel_hi:[1,0,1]
	v_pk_fma_f32 v[136:137], v[180:181], v[140:141], v[136:137] op_sel_hi:[1,0,1]
	v_cndmask_b32_e32 v138, v221, v138, vcc
	s_waitcnt vmcnt(33) lgkmcnt(0)
	v_pk_fma_f32 v[136:137], v[176:177], v[142:143], v[136:137] op_sel_hi:[1,0,1]
	v_pk_fma_f32 v[134:135], v[174:175], v[142:143], v[134:135] op_sel_hi:[1,0,1]
	v_lshlrev_b32_e32 v141, 2, v138
	s_lshl_b64 s[54:55], s[54:55], 8
	ds_bpermute_b32 v142, v231, v223
	ds_bpermute_b32 v138, v141, v134
	ds_bpermute_b32 v139, v141, v135
	ds_bpermute_b32 v140, v141, v136
	ds_bpermute_b32 v141, v141, v137
	s_or_b32 s2, s54, s80
	s_mul_i32 s50, s55, 0x210
	s_mul_hi_u32 s54, s2, 0x210
	s_add_i32 s50, s54, s50
	s_mulk_i32 s2, 0x210
	s_add_u32 s54, s3, s2
	s_addc_u32 s55, s4, s50
	s_and_saveexec_b64 s[58:59], s[8:9]
	s_cbranch_execz .LBB0_1130
	s_waitcnt lgkmcnt(0)
	v_pk_add_f32 v[136:137], v[136:137], v[140:141]
	v_pk_add_f32 v[134:135], v[134:135], v[138:139]
	global_store_dwordx4 v220, v[134:137], s[54:55]
	s_or_b64 exec, exec, s[58:59]
	s_and_saveexec_b64 s[58:59], s[10:11]
	s_cbranch_execz .LBB0_1125
	s_branch .LBB0_1131

; __device__ __forceinline__ void sb_decode_stream(Frame& F, unsigned* qctr, int base, int limit) {
;     ...
;         const int bh = ((it >> 11) << 3) | (it & 7), blk = (it >> 3) & 255, h = it & 7;
;         const unsigned vn = __hip_atomic_fetch_add(qctr, 1u, __ATOMIC_RELAXED, __HIP_MEMORY_SCOPE_AGENT);
;         const float k2 = kin(12)[h] * 1.4426950408889634f;
;         int zi = 0;
;     ...
;         DEC_SCORES(A, 0);
.LBB0_1300:
	s_mov_b64 s[54:55], exec
	v_mbcnt_lo_u32_b32 v134, s54, 0
	v_mbcnt_hi_u32_b32 v134, s55, v134
	v_cmp_eq_u32_e32 vcc, 0, v134
	s_and_saveexec_b64 s[52:53], vcc
	s_cbranch_execz .LBB0_1302
	s_bcnt1_i32_b64 s2, s[54:55]
	v_mov_b32_e32 v135, s2
	global_atomic_add v253, v1, v135, s[40:41] sc0
.LBB0_1302:
	s_or_b64 exec, exec, s[52:53]
	s_waitcnt vmcnt(31)
	v_mul_f32_e32 v131, v131, v3
	v_fmac_f32_e32 v131, v130, v2
	v_mul_f32_e32 v130, v133, v5
	v_fmac_f32_e32 v130, v132, v4
	v_add_f32_e32 v130, v131, v130
	s_waitcnt vmcnt(30)
	v_mul_f32_e32 v127, v127, v3
	v_fmac_f32_e32 v127, v126, v2
	v_add_f32_dpp v130, v130, v130 quad_perm:[1,0,3,2] row_mask:0xf bank_mask:0xf bound_ctrl:1
	v_mul_f32_e32 v126, v129, v5
	v_fmac_f32_e32 v126, v128, v4
	v_add_f32_dpp v130, v130, v130 quad_perm:[2,3,0,1] row_mask:0xf bank_mask:0xf bound_ctrl:1
	s_waitcnt vmcnt(29)
	v_mul_f32_e32 v123, v123, v3
	v_add_f32_e32 v126, v127, v126
	v_add_f32_dpp v130, v130, v130 row_half_mirror row_mask:0xf bank_mask:0xf bound_ctrl:1
	v_fmac_f32_e32 v123, v122, v2
	v_mul_f32_e32 v122, v125, v5
	s_movk_i32 s54, 0x60
	v_add_f32_dpp v131, v130, v130 row_mirror row_mask:0xf bank_mask:0xf bound_ctrl:1
	v_add_f32_dpp v126, v126, v126 quad_perm:[1,0,3,2] row_mask:0xf bank_mask:0xf bound_ctrl:1
	v_fmac_f32_e32 v122, v124, v4
	s_waitcnt vmcnt(28)
	v_mul_f32_e32 v119, v119, v3
	ds_swizzle_b32 v132, v131 offset:swizzle(SWAP,16)
	v_add_f32_dpp v126, v126, v126 quad_perm:[2,3,0,1] row_mask:0xf bank_mask:0xf bound_ctrl:1
	v_add_f32_e32 v122, v123, v122
	v_fmac_f32_e32 v119, v118, v2
	v_mul_f32_e32 v118, v121, v5
	s_load_dwordx2 s[54:55], s[0:1], s54 offset:0x0
	v_add_f32_dpp v126, v126, v126 row_half_mirror row_mask:0xf bank_mask:0xf bound_ctrl:1
	v_add_f32_dpp v122, v122, v122 quad_perm:[1,0,3,2] row_mask:0xf bank_mask:0xf bound_ctrl:1
	v_fmac_f32_e32 v118, v120, v4
	s_waitcnt vmcnt(27)
	v_mul_f32_e32 v115, v115, v3
	v_add_f32_dpp v126, v126, v126 row_mirror row_mask:0xf bank_mask:0xf bound_ctrl:1
	v_add_f32_dpp v122, v122, v122 quad_perm:[2,3,0,1] row_mask:0xf bank_mask:0xf bound_ctrl:1
	v_add_f32_e32 v118, v119, v118
	v_fmac_f32_e32 v115, v114, v2
	v_mul_f32_e32 v114, v117, v5
	s_and_b32 s52, s48, 7
	s_waitcnt vmcnt(1)
	ds_swizzle_b32 v127, v126 offset:swizzle(SWAP,16)
	v_add_f32_dpp v122, v122, v122 row_half_mirror row_mask:0xf bank_mask:0xf bound_ctrl:1
	v_add_f32_dpp v118, v118, v118 quad_perm:[1,0,3,2] row_mask:0xf bank_mask:0xf bound_ctrl:1
	v_fmac_f32_e32 v114, v116, v4
	v_mul_f32_e32 v111, v111, v3
	s_lshl_b32 s2, s52, 2
	v_add_f32_dpp v122, v122, v122 row_mirror row_mask:0xf bank_mask:0xf bound_ctrl:1
	v_add_f32_dpp v118, v118, v118 quad_perm:[2,3,0,1] row_mask:0xf bank_mask:0xf bound_ctrl:1
	v_add_f32_e32 v114, v115, v114
	v_fmac_f32_e32 v111, v110, v2
	v_mul_f32_e32 v110, v113, v5
	v_mov_b32_e32 v130, s2
	s_waitcnt lgkmcnt(0)
	v_add_f32_e32 v131, v131, v132
	ds_swizzle_b32 v123, v122 offset:swizzle(SWAP,16)
	v_add_f32_dpp v118, v118, v118 row_half_mirror row_mask:0xf bank_mask:0xf bound_ctrl:1
	v_add_f32_dpp v114, v114, v114 quad_perm:[1,0,3,2] row_mask:0xf bank_mask:0xf bound_ctrl:1
	v_fmac_f32_e32 v110, v112, v4
	v_mul_f32_e32 v107, v107, v3
	global_load_dword v130, v130, s[54:55]
	v_readlane_b32 s2, v131, 0
	v_readlane_b32 s54, v131, 32
	v_mov_b32_e32 v131, 0
	v_add_f32_dpp v118, v118, v118 row_mirror row_mask:0xf bank_mask:0xf bound_ctrl:1
	v_add_f32_dpp v114, v114, v114 quad_perm:[2,3,0,1] row_mask:0xf bank_mask:0xf bound_ctrl:1
	v_add_f32_e32 v110, v111, v110
	v_fmac_f32_e32 v107, v106, v2
	v_mul_f32_e32 v106, v109, v5
	s_nop 3
	v_writelane_b32 v131, s2, 0
	ds_swizzle_b32 v119, v118 offset:swizzle(SWAP,16)
	v_add_f32_dpp v114, v114, v114 row_half_mirror row_mask:0xf bank_mask:0xf bound_ctrl:1
	v_add_f32_dpp v110, v110, v110 quad_perm:[1,0,3,2] row_mask:0xf bank_mask:0xf bound_ctrl:1
	v_fmac_f32_e32 v106, v108, v4
	v_mul_f32_e32 v103, v103, v3
	v_writelane_b32 v131, s54, 1
	v_add_f32_e32 v126, v126, v127
	v_add_f32_dpp v114, v114, v114 row_mirror row_mask:0xf bank_mask:0xf bound_ctrl:1
	v_add_f32_dpp v110, v110, v110 quad_perm:[2,3,0,1] row_mask:0xf bank_mask:0xf bound_ctrl:1
	v_add_f32_e32 v106, v107, v106
	v_fmac_f32_e32 v103, v102, v2
	v_mul_f32_e32 v102, v105, v5
	v_readlane_b32 s2, v126, 0
	s_nop 3
	v_writelane_b32 v131, s2, 2
	ds_swizzle_b32 v115, v114 offset:swizzle(SWAP,16)
	v_add_f32_dpp v110, v110, v110 row_half_mirror row_mask:0xf bank_mask:0xf bound_ctrl:1
	v_add_f32_dpp v106, v106, v106 quad_perm:[1,0,3,2] row_mask:0xf bank_mask:0xf bound_ctrl:1
	v_fmac_f32_e32 v102, v104, v4
	v_mul_f32_e32 v99, v99, v3
	v_readlane_b32 s54, v126, 32
	v_writelane_b32 v131, s54, 3
	s_waitcnt lgkmcnt(2)
	v_add_f32_e32 v122, v122, v123
	v_add_f32_dpp v110, v110, v110 row_mirror row_mask:0xf bank_mask:0xf bound_ctrl:1
	v_add_f32_dpp v106, v106, v106 quad_perm:[2,3,0,1] row_mask:0xf bank_mask:0xf bound_ctrl:1
	v_add_f32_e32 v102, v103, v102
	v_fmac_f32_e32 v99, v98, v2
	v_mul_f32_e32 v98, v101, v5
	v_readlane_b32 s2, v122, 0
	s_nop 3
	v_writelane_b32 v131, s2, 4
	ds_swizzle_b32 v111, v110 offset:swizzle(SWAP,16)
	v_add_f32_dpp v106, v106, v106 row_half_mirror row_mask:0xf bank_mask:0xf bound_ctrl:1
	v_add_f32_dpp v102, v102, v102 quad_perm:[1,0,3,2] row_mask:0xf bank_mask:0xf bound_ctrl:1
	v_fmac_f32_e32 v98, v100, v4
	v_mul_f32_e32 v95, v95, v3
	v_readlane_b32 s54, v122, 32
	v_writelane_b32 v131, s54, 5
	s_waitcnt lgkmcnt(2)
; __device__ __forceinline__ void sb_decode_stream(Frame& F, unsigned* qctr, int base, int limit) {
;     ...
;         DEC_SCORES(A, 0);
	v_add_f32_e32 v118, v118, v119
	v_add_f32_dpp v106, v106, v106 row_mirror row_mask:0xf bank_mask:0xf bound_ctrl:1
	v_add_f32_dpp v102, v102, v102 quad_perm:[2,3,0,1] row_mask:0xf bank_mask:0xf bound_ctrl:1
	v_add_f32_e32 v98, v99, v98
	v_fmac_f32_e32 v95, v94, v2
	v_mul_f32_e32 v94, v97, v5
	v_readlane_b32 s2, v118, 0
	s_nop 3
	v_writelane_b32 v131, s2, 6
	ds_swizzle_b32 v107, v106 offset:swizzle(SWAP,16)
	v_add_f32_dpp v102, v102, v102 row_half_mirror row_mask:0xf bank_mask:0xf bound_ctrl:1
	v_add_f32_dpp v98, v98, v98 quad_perm:[1,0,3,2] row_mask:0xf bank_mask:0xf bound_ctrl:1
	v_fmac_f32_e32 v94, v96, v4
	v_mul_f32_e32 v91, v91, v3
	v_readlane_b32 s54, v118, 32
	v_writelane_b32 v131, s54, 7
	s_waitcnt lgkmcnt(2)
	v_add_f32_e32 v114, v114, v115
	v_add_f32_dpp v102, v102, v102 row_mirror row_mask:0xf bank_mask:0xf bound_ctrl:1
	v_add_f32_dpp v98, v98, v98 quad_perm:[2,3,0,1] row_mask:0xf bank_mask:0xf bound_ctrl:1
	v_add_f32_e32 v94, v95, v94
	v_fmac_f32_e32 v91, v90, v2
	v_mul_f32_e32 v90, v93, v5
	v_readlane_b32 s2, v114, 0
	s_nop 3
	v_writelane_b32 v131, s2, 8
	ds_swizzle_b32 v103, v102 offset:swizzle(SWAP,16)
	v_add_f32_dpp v98, v98, v98 row_half_mirror row_mask:0xf bank_mask:0xf bound_ctrl:1
	v_add_f32_dpp v94, v94, v94 quad_perm:[1,0,3,2] row_mask:0xf bank_mask:0xf bound_ctrl:1
	v_fmac_f32_e32 v90, v92, v4
	v_mul_f32_e32 v87, v87, v3
	v_readlane_b32 s54, v114, 32
	v_writelane_b32 v131, s54, 9
	s_waitcnt lgkmcnt(2)
	v_add_f32_e32 v110, v110, v111
	v_add_f32_dpp v98, v98, v98 row_mirror row_mask:0xf bank_mask:0xf bound_ctrl:1
	v_add_f32_dpp v94, v94, v94 quad_perm:[2,3,0,1] row_mask:0xf bank_mask:0xf bound_ctrl:1
	v_add_f32_e32 v90, v91, v90
	v_fmac_f32_e32 v87, v86, v2
	v_mul_f32_e32 v86, v89, v5
	v_readlane_b32 s2, v110, 0
	s_nop 3
	v_writelane_b32 v131, s2, 10
	ds_swizzle_b32 v99, v98 offset:swizzle(SWAP,16)
	v_add_f32_dpp v94, v94, v94 row_half_mirror row_mask:0xf bank_mask:0xf bound_ctrl:1
	v_add_f32_dpp v90, v90, v90 quad_perm:[1,0,3,2] row_mask:0xf bank_mask:0xf bound_ctrl:1
	v_fmac_f32_e32 v86, v88, v4
	v_mul_f32_e32 v83, v83, v3
	v_readlane_b32 s54, v110, 32
	v_writelane_b32 v131, s54, 11
	s_waitcnt lgkmcnt(2)
	v_add_f32_e32 v106, v106, v107
	v_add_f32_dpp v94, v94, v94 row_mirror row_mask:0xf bank_mask:0xf bound_ctrl:1
	v_add_f32_dpp v90, v90, v90 quad_perm:[2,3,0,1] row_mask:0xf bank_mask:0xf bound_ctrl:1
	v_add_f32_e32 v86, v87, v86
	v_fmac_f32_e32 v83, v82, v2
	v_mul_f32_e32 v82, v85, v5
	v_readlane_b32 s2, v106, 0
	s_nop 3
	v_writelane_b32 v131, s2, 12
	ds_swizzle_b32 v95, v94 offset:swizzle(SWAP,16)
	v_add_f32_dpp v90, v90, v90 row_half_mirror row_mask:0xf bank_mask:0xf bound_ctrl:1
	v_add_f32_dpp v86, v86, v86 quad_perm:[1,0,3,2] row_mask:0xf bank_mask:0xf bound_ctrl:1
	v_fmac_f32_e32 v82, v84, v4
	v_mul_f32_e32 v75, v75, v3
	v_readlane_b32 s54, v106, 32
	v_writelane_b32 v131, s54, 13
	s_waitcnt lgkmcnt(2)
	v_add_f32_e32 v102, v102, v103
	v_add_f32_dpp v90, v90, v90 row_mirror row_mask:0xf bank_mask:0xf bound_ctrl:1
	v_add_f32_dpp v86, v86, v86 quad_perm:[2,3,0,1] row_mask:0xf bank_mask:0xf bound_ctrl:1
	v_add_f32_e32 v82, v83, v82
	v_fmac_f32_e32 v75, v74, v2
	v_mul_f32_e32 v74, v77, v5
	v_readlane_b32 s2, v102, 0
	s_nop 3
	v_writelane_b32 v131, s2, 14
	ds_swizzle_b32 v91, v90 offset:swizzle(SWAP,16)
	v_add_f32_dpp v86, v86, v86 row_half_mirror row_mask:0xf bank_mask:0xf bound_ctrl:1
	v_add_f32_dpp v82, v82, v82 quad_perm:[1,0,3,2] row_mask:0xf bank_mask:0xf bound_ctrl:1
	v_fmac_f32_e32 v74, v76, v4
	v_mul_f32_e32 v71, v71, v3
	v_readlane_b32 s54, v102, 32
	v_writelane_b32 v131, s54, 15
	s_waitcnt lgkmcnt(2)
	v_add_f32_e32 v98, v98, v99
	v_add_f32_dpp v86, v86, v86 row_mirror row_mask:0xf bank_mask:0xf bound_ctrl:1
	v_add_f32_dpp v82, v82, v82 quad_perm:[2,3,0,1] row_mask:0xf bank_mask:0xf bound_ctrl:1
	v_add_f32_e32 v74, v75, v74
	v_fmac_f32_e32 v71, v70, v2
	v_mul_f32_e32 v70, v73, v5
	v_mul_f32_e32 v63, v63, v3
	v_readlane_b32 s2, v98, 0
	s_nop 3
	v_writelane_b32 v131, s2, 16
	ds_swizzle_b32 v87, v86 offset:swizzle(SWAP,16)
	v_add_f32_dpp v82, v82, v82 row_half_mirror row_mask:0xf bank_mask:0xf bound_ctrl:1
	v_add_f32_dpp v74, v74, v74 quad_perm:[1,0,3,2] row_mask:0xf bank_mask:0xf bound_ctrl:1
	v_fmac_f32_e32 v70, v72, v4
	v_fmac_f32_e32 v63, v62, v2
	v_mul_f32_e32 v62, v65, v5
	v_readlane_b32 s54, v98, 32
	v_writelane_b32 v131, s54, 17
	s_waitcnt lgkmcnt(2)
	v_add_f32_e32 v94, v94, v95
	v_add_f32_dpp v82, v82, v82 row_mirror row_mask:0xf bank_mask:0xf bound_ctrl:1
	v_add_f32_dpp v74, v74, v74 quad_perm:[2,3,0,1] row_mask:0xf bank_mask:0xf bound_ctrl:1
	v_add_f32_e32 v70, v71, v70
	v_fmac_f32_e32 v62, v64, v4
	v_readlane_b32 s2, v94, 0
	s_nop 3
	v_writelane_b32 v131, s2, 18
	ds_swizzle_b32 v83, v82 offset:swizzle(SWAP,16)
	v_add_f32_dpp v74, v74, v74 row_half_mirror row_mask:0xf bank_mask:0xf bound_ctrl:1
	v_add_f32_dpp v70, v70, v70 quad_perm:[1,0,3,2] row_mask:0xf bank_mask:0xf bound_ctrl:1
	v_add_f32_e32 v62, v63, v62
	v_readlane_b32 s54, v94, 32
	v_writelane_b32 v131, s54, 19
	s_waitcnt lgkmcnt(2)
	v_add_f32_e32 v90, v90, v91
	v_add_f32_dpp v74, v74, v74 row_mirror row_mask:0xf bank_mask:0xf bound_ctrl:1
	v_add_f32_dpp v70, v70, v70 quad_perm:[2,3,0,1] row_mask:0xf bank_mask:0xf bound_ctrl:1
	v_add_f32_dpp v62, v62, v62 quad_perm:[1,0,3,2] row_mask:0xf bank_mask:0xf bound_ctrl:1
	v_readlane_b32 s2, v90, 0
	s_nop 3
	v_writelane_b32 v131, s2, 20
	ds_swizzle_b32 v75, v74 offset:swizzle(SWAP,16)
	v_add_f32_dpp v70, v70, v70 row_half_mirror row_mask:0xf bank_mask:0xf bound_ctrl:1
	v_add_f32_dpp v62, v62, v62 quad_perm:[2,3,0,1] row_mask:0xf bank_mask:0xf bound_ctrl:1
	v_readlane_b32 s54, v90, 32
	v_writelane_b32 v131, s54, 21
	s_waitcnt lgkmcnt(2)
; __device__ __forceinline__ void sb_decode_stream(Frame& F, unsigned* qctr, int base, int limit) {
;     ...
;         DEC_SCORES(A, 0);
; #pragma unroll
;         for (int i = 0; i < 16; ++i) A[i] = __builtin_nontemporal_load((const f32x4*)(CV + cb + (size_t)(2 * i) * (NH * HD)));
;         DEC_SCORES(B, 1);
	v_add_f32_e32 v86, v86, v87
	v_add_f32_dpp v70, v70, v70 row_mirror row_mask:0xf bank_mask:0xf bound_ctrl:1
	v_add_f32_dpp v62, v62, v62 row_half_mirror row_mask:0xf bank_mask:0xf bound_ctrl:1
	v_readlane_b32 s2, v86, 0
	s_nop 3
	v_writelane_b32 v131, s2, 22
	ds_swizzle_b32 v71, v70 offset:swizzle(SWAP,16)
	v_add_f32_dpp v62, v62, v62 row_mirror row_mask:0xf bank_mask:0xf bound_ctrl:1
	v_readlane_b32 s54, v86, 32
	v_writelane_b32 v131, s54, 23
	s_waitcnt lgkmcnt(2)
	v_add_f32_e32 v82, v82, v83
	ds_swizzle_b32 v63, v62 offset:swizzle(SWAP,16)
	v_readlane_b32 s2, v82, 0
	s_nop 3
	v_writelane_b32 v131, s2, 24
	v_readlane_b32 s54, v82, 32
	v_writelane_b32 v131, s54, 25
	s_waitcnt lgkmcnt(2)
	v_add_f32_e32 v74, v74, v75
	s_waitcnt lgkmcnt(1)
	v_add_f32_e32 v70, v70, v71
	v_readlane_b32 s2, v74, 0
	s_nop 3
	v_writelane_b32 v131, s2, 26
	v_readlane_b32 s54, v74, 32
	v_writelane_b32 v131, s54, 27
	v_readlane_b32 s2, v70, 0
	v_readlane_b32 s54, v70, 32
	s_nop 3
	v_writelane_b32 v131, s2, 28
	s_waitcnt lgkmcnt(0)
	v_add_f32_e32 v62, v62, v63
	v_lshl_add_u64 v[132:133], v[184:185], 2, s[44:45]
	v_writelane_b32 v131, s54, 29
	v_readlane_b32 s2, v62, 0
	v_readlane_b32 s54, v62, 32
	v_add_co_u32_e32 v62, vcc, s5, v132
	s_nop 3
	v_writelane_b32 v131, s2, 30
	v_mul_f32_e32 v79, v79, v3
	s_nop 0
	v_addc_co_u32_e32 v63, vcc, 0, v133, vcc
	v_writelane_b32 v131, s54, 31
	global_load_dwordx4 v[126:129], v[132:133], off nt
	global_load_dwordx4 v[114:117], v[62:63], off nt
	v_add_co_u32_e32 v62, vcc, s22, v132
	v_fmac_f32_e32 v79, v78, v2
	s_nop 0
	v_addc_co_u32_e32 v63, vcc, 0, v133, vcc
	v_add_co_u32_e32 v64, vcc, s23, v132
	v_mul_f32_e32 v78, v81, v5
	s_nop 0
	v_addc_co_u32_e32 v65, vcc, 0, v133, vcc
	global_load_dwordx4 v[122:125], v[62:63], off nt
	global_load_dwordx4 v[118:121], v[64:65], off nt
	v_add_co_u32_e32 v62, vcc, s28, v132
	v_fmac_f32_e32 v78, v80, v4
	s_nop 0
	v_addc_co_u32_e32 v63, vcc, 0, v133, vcc
	v_add_co_u32_e32 v64, vcc, s29, v132
	v_mul_f32_e32 v67, v67, v3
	s_nop 0
	v_addc_co_u32_e32 v65, vcc, 0, v133, vcc
	global_load_dwordx4 v[102:105], v[62:63], off nt
	global_load_dwordx4 v[106:109], v[64:65], off nt
	v_add_co_u32_e32 v62, vcc, s30, v132
	v_add_f32_e32 v78, v79, v78
	s_nop 0
	v_addc_co_u32_e32 v63, vcc, 0, v133, vcc
	v_add_co_u32_e32 v64, vcc, s31, v132
	v_fmac_f32_e32 v67, v66, v2
	s_nop 0
	v_addc_co_u32_e32 v65, vcc, 0, v133, vcc
	global_load_dwordx4 v[110:113], v[62:63], off nt
	global_load_dwordx4 v[86:89], v[64:65], off nt
	v_add_co_u32_e32 v62, vcc, s33, v132
	v_mul_f32_e32 v66, v69, v5
	s_nop 0
	v_addc_co_u32_e32 v63, vcc, 0, v133, vcc
	v_add_co_u32_e32 v64, vcc, s35, v132
	v_add_f32_dpp v78, v78, v78 quad_perm:[1,0,3,2] row_mask:0xf bank_mask:0xf bound_ctrl:1
	s_nop 0
	v_addc_co_u32_e32 v65, vcc, 0, v133, vcc
	global_load_dwordx4 v[98:101], v[62:63], off nt
	global_load_dwordx4 v[94:97], v[64:65], off nt
	v_add_co_u32_e32 v62, vcc, s36, v132
	v_fmac_f32_e32 v66, v68, v4
	s_nop 0
	v_addc_co_u32_e32 v63, vcc, 0, v133, vcc
	v_add_co_u32_e32 v64, vcc, s37, v132
	v_mul_f32_e32 v59, v59, v3
	s_nop 0
	v_addc_co_u32_e32 v65, vcc, 0, v133, vcc
	v_add_f32_dpp v78, v78, v78 quad_perm:[2,3,0,1] row_mask:0xf bank_mask:0xf bound_ctrl:1
	v_add_f32_e32 v66, v67, v66
	v_fmac_f32_e32 v59, v58, v2
	v_mul_f32_e32 v58, v61, v5
	global_load_dwordx4 v[70:73], v[62:63], off nt
	global_load_dwordx4 v[74:77], v[64:65], off nt
	v_add_co_u32_e32 v62, vcc, s58, v132
	v_add_f32_dpp v78, v78, v78 row_half_mirror row_mask:0xf bank_mask:0xf bound_ctrl:1
	v_add_f32_dpp v66, v66, v66 quad_perm:[1,0,3,2] row_mask:0xf bank_mask:0xf bound_ctrl:1
	v_fmac_f32_e32 v58, v60, v4
	v_mul_f32_e32 v55, v55, v3
	v_addc_co_u32_e32 v63, vcc, 0, v133, vcc
	v_add_f32_dpp v134, v78, v78 row_mirror row_mask:0xf bank_mask:0xf bound_ctrl:1
	v_add_f32_dpp v66, v66, v66 quad_perm:[2,3,0,1] row_mask:0xf bank_mask:0xf bound_ctrl:1
	v_add_f32_e32 v58, v59, v58
	v_fmac_f32_e32 v55, v54, v2
	v_mul_f32_e32 v54, v57, v5
	v_add_co_u32_e32 v64, vcc, s59, v132
	ds_swizzle_b32 v135, v134 offset:swizzle(SWAP,16)
	v_add_f32_dpp v66, v66, v66 row_half_mirror row_mask:0xf bank_mask:0xf bound_ctrl:1
	v_add_f32_dpp v58, v58, v58 quad_perm:[1,0,3,2] row_mask:0xf bank_mask:0xf bound_ctrl:1
	v_fmac_f32_e32 v54, v56, v4
	v_mul_f32_e32 v51, v51, v3
	v_addc_co_u32_e32 v65, vcc, 0, v133, vcc
	v_add_f32_dpp v66, v66, v66 row_mirror row_mask:0xf bank_mask:0xf bound_ctrl:1
	v_add_f32_dpp v58, v58, v58 quad_perm:[2,3,0,1] row_mask:0xf bank_mask:0xf bound_ctrl:1
	v_add_f32_e32 v54, v55, v54
	v_fmac_f32_e32 v51, v50, v2
	v_mul_f32_e32 v50, v53, v5
	v_add_co_u32_e32 v90, vcc, s60, v132
	ds_swizzle_b32 v67, v66 offset:swizzle(SWAP,16)
	v_add_f32_dpp v58, v58, v58 row_half_mirror row_mask:0xf bank_mask:0xf bound_ctrl:1
	v_add_f32_dpp v54, v54, v54 quad_perm:[1,0,3,2] row_mask:0xf bank_mask:0xf bound_ctrl:1
	v_fmac_f32_e32 v50, v52, v4
	v_mul_f32_e32 v47, v47, v3
	v_addc_co_u32_e32 v91, vcc, 0, v133, vcc
	v_add_f32_dpp v58, v58, v58 row_mirror row_mask:0xf bank_mask:0xf bound_ctrl:1
	v_add_f32_dpp v54, v54, v54 quad_perm:[2,3,0,1] row_mask:0xf bank_mask:0xf bound_ctrl:1
	v_add_f32_e32 v50, v51, v50
	v_fmac_f32_e32 v47, v46, v2
	v_mul_f32_e32 v46, v49, v5
	s_ashr_i32 s53, s48, 8
	v_add_co_u32_e32 v78, vcc, s61, v132
	ds_swizzle_b32 v59, v58 offset:swizzle(SWAP,16)
	v_add_f32_dpp v54, v54, v54 row_half_mirror row_mask:0xf bank_mask:0xf bound_ctrl:1
	v_add_f32_dpp v50, v50, v50 quad_perm:[1,0,3,2] row_mask:0xf bank_mask:0xf bound_ctrl:1
	v_fmac_f32_e32 v46, v48, v4
	v_mul_f32_e32 v43, v43, v3
	s_and_b32 s2, s53, -8
	v_addc_co_u32_e32 v79, vcc, 0, v133, vcc
	s_waitcnt lgkmcnt(2)
; __device__ __forceinline__ void sb_decode_stream(Frame& F, unsigned* qctr, int base, int limit) {
;     ...
;         DEC_SCORES(A, 0);
; #pragma unroll
;         for (int i = 0; i < 16; ++i) A[i] = __builtin_nontemporal_load((const f32x4*)(CV + cb + (size_t)(2 * i) * (NH * HD)));
;         DEC_SCORES(B, 1);
	v_add_f32_e32 v134, v134, v135
	v_add_f32_dpp v54, v54, v54 row_mirror row_mask:0xf bank_mask:0xf bound_ctrl:1
	v_add_f32_dpp v50, v50, v50 quad_perm:[2,3,0,1] row_mask:0xf bank_mask:0xf bound_ctrl:1
	v_add_f32_e32 v46, v47, v46
	v_fmac_f32_e32 v43, v42, v2
	v_mul_f32_e32 v42, v45, v5
	global_load_dwordx4 v[82:85], v[62:63], off nt
	s_nop 0
	global_load_dwordx4 v[62:65], v[64:65], off nt
	s_nop 0
	global_load_dwordx4 v[90:93], v[90:91], off nt
	s_nop 0
	global_load_dwordx4 v[78:81], v[78:79], off nt
	s_or_b32 s52, s2, s52
	v_readlane_b32 s2, v134, 0
	s_nop 3
	v_writelane_b32 v131, s2, 32
	ds_swizzle_b32 v55, v54 offset:swizzle(SWAP,16)
	v_add_f32_dpp v50, v50, v50 row_half_mirror row_mask:0xf bank_mask:0xf bound_ctrl:1
	v_add_f32_dpp v46, v46, v46 quad_perm:[1,0,3,2] row_mask:0xf bank_mask:0xf bound_ctrl:1
	v_fmac_f32_e32 v42, v44, v4
	v_mul_f32_e32 v39, v39, v3
	v_readlane_b32 s53, v134, 32
	v_writelane_b32 v131, s53, 33
	s_waitcnt lgkmcnt(2)
	v_add_f32_e32 v66, v66, v67
	v_add_f32_dpp v50, v50, v50 row_mirror row_mask:0xf bank_mask:0xf bound_ctrl:1
	v_add_f32_dpp v46, v46, v46 quad_perm:[2,3,0,1] row_mask:0xf bank_mask:0xf bound_ctrl:1
	v_add_f32_e32 v42, v43, v42
	v_fmac_f32_e32 v39, v38, v2
	v_mul_f32_e32 v38, v41, v5
	v_readlane_b32 s2, v66, 0
	s_nop 3
	v_writelane_b32 v131, s2, 34
	ds_swizzle_b32 v51, v50 offset:swizzle(SWAP,16)
	v_add_f32_dpp v46, v46, v46 row_half_mirror row_mask:0xf bank_mask:0xf bound_ctrl:1
	v_add_f32_dpp v42, v42, v42 quad_perm:[1,0,3,2] row_mask:0xf bank_mask:0xf bound_ctrl:1
	v_fmac_f32_e32 v38, v40, v4
	v_mul_f32_e32 v35, v35, v3
	v_readlane_b32 s53, v66, 32
	v_writelane_b32 v131, s53, 35
	s_waitcnt lgkmcnt(2)
	v_add_f32_e32 v58, v58, v59
	v_add_f32_dpp v46, v46, v46 row_mirror row_mask:0xf bank_mask:0xf bound_ctrl:1
	v_add_f32_dpp v42, v42, v42 quad_perm:[2,3,0,1] row_mask:0xf bank_mask:0xf bound_ctrl:1
	v_add_f32_e32 v38, v39, v38
	v_fmac_f32_e32 v35, v34, v2
	v_mul_f32_e32 v34, v37, v5
	v_readlane_b32 s2, v58, 0
	s_nop 3
	v_writelane_b32 v131, s2, 36
	ds_swizzle_b32 v47, v46 offset:swizzle(SWAP,16)
	v_add_f32_dpp v42, v42, v42 row_half_mirror row_mask:0xf bank_mask:0xf bound_ctrl:1
	v_add_f32_dpp v38, v38, v38 quad_perm:[1,0,3,2] row_mask:0xf bank_mask:0xf bound_ctrl:1
	v_fmac_f32_e32 v34, v36, v4
	v_mul_f32_e32 v31, v31, v3
	v_readlane_b32 s53, v58, 32
	v_writelane_b32 v131, s53, 37
	s_waitcnt lgkmcnt(2)
	v_add_f32_e32 v54, v54, v55
	v_add_f32_dpp v42, v42, v42 row_mirror row_mask:0xf bank_mask:0xf bound_ctrl:1
	v_add_f32_dpp v38, v38, v38 quad_perm:[2,3,0,1] row_mask:0xf bank_mask:0xf bound_ctrl:1
	v_add_f32_e32 v34, v35, v34
	v_fmac_f32_e32 v31, v30, v2
	v_mul_f32_e32 v30, v33, v5
	v_readlane_b32 s2, v54, 0
	s_nop 3
	v_writelane_b32 v131, s2, 38
	ds_swizzle_b32 v43, v42 offset:swizzle(SWAP,16)
	v_add_f32_dpp v38, v38, v38 row_half_mirror row_mask:0xf bank_mask:0xf bound_ctrl:1
	v_add_f32_dpp v34, v34, v34 quad_perm:[1,0,3,2] row_mask:0xf bank_mask:0xf bound_ctrl:1
	v_fmac_f32_e32 v30, v32, v4
	v_mul_f32_e32 v27, v27, v3
	v_readlane_b32 s53, v54, 32
	v_writelane_b32 v131, s53, 39
	s_waitcnt lgkmcnt(2)
	v_add_f32_e32 v50, v50, v51
	v_add_f32_dpp v38, v38, v38 row_mirror row_mask:0xf bank_mask:0xf bound_ctrl:1
	v_add_f32_dpp v34, v34, v34 quad_perm:[2,3,0,1] row_mask:0xf bank_mask:0xf bound_ctrl:1
	v_add_f32_e32 v30, v31, v30
	v_fmac_f32_e32 v27, v26, v2
	v_mul_f32_e32 v26, v29, v5
	v_readlane_b32 s2, v50, 0
	s_nop 3
	v_writelane_b32 v131, s2, 40
	ds_swizzle_b32 v39, v38 offset:swizzle(SWAP,16)
	v_add_f32_dpp v34, v34, v34 row_half_mirror row_mask:0xf bank_mask:0xf bound_ctrl:1
	v_add_f32_dpp v30, v30, v30 quad_perm:[1,0,3,2] row_mask:0xf bank_mask:0xf bound_ctrl:1
	v_fmac_f32_e32 v26, v28, v4
	v_mul_f32_e32 v23, v23, v3
	v_readlane_b32 s53, v50, 32
	v_writelane_b32 v131, s53, 41
	s_waitcnt lgkmcnt(2)
	v_add_f32_e32 v46, v46, v47
	v_add_f32_dpp v34, v34, v34 row_mirror row_mask:0xf bank_mask:0xf bound_ctrl:1
	v_add_f32_dpp v30, v30, v30 quad_perm:[2,3,0,1] row_mask:0xf bank_mask:0xf bound_ctrl:1
	v_add_f32_e32 v26, v27, v26
	v_fmac_f32_e32 v23, v22, v2
	v_mul_f32_e32 v22, v25, v5
	v_readlane_b32 s2, v46, 0
	s_nop 3
	v_writelane_b32 v131, s2, 42
	ds_swizzle_b32 v35, v34 offset:swizzle(SWAP,16)
	v_add_f32_dpp v30, v30, v30 row_half_mirror row_mask:0xf bank_mask:0xf bound_ctrl:1
	v_add_f32_dpp v26, v26, v26 quad_perm:[1,0,3,2] row_mask:0xf bank_mask:0xf bound_ctrl:1
	v_fmac_f32_e32 v22, v24, v4
	v_mul_f32_e32 v19, v19, v3
	v_readlane_b32 s53, v46, 32
	v_writelane_b32 v131, s53, 43
	s_waitcnt lgkmcnt(2)
	v_add_f32_e32 v42, v42, v43
	v_add_f32_dpp v30, v30, v30 row_mirror row_mask:0xf bank_mask:0xf bound_ctrl:1
	v_add_f32_dpp v26, v26, v26 quad_perm:[2,3,0,1] row_mask:0xf bank_mask:0xf bound_ctrl:1
	v_add_f32_e32 v22, v23, v22
	v_fmac_f32_e32 v19, v18, v2
	v_mul_f32_e32 v18, v21, v5
	v_readlane_b32 s2, v42, 0
	s_nop 3
	v_writelane_b32 v131, s2, 44
	ds_swizzle_b32 v31, v30 offset:swizzle(SWAP,16)
	v_add_f32_dpp v26, v26, v26 row_half_mirror row_mask:0xf bank_mask:0xf bound_ctrl:1
	v_add_f32_dpp v22, v22, v22 quad_perm:[1,0,3,2] row_mask:0xf bank_mask:0xf bound_ctrl:1
	v_fmac_f32_e32 v18, v20, v4
	v_mul_f32_e32 v15, v15, v3
	v_readlane_b32 s53, v42, 32
	v_writelane_b32 v131, s53, 45
	s_waitcnt lgkmcnt(2)
	v_add_f32_e32 v38, v38, v39
	v_add_f32_dpp v26, v26, v26 row_mirror row_mask:0xf bank_mask:0xf bound_ctrl:1
	v_add_f32_dpp v22, v22, v22 quad_perm:[2,3,0,1] row_mask:0xf bank_mask:0xf bound_ctrl:1
	v_add_f32_e32 v18, v19, v18
	v_fmac_f32_e32 v15, v14, v2
	v_mul_f32_e32 v14, v17, v5
	v_mul_f32_e32 v11, v11, v3
	v_readlane_b32 s2, v38, 0
	s_nop 3
	v_writelane_b32 v131, s2, 46
	ds_swizzle_b32 v27, v26 offset:swizzle(SWAP,16)
	v_add_f32_dpp v22, v22, v22 row_half_mirror row_mask:0xf bank_mask:0xf bound_ctrl:1
	v_add_f32_dpp v18, v18, v18 quad_perm:[1,0,3,2] row_mask:0xf bank_mask:0xf bound_ctrl:1
	v_fmac_f32_e32 v14, v16, v4
	v_fmac_f32_e32 v11, v10, v2
	v_mul_f32_e32 v10, v13, v5
	v_readlane_b32 s53, v38, 32
	v_writelane_b32 v131, s53, 47
	s_waitcnt lgkmcnt(2)
; __device__ __forceinline__ void sb_decode_stream(Frame& F, unsigned* qctr, int base, int limit) {
;     ...
;         DEC_SCORES(B, 1);
;     ...
; #pragma unroll
;         for (int i = 0; i < 16; ++i) B[i] = __builtin_nontemporal_load((const f32x4*)(CV + cb + (size_t)(32 + 2 * i) * (NH * HD)));
;         const float z = __builtin_bit_cast(float, zi);
;         const float e = __builtin_amdgcn_exp2f(-(z * k1 + k2));
;         const float be = __builtin_amdgcn_rcpf(1.0f + e), m = 1.0f - be;
;         float s = m;
; #pragma unroll
;         for (int o = 1; o < 64; o <<= 1) { const float t = __shfl_down(s, o); if (lane + o < 64) s *= t; }
;         const float tot = __shfl(s, 0);
;         const float sx = __shfl_down(s, 1);
;         const float a = be * (lane < 63 ? sx : 1.0f);
;         int itn = (int)(__builtin_amdgcn_readfirstlane(vn) >> 6); const bool more = itn < limit; itn = more ? itn + base : it;
;         const int bn = itn >> 11, hn = itn & 7, p0n = ((itn >> 3) & 255) * 64;
;         const int pagen = PT[bn * NPAGES + (p0n >> 7)];
;         const size_t cbn = (((size_t)pagen * PAGE + (p0n & 127)) * NH + hn) * HD + lo;
;         const size_t stepn = more ? (size_t)(NH * HD) : 0;
	v_add_f32_e32 v34, v34, v35
	v_add_f32_dpp v22, v22, v22 row_mirror row_mask:0xf bank_mask:0xf bound_ctrl:1
	v_add_f32_dpp v18, v18, v18 quad_perm:[2,3,0,1] row_mask:0xf bank_mask:0xf bound_ctrl:1
	v_add_f32_e32 v14, v15, v14
	v_fmac_f32_e32 v10, v12, v4
	v_pk_mul_f32 v[4:5], v[8:9], v[4:5]
	v_pk_mul_f32 v[2:3], v[6:7], v[2:3]
	v_readlane_b32 s2, v34, 0
	s_nop 3
	v_writelane_b32 v131, s2, 48
	ds_swizzle_b32 v23, v22 offset:swizzle(SWAP,16)
	v_add_f32_dpp v18, v18, v18 row_half_mirror row_mask:0xf bank_mask:0xf bound_ctrl:1
	v_add_f32_dpp v14, v14, v14 quad_perm:[1,0,3,2] row_mask:0xf bank_mask:0xf bound_ctrl:1
	v_pk_mov_b32 v[6:7], v[2:3], v[4:5] op_sel:[1,0]
	v_mov_b32_e32 v3, v5
	v_readlane_b32 s53, v34, 32
	v_writelane_b32 v131, s53, 49
	s_waitcnt lgkmcnt(2)
	v_add_f32_e32 v30, v30, v31
	v_add_f32_dpp v18, v18, v18 row_mirror row_mask:0xf bank_mask:0xf bound_ctrl:1
	v_add_f32_dpp v14, v14, v14 quad_perm:[2,3,0,1] row_mask:0xf bank_mask:0xf bound_ctrl:1
	v_add_f32_e32 v10, v11, v10
	v_pk_add_f32 v[2:3], v[6:7], v[2:3]
	v_readlane_b32 s2, v30, 0
	s_nop 3
	v_writelane_b32 v131, s2, 50
	ds_swizzle_b32 v19, v18 offset:swizzle(SWAP,16)
	v_add_f32_dpp v14, v14, v14 row_half_mirror row_mask:0xf bank_mask:0xf bound_ctrl:1
	v_add_f32_dpp v10, v10, v10 quad_perm:[1,0,3,2] row_mask:0xf bank_mask:0xf bound_ctrl:1
	v_add_f32_e32 v2, v2, v3
	v_readlane_b32 s53, v30, 32
	v_writelane_b32 v131, s53, 51
	s_waitcnt lgkmcnt(2)
	v_add_f32_e32 v26, v26, v27
	v_add_f32_dpp v14, v14, v14 row_mirror row_mask:0xf bank_mask:0xf bound_ctrl:1
	v_add_f32_dpp v10, v10, v10 quad_perm:[2,3,0,1] row_mask:0xf bank_mask:0xf bound_ctrl:1
	v_add_f32_dpp v2, v2, v2 quad_perm:[1,0,3,2] row_mask:0xf bank_mask:0xf bound_ctrl:1
	v_readlane_b32 s2, v26, 0
	s_nop 3
	v_writelane_b32 v131, s2, 52
	ds_swizzle_b32 v15, v14 offset:swizzle(SWAP,16)
	v_add_f32_dpp v10, v10, v10 row_half_mirror row_mask:0xf bank_mask:0xf bound_ctrl:1
	v_add_f32_dpp v2, v2, v2 quad_perm:[2,3,0,1] row_mask:0xf bank_mask:0xf bound_ctrl:1
	v_readlane_b32 s53, v26, 32
	v_writelane_b32 v131, s53, 53
	s_waitcnt lgkmcnt(2)
	v_add_f32_e32 v22, v22, v23
	v_add_f32_dpp v10, v10, v10 row_mirror row_mask:0xf bank_mask:0xf bound_ctrl:1
	v_add_f32_dpp v2, v2, v2 row_half_mirror row_mask:0xf bank_mask:0xf bound_ctrl:1
	v_readlane_b32 s2, v22, 0
	s_nop 3
	v_writelane_b32 v131, s2, 54
	ds_swizzle_b32 v11, v10 offset:swizzle(SWAP,16)
	v_add_f32_dpp v2, v2, v2 row_mirror row_mask:0xf bank_mask:0xf bound_ctrl:1
	v_readlane_b32 s53, v22, 32
	v_writelane_b32 v131, s53, 55
	s_waitcnt lgkmcnt(2)
	v_add_f32_e32 v18, v18, v19
	ds_swizzle_b32 v3, v2 offset:swizzle(SWAP,16)
	v_readlane_b32 s2, v18, 0
	s_nop 3
	v_writelane_b32 v131, s2, 56
	v_readlane_b32 s53, v18, 32
	v_writelane_b32 v131, s53, 57
	s_waitcnt lgkmcnt(2)
	v_add_f32_e32 v14, v14, v15
	s_waitcnt lgkmcnt(1)
	v_add_f32_e32 v10, v10, v11
	v_readlane_b32 s2, v14, 0
	s_nop 3
	v_writelane_b32 v131, s2, 58
	v_readlane_b32 s53, v14, 32
	v_writelane_b32 v131, s53, 59
	v_readlane_b32 s2, v10, 0
	v_readlane_b32 s53, v10, 32
	s_nop 3
	v_writelane_b32 v131, s2, 60
	s_waitcnt lgkmcnt(0)
	v_add_f32_e32 v2, v2, v3
	v_writelane_b32 v131, s53, 61
	s_bfe_u32 s78, s48, 0x80003
	v_readlane_b32 s2, v2, 0
	v_readlane_b32 s53, v2, 32
	v_add_co_u32_e32 v2, vcc, s62, v132
	s_nop 3
	v_writelane_b32 v131, s2, 62
	s_waitcnt vmcnt(17)
	v_readfirstlane_b32 s2, v253
	s_nop 0
	v_addc_co_u32_e32 v3, vcc, 0, v133, vcc
	v_add_co_u32_e32 v4, vcc, s63, v132
	v_writelane_b32 v131, s53, 63
	s_ashr_i32 s79, s2, 6
	s_nop 0
	v_addc_co_u32_e32 v5, vcc, 0, v133, vcc
	global_load_dwordx4 v[18:21], v[2:3], off nt
	global_load_dwordx4 v[6:9], v[4:5], off nt
	v_add_co_u32_e32 v2, vcc, s64, v132
	s_cmpk_lt_i32 s79, 0x1800
	s_nop 0
	v_addc_co_u32_e32 v3, vcc, 0, v133, vcc
	v_add_co_u32_e32 v4, vcc, s65, v132
	s_cselect_b64 s[56:57], -1, 0
	s_nop 0
	v_addc_co_u32_e32 v5, vcc, 0, v133, vcc
	global_load_dwordx4 v[14:17], v[2:3], off nt
	global_load_dwordx4 v[10:13], v[4:5], off nt
	v_add_co_u32_e32 v2, vcc, s66, v132
	s_cmpk_gt_i32 s79, 0x17ff
	s_nop 0
	v_addc_co_u32_e32 v3, vcc, 0, v133, vcc
	s_cselect_b64 s[54:55], -1, 0
	s_and_b64 s[80:81], s[56:57], exec
	v_add_co_u32_e32 v4, vcc, s67, v132
	s_cselect_b32 s53, s79, s48
	s_nop 0
	v_addc_co_u32_e32 v5, vcc, 0, v133, vcc
	s_ashr_i32 s48, s53, 11
	global_load_dwordx4 v[138:141], v[2:3], off nt
	global_load_dwordx4 v[142:145], v[4:5], off nt
	v_add_co_u32_e32 v2, vcc, s68, v132
	s_lshl_b32 s80, s48, 7
	s_bfe_u32 s81, s53, 0x70004
	v_addc_co_u32_e32 v3, vcc, 0, v133, vcc
	s_or_b32 s80, s80, s81
	v_add_co_u32_e32 v4, vcc, s69, v132
	s_ashr_i32 s81, s80, 31
	s_nop 0
	v_addc_co_u32_e32 v5, vcc, 0, v133, vcc
	s_and_b32 s2, s53, 7
	s_lshl_b64 s[80:81], s[80:81], 2
	global_load_dwordx4 v[146:149], v[2:3], off nt
	global_load_dwordx4 v[134:137], v[4:5], off nt
	s_waitcnt vmcnt(24)
	v_pk_mul_f32 v[4:5], v[130:131], s[50:51]
	s_add_u32 s80, s46, s80
	v_add_f32_e32 v4, v4, v5
	s_addc_u32 s81, s47, s81
	v_exp_f32_e64 v5, -v4
	global_load_dword v4, v1, s[80:81]
	v_add_co_u32_e32 v2, vcc, s70, v132
	v_add_f32_e32 v5, 1.0, v5
	s_nop 0
	v_addc_co_u32_e32 v3, vcc, 0, v133, vcc
	v_rcp_f32_e32 v5, v5
	v_add_co_u32_e32 v22, vcc, s71, v132
	v_and_b32_e32 v24, 63, v221
	s_nop 0
	v_addc_co_u32_e32 v23, vcc, 0, v133, vcc
	v_cmp_ne_u32_e32 vcc, 63, v24
	global_load_dwordx4 v[154:157], v[2:3], off nt
	global_load_dwordx4 v[150:153], v[22:23], off nt
	v_addc_co_u32_e32 v2, vcc, 0, v221, vcc
	v_sub_f32_e32 v22, 1.0, v5
	v_lshlrev_b32_e32 v25, 2, v2
	ds_bpermute_b32 v23, v25, v22
	v_add_co_u32_e32 v2, vcc, s72, v132
	v_and_b32_e32 v229, 64, v221
	s_nop 0
	v_addc_co_u32_e32 v3, vcc, 0, v133, vcc
	s_waitcnt lgkmcnt(0)
; __device__ __forceinline__ void sb_decode_stream(Frame& F, unsigned* qctr, int base, int limit) {
;     ...
;         float s = m;
; #pragma unroll
;         for (int o = 1; o < 64; o <<= 1) { const float t = __shfl_down(s, o); if (lane + o < 64) s *= t; }
;         const float tot = __shfl(s, 0);
;         const float sx = __shfl_down(s, 1);
;         const float a = be * (lane < 63 ? sx : 1.0f);
;         int itn = (int)(__builtin_amdgcn_readfirstlane(vn) >> 6); const bool more = itn < limit; itn = more ? itn + base : it;
;         const int bn = itn >> 11, hn = itn & 7, p0n = ((itn >> 3) & 255) * 64;
;         const int pagen = PT[bn * NPAGES + (p0n >> 7)];
;         const size_t cbn = (((size_t)pagen * PAGE + (p0n & 127)) * NH + hn) * HD + lo;
;         const size_t stepn = more ? (size_t)(NH * HD) : 0;
;         f32x4 o4 = {0.f, 0.f, 0.f, 0.f};
; #pragma unroll
;         for (int i = 0; i < 16; ++i) { const float aj = __shfl(a, 2 * i + half); o4 += aj * A[i]; }
	v_mul_f32_e32 v23, v22, v23
	v_cmp_gt_u32_e32 vcc, 62, v24
	v_cndmask_b32_e64 v26, v22, v23, s[6:7]
	s_lshl_b32 s53, s53, 6
	v_cndmask_b32_e64 v22, 0, 2, vcc
	v_add_lshl_u32 v22, v22, v221, 2
	ds_bpermute_b32 v27, v22, v26
	v_add_co_u32_e32 v22, vcc, s73, v132
	s_and_b32 s53, s53, 0x200
	s_nop 0
	v_addc_co_u32_e32 v23, vcc, 0, v133, vcc
	global_load_dwordx4 v[162:165], v[2:3], off nt
	global_load_dwordx4 v[158:161], v[22:23], off nt
	s_waitcnt lgkmcnt(0)
	v_mul_f32_e32 v2, v26, v27
	v_cmp_gt_u32_e32 vcc, 60, v24
	v_cndmask_b32_e64 v22, v26, v2, s[12:13]
	s_mulk_i32 s48, 0x7040
	v_cndmask_b32_e64 v2, 0, 4, vcc
	v_add_lshl_u32 v2, v2, v221, 2
	ds_bpermute_b32 v23, v2, v22
	v_add_co_u32_e32 v2, vcc, s74, v132
	v_or_b32_e32 v228, v229, v207
	s_nop 0
	v_addc_co_u32_e32 v3, vcc, 0, v133, vcc
	s_waitcnt lgkmcnt(0)
	v_mul_f32_e32 v23, v22, v23
	v_cmp_gt_u32_e32 vcc, 56, v24
	v_cndmask_b32_e64 v26, v22, v23, s[14:15]
	v_lshlrev_b32_e32 v228, 2, v228
	v_cndmask_b32_e64 v22, 0, 8, vcc
	v_add_lshl_u32 v22, v22, v221, 2
	ds_bpermute_b32 v27, v22, v26
	v_add_co_u32_e32 v22, vcc, s75, v132
	v_or_b32_e32 v230, v229, v208
	s_nop 0
	v_addc_co_u32_e32 v23, vcc, 0, v133, vcc
	global_load_dwordx4 v[170:173], v[2:3], off nt
	global_load_dwordx4 v[166:169], v[22:23], off nt
	s_waitcnt lgkmcnt(0)
	v_mul_f32_e32 v2, v26, v27
	v_cmp_gt_u32_e32 vcc, 48, v24
	v_cndmask_b32_e64 v22, v26, v2, s[16:17]
	v_lshlrev_b32_e32 v230, 2, v230
	v_cndmask_b32_e64 v2, 0, 16, vcc
	v_add_lshl_u32 v2, v2, v221, 2
	ds_bpermute_b32 v23, v2, v22
	v_add_co_u32_e32 v2, vcc, s76, v132
	v_lshlrev_b32_e32 v231, 2, v229
	s_nop 0
	v_addc_co_u32_e32 v3, vcc, 0, v133, vcc
	s_waitcnt lgkmcnt(0)
	v_mul_f32_e32 v23, v22, v23
	v_cndmask_b32_e64 v24, v22, v23, s[18:19]
	ds_bpermute_b32 v26, v222, v24
	v_add_co_u32_e32 v22, vcc, s77, v132
	v_or_b32_e32 v232, v229, v209
	s_nop 0
	v_addc_co_u32_e32 v23, vcc, 0, v133, vcc
	s_waitcnt lgkmcnt(0)
	v_mul_f32_e32 v26, v24, v26
	v_cndmask_b32_e64 v223, v24, v26, s[20:21]
	ds_bpermute_b32 v24, v25, v223
	global_load_dwordx4 v[178:181], v[2:3], off nt
	global_load_dwordx4 v[174:177], v[22:23], off nt
	v_or_b32_e32 v22, v229, v187
	v_lshlrev_b32_e32 v22, 2, v22
	v_or_b32_e32 v23, v229, v188
	s_waitcnt lgkmcnt(0)
	v_cndmask_b32_e64 v2, 1.0, v24, s[6:7]
	v_mul_f32_e32 v233, v5, v2
	s_waitcnt vmcnt(8)
	v_ashrrev_i32_e32 v5, 31, v4
	v_lshlrev_b64 v[2:3], 10, v[4:5]
	v_or_b32_e32 v4, v229, v186
	v_lshlrev_b32_e32 v4, 2, v4
	ds_bpermute_b32 v4, v4, v233
	ds_bpermute_b32 v22, v22, v233
	v_or_b32_e32 v2, s53, v2
	v_or_b32_e32 v2, s2, v2
	v_lshlrev_b32_e32 v23, 2, v23
	v_lshlrev_b64 v[2:3], 7, v[2:3]
	ds_bpermute_b32 v24, v23, v233
	v_or_b32_e32 v23, v229, v189
	v_lshl_add_u64 v[184:185], v[2:3], 0, v[182:183]
	s_waitcnt lgkmcnt(2)
	v_pk_fma_f32 v[2:3], v[126:127], v[4:5], 0 op_sel_hi:[1,0,0]
	v_pk_fma_f32 v[4:5], v[128:129], v[4:5], 0 op_sel_hi:[1,0,0]
	v_lshlrev_b32_e32 v23, 2, v23
	s_waitcnt lgkmcnt(1)
	v_pk_fma_f32 v[4:5], v[116:117], v[22:23], v[4:5] op_sel_hi:[1,0,1]
	v_pk_fma_f32 v[2:3], v[114:115], v[22:23], v[2:3] op_sel_hi:[1,0,1]
	v_or_b32_e32 v22, v229, v190
	ds_bpermute_b32 v26, v23, v233
	v_lshlrev_b32_e32 v22, 2, v22
	ds_bpermute_b32 v22, v22, v233
	v_or_b32_e32 v23, v229, v191
	v_lshlrev_b32_e32 v23, 2, v23
	s_waitcnt lgkmcnt(2)
	v_pk_fma_f32 v[2:3], v[122:123], v[24:25], v[2:3] op_sel_hi:[1,0,1]
	v_pk_fma_f32 v[4:5], v[124:125], v[24:25], v[4:5] op_sel_hi:[1,0,1]
	ds_bpermute_b32 v24, v23, v233
	v_or_b32_e32 v23, v229, v192
	s_waitcnt lgkmcnt(2)
	v_pk_fma_f32 v[4:5], v[120:121], v[26:27], v[4:5] op_sel_hi:[1,0,1]
	v_pk_fma_f32 v[2:3], v[118:119], v[26:27], v[2:3] op_sel_hi:[1,0,1]
	v_lshlrev_b32_e32 v23, 2, v23
	s_waitcnt lgkmcnt(1)
	v_pk_fma_f32 v[2:3], v[102:103], v[22:23], v[2:3] op_sel_hi:[1,0,1]
	v_pk_fma_f32 v[4:5], v[104:105], v[22:23], v[4:5] op_sel_hi:[1,0,1]
	v_or_b32_e32 v22, v229, v193
	ds_bpermute_b32 v26, v23, v233
	v_lshlrev_b32_e32 v22, 2, v22
	ds_bpermute_b32 v22, v22, v233
	v_or_b32_e32 v23, v229, v194
	v_lshlrev_b32_e32 v23, 2, v23
	s_waitcnt lgkmcnt(2)
	v_pk_fma_f32 v[4:5], v[108:109], v[24:25], v[4:5] op_sel_hi:[1,0,1]
	v_pk_fma_f32 v[2:3], v[106:107], v[24:25], v[2:3] op_sel_hi:[1,0,1]
	ds_bpermute_b32 v24, v23, v233
	v_or_b32_e32 v23, v229, v195
	s_waitcnt lgkmcnt(2)
	v_pk_fma_f32 v[2:3], v[110:111], v[26:27], v[2:3] op_sel_hi:[1,0,1]
	v_pk_fma_f32 v[4:5], v[112:113], v[26:27], v[4:5] op_sel_hi:[1,0,1]
	v_lshlrev_b32_e32 v23, 2, v23
	s_waitcnt lgkmcnt(1)
	v_pk_fma_f32 v[4:5], v[88:89], v[22:23], v[4:5] op_sel_hi:[1,0,1]
	v_pk_fma_f32 v[2:3], v[86:87], v[22:23], v[2:3] op_sel_hi:[1,0,1]
	v_or_b32_e32 v22, v229, v196
	ds_bpermute_b32 v26, v23, v233
	v_lshlrev_b32_e32 v22, 2, v22
	ds_bpermute_b32 v22, v22, v233
	v_or_b32_e32 v23, v229, v197
	v_lshlrev_b32_e32 v23, 2, v23
	s_waitcnt lgkmcnt(2)
	v_pk_fma_f32 v[2:3], v[98:99], v[24:25], v[2:3] op_sel_hi:[1,0,1]
	v_pk_fma_f32 v[4:5], v[100:101], v[24:25], v[4:5] op_sel_hi:[1,0,1]
	ds_bpermute_b32 v24, v23, v233
	v_or_b32_e32 v23, v229, v198
	v_lshlrev_b32_e32 v23, 2, v23
	s_waitcnt lgkmcnt(2)
	v_pk_fma_f32 v[4:5], v[96:97], v[26:27], v[4:5] op_sel_hi:[1,0,1]
	v_pk_fma_f32 v[2:3], v[94:95], v[26:27], v[2:3] op_sel_hi:[1,0,1]
	ds_bpermute_b32 v26, v23, v233
	s_waitcnt lgkmcnt(2)
	v_pk_fma_f32 v[2:3], v[70:71], v[22:23], v[2:3] op_sel_hi:[1,0,1]
	v_pk_fma_f32 v[4:5], v[72:73], v[22:23], v[4:5] op_sel_hi:[1,0,1]
	v_or_b32_e32 v22, v229, v200
	v_or_b32_e32 v23, v229, v201
	v_lshlrev_b32_e32 v22, 2, v22
	v_lshlrev_b32_e32 v23, 2, v23
	s_waitcnt lgkmcnt(1)
; __device__ __forceinline__ void sb_decode_stream(Frame& F, unsigned* qctr, int base, int limit) {
;     ...
;         for (int i = 0; i < 16; ++i) { const float aj = __shfl(a, 2 * i + half); o4 += aj * A[i]; }
;         const f32x4 q4n = *(const f32x4*)(SSP(S_PROJ) + (size_t)bn * IN_COLS + hn * HD + 4 * l32);
; #pragma unroll
;         for (int i = 0; i < 16; ++i) A[i] = __builtin_nontemporal_load((const f32x4*)(CK + cbn + (size_t)(2 * i) * stepn));
; #pragma unroll
;         for (int i = 0; i < 16; ++i) { const float aj = __shfl(a, 32 + 2 * i + half); o4 += aj * B[i]; }
; #pragma unroll
;         for (int i = 0; i < 16; ++i) B[i] = __builtin_nontemporal_load((const f32x4*)(CK + cbn + (size_t)(32 + 2 * i) * stepn));
	v_pk_fma_f32 v[4:5], v[76:77], v[24:25], v[4:5] op_sel_hi:[1,0,1]
	v_pk_fma_f32 v[2:3], v[74:75], v[24:25], v[2:3] op_sel_hi:[1,0,1]
	ds_bpermute_b32 v22, v22, v233
	ds_bpermute_b32 v24, v23, v233
	v_or_b32_e32 v23, v229, v202
	v_lshlrev_b32_e32 v23, 2, v23
	s_ashr_i32 s53, s48, 31
	s_waitcnt lgkmcnt(2)
	v_pk_fma_f32 v[2:3], v[82:83], v[26:27], v[2:3] op_sel_hi:[1,0,1]
	v_pk_fma_f32 v[4:5], v[84:85], v[26:27], v[4:5] op_sel_hi:[1,0,1]
	ds_bpermute_b32 v26, v23, v233
	s_add_u32 s48, s38, s48
	s_addc_u32 s53, s39, s53
	s_lshl_b32 s2, s2, 9
	s_add_u32 s80, s48, s2
	s_waitcnt lgkmcnt(2)
	v_pk_fma_f32 v[4:5], v[64:65], v[22:23], v[4:5] op_sel_hi:[1,0,1]
	v_pk_fma_f32 v[2:3], v[62:63], v[22:23], v[2:3] op_sel_hi:[1,0,1]
	s_addc_u32 s81, s53, 0
	s_waitcnt lgkmcnt(1)
	v_pk_fma_f32 v[2:3], v[90:91], v[24:25], v[2:3] op_sel_hi:[1,0,1]
	v_pk_fma_f32 v[4:5], v[92:93], v[24:25], v[4:5] op_sel_hi:[1,0,1]
	s_and_b64 s[56:57], s[56:57], exec
	s_waitcnt lgkmcnt(0)
	v_pk_fma_f32 v[22:23], v[80:81], v[26:27], v[4:5] op_sel_hi:[1,0,1]
	v_pk_fma_f32 v[24:25], v[78:79], v[26:27], v[2:3] op_sel_hi:[1,0,1]
	v_lshl_add_u64 v[26:27], v[184:185], 2, s[42:43]
	s_cselect_b32 s48, 0x2000, 0
	v_lshl_add_u64 v[28:29], v[26:27], 0, s[48:49]
	global_load_dwordx4 v[2:5], v220, s[80:81]
	global_load_dwordx4 v[130:133], v[26:27], off nt
	global_load_dwordx4 v[126:129], v[28:29], off nt
	v_lshl_add_u64 v[26:27], v[28:29], 0, s[48:49]
	v_lshl_add_u64 v[28:29], v[26:27], 0, s[48:49]
	global_load_dwordx4 v[122:125], v[26:27], off nt
	global_load_dwordx4 v[118:121], v[28:29], off nt
	v_lshl_add_u64 v[26:27], v[28:29], 0, s[48:49]
	v_lshl_add_u64 v[28:29], v[26:27], 0, s[48:49]
	global_load_dwordx4 v[114:117], v[26:27], off nt
	global_load_dwordx4 v[110:113], v[28:29], off nt
	v_lshl_add_u64 v[26:27], v[28:29], 0, s[48:49]
	v_lshl_add_u64 v[28:29], v[26:27], 0, s[48:49]
	global_load_dwordx4 v[106:109], v[26:27], off nt
	global_load_dwordx4 v[102:105], v[28:29], off nt
	v_lshl_add_u64 v[26:27], v[28:29], 0, s[48:49]
	v_or_b32_e32 v28, v229, v203
	v_lshlrev_b32_e32 v28, 2, v28
	ds_bpermute_b32 v28, v28, v233
	global_load_dwordx4 v[98:101], v[26:27], off nt
	v_lshl_add_u64 v[26:27], v[26:27], 0, s[48:49]
	global_load_dwordx4 v[94:97], v[26:27], off nt
	v_lshl_add_u64 v[26:27], v[26:27], 0, s[48:49]
	s_waitcnt lgkmcnt(0)
	v_pk_fma_f32 v[20:21], v[20:21], v[28:29], v[22:23] op_sel_hi:[1,0,1]
	v_or_b32_e32 v22, v229, v204
	v_or_b32_e32 v23, v229, v205
	v_lshlrev_b32_e32 v22, 2, v22
	v_lshlrev_b32_e32 v23, 2, v23
	v_pk_fma_f32 v[18:19], v[18:19], v[28:29], v[24:25] op_sel_hi:[1,0,1]
	ds_bpermute_b32 v22, v22, v233
	ds_bpermute_b32 v24, v23, v233
	v_or_b32_e32 v23, v229, v206
	v_lshlrev_b32_e32 v23, 2, v23
	global_load_dwordx4 v[90:93], v[26:27], off nt
	v_lshl_add_u64 v[26:27], v[26:27], 0, s[48:49]
	ds_bpermute_b32 v28, v23, v233
	global_load_dwordx4 v[86:89], v[26:27], off nt
	v_lshl_add_u64 v[26:27], v[26:27], 0, s[48:49]
	global_load_dwordx4 v[82:85], v[26:27], off nt
	v_lshl_add_u64 v[26:27], v[26:27], 0, s[48:49]
	global_load_dwordx4 v[74:77], v[26:27], off nt
	v_lshl_add_u64 v[26:27], v[26:27], 0, s[48:49]
	s_waitcnt lgkmcnt(2)
	v_pk_fma_f32 v[6:7], v[6:7], v[22:23], v[18:19] op_sel_hi:[1,0,1]
	global_load_dwordx4 v[70:73], v[26:27], off nt
	v_lshl_add_u64 v[26:27], v[26:27], 0, s[48:49]
	s_waitcnt lgkmcnt(1)
	v_pk_fma_f32 v[6:7], v[14:15], v[24:25], v[6:7] op_sel_hi:[1,0,1]
	v_pk_fma_f32 v[8:9], v[8:9], v[22:23], v[20:21] op_sel_hi:[1,0,1]
	s_waitcnt lgkmcnt(0)
	v_pk_fma_f32 v[226:227], v[10:11], v[28:29], v[6:7] op_sel_hi:[1,0,1]
	v_lshl_add_u64 v[6:7], v[26:27], 0, s[48:49]
	global_load_dwordx4 v[78:81], v[6:7], off nt
	v_lshl_add_u64 v[6:7], v[6:7], 0, s[48:49]
	global_load_dwordx4 v[66:69], v[6:7], off nt
	v_lshl_add_u64 v[6:7], v[6:7], 0, s[48:49]
	global_load_dwordx4 v[58:61], v[6:7], off nt
	v_lshl_add_u64 v[6:7], v[6:7], 0, s[48:49]
	global_load_dwordx4 v[54:57], v[6:7], off nt
	v_lshl_add_u64 v[6:7], v[6:7], 0, s[48:49]
	global_load_dwordx4 v[50:53], v[6:7], off nt
	v_lshl_add_u64 v[6:7], v[6:7], 0, s[48:49]
	global_load_dwordx4 v[46:49], v[6:7], off nt
	v_lshl_add_u64 v[6:7], v[6:7], 0, s[48:49]
	global_load_dwordx4 v[42:45], v[6:7], off nt
	v_lshl_add_u64 v[6:7], v[6:7], 0, s[48:49]
	global_load_dwordx4 v[38:41], v[6:7], off nt
	v_lshl_add_u64 v[6:7], v[6:7], 0, s[48:49]
	global_load_dwordx4 v[34:37], v[6:7], off nt
	v_lshl_add_u64 v[6:7], v[6:7], 0, s[48:49]
	v_pk_fma_f32 v[8:9], v[16:17], v[24:25], v[8:9] op_sel_hi:[1,0,1]
	global_load_dwordx4 v[30:33], v[6:7], off nt
	v_lshl_add_u64 v[6:7], v[6:7], 0, s[48:49]
	global_load_dwordx4 v[62:65], v[26:27], off nt
	v_pk_fma_f32 v[224:225], v[12:13], v[28:29], v[8:9] op_sel_hi:[1,0,1]
	global_load_dwordx4 v[26:29], v[6:7], off nt
	v_lshl_add_u64 v[6:7], v[6:7], 0, s[48:49]
	global_load_dwordx4 v[22:25], v[6:7], off nt
	v_lshl_add_u64 v[6:7], v[6:7], 0, s[48:49]
	global_load_dwordx4 v[18:21], v[6:7], off nt
	v_lshl_add_u64 v[6:7], v[6:7], 0, s[48:49]
	global_load_dwordx4 v[14:17], v[6:7], off nt
	v_lshl_add_u64 v[6:7], v[6:7], 0, s[48:49]
	global_load_dwordx4 v[10:13], v[6:7], off nt
	v_lshl_add_u64 v[6:7], v[6:7], 0, s[48:49]
	global_load_dwordx4 v[6:9], v[6:7], off nt
	ds_bpermute_b32 v228, v228, v233
	ds_bpermute_b32 v230, v230, v233
	v_lshlrev_b32_e32 v232, 2, v232
	ds_bpermute_b32 v232, v232, v233
	s_ashr_i32 s53, s52, 31
	s_waitcnt lgkmcnt(2)
; __device__ __forceinline__ void sb_decode_stream(Frame& F, unsigned* qctr, int base, int limit) {
;     ...
;         for (int i = 0; i < 16; ++i) { const float aj = __shfl(a, 32 + 2 * i + half); o4 += aj * B[i]; }
; #pragma unroll
;         for (int i = 0; i < 16; ++i) B[i] = __builtin_nontemporal_load((const f32x4*)(CK + cbn + (size_t)(32 + 2 * i) * stepn));
;         o4.x += __shfl_xor(o4.x, 32); o4.y += __shfl_xor(o4.y, 32); o4.z += __shfl_xor(o4.z, 32); o4.w += __shfl_xor(o4.w, 32);
;         float* P = SSP(S_PART) + ((size_t)bh * DSEG + blk) * DPART;
;         if (half == 0) *(f32x4*)(P + 4 * l32) = o4; if (lane == 0) P[128] = tot;
;         if (!more) break;
;         it = itn; cb = cbn; q4 = q4n;
	v_pk_fma_f32 v[138:139], v[138:139], v[228:229], v[226:227] op_sel_hi:[1,0,1]
	v_pk_fma_f32 v[140:141], v[140:141], v[228:229], v[224:225] op_sel_hi:[1,0,1]
	s_waitcnt lgkmcnt(1)
	v_pk_fma_f32 v[138:139], v[142:143], v[230:231], v[138:139] op_sel_hi:[1,0,1]
	v_or_b32_e32 v142, v229, v210
	v_lshlrev_b32_e32 v142, 2, v142
	ds_bpermute_b32 v142, v142, v233
	v_or_b32_e32 v143, v229, v211
	v_lshlrev_b32_e32 v143, 2, v143
	v_pk_fma_f32 v[140:141], v[144:145], v[230:231], v[140:141] op_sel_hi:[1,0,1]
	ds_bpermute_b32 v144, v143, v233
	v_or_b32_e32 v143, v229, v212
	s_waitcnt lgkmcnt(2)
	v_pk_fma_f32 v[138:139], v[146:147], v[232:233], v[138:139] op_sel_hi:[1,0,1]
	v_lshlrev_b32_e32 v143, 2, v143
	s_waitcnt lgkmcnt(1)
	v_pk_fma_f32 v[134:135], v[134:135], v[142:143], v[138:139] op_sel_hi:[1,0,1]
	v_or_b32_e32 v138, v229, v213
	ds_bpermute_b32 v146, v143, v233
	v_lshlrev_b32_e32 v138, 2, v138
	ds_bpermute_b32 v138, v138, v233
	v_pk_fma_f32 v[140:141], v[148:149], v[232:233], v[140:141] op_sel_hi:[1,0,1]
	v_or_b32_e32 v139, v229, v214
	v_pk_fma_f32 v[136:137], v[136:137], v[142:143], v[140:141] op_sel_hi:[1,0,1]
	v_lshlrev_b32_e32 v139, 2, v139
	s_waitcnt vmcnt(40) lgkmcnt(2)
	v_pk_fma_f32 v[134:135], v[154:155], v[144:145], v[134:135] op_sel_hi:[1,0,1]
	v_pk_fma_f32 v[136:137], v[156:157], v[144:145], v[136:137] op_sel_hi:[1,0,1]
	ds_bpermute_b32 v140, v139, v233
	v_or_b32_e32 v139, v229, v215
	s_waitcnt vmcnt(39) lgkmcnt(2)
	v_pk_fma_f32 v[136:137], v[152:153], v[146:147], v[136:137] op_sel_hi:[1,0,1]
	v_pk_fma_f32 v[134:135], v[150:151], v[146:147], v[134:135] op_sel_hi:[1,0,1]
	v_lshlrev_b32_e32 v139, 2, v139
	ds_bpermute_b32 v142, v139, v233
	s_waitcnt vmcnt(38) lgkmcnt(2)
	v_pk_fma_f32 v[134:135], v[162:163], v[138:139], v[134:135] op_sel_hi:[1,0,1]
	v_pk_fma_f32 v[136:137], v[164:165], v[138:139], v[136:137] op_sel_hi:[1,0,1]
	v_or_b32_e32 v138, v229, v216
	v_lshlrev_b32_e32 v138, 2, v138
	v_or_b32_e32 v139, v229, v218
	ds_bpermute_b32 v138, v138, v233
	v_lshlrev_b32_e32 v139, 2, v139
	s_waitcnt vmcnt(37) lgkmcnt(2)
	v_pk_fma_f32 v[136:137], v[160:161], v[140:141], v[136:137] op_sel_hi:[1,0,1]
	v_pk_fma_f32 v[134:135], v[158:159], v[140:141], v[134:135] op_sel_hi:[1,0,1]
	ds_bpermute_b32 v140, v139, v233
	v_or_b32_e32 v139, v229, v219
	v_lshlrev_b32_e32 v139, 2, v139
	s_waitcnt vmcnt(36) lgkmcnt(2)
	v_pk_fma_f32 v[134:135], v[170:171], v[142:143], v[134:135] op_sel_hi:[1,0,1]
	v_pk_fma_f32 v[136:137], v[172:173], v[142:143], v[136:137] op_sel_hi:[1,0,1]
	ds_bpermute_b32 v142, v139, v233
	s_waitcnt vmcnt(35) lgkmcnt(2)
	v_pk_fma_f32 v[136:137], v[168:169], v[138:139], v[136:137] op_sel_hi:[1,0,1]
	v_pk_fma_f32 v[134:135], v[166:167], v[138:139], v[134:135] op_sel_hi:[1,0,1]
	v_xor_b32_e32 v138, 32, v221
	v_add_u32_e32 v139, 64, v229
	v_cmp_lt_i32_e32 vcc, v138, v139
	s_waitcnt vmcnt(34) lgkmcnt(1)
	v_pk_fma_f32 v[134:135], v[178:179], v[140:141], v[134:135] op_sel_hi:[1,0,1]
	v_pk_fma_f32 v[136:137], v[180:181], v[140:141], v[136:137] op_sel_hi:[1,0,1]
	v_cndmask_b32_e32 v138, v221, v138, vcc
	s_waitcnt vmcnt(33) lgkmcnt(0)
	v_pk_fma_f32 v[136:137], v[176:177], v[142:143], v[136:137] op_sel_hi:[1,0,1]
	v_pk_fma_f32 v[134:135], v[174:175], v[142:143], v[134:135] op_sel_hi:[1,0,1]
	v_lshlrev_b32_e32 v141, 2, v138
	s_lshl_b64 s[52:53], s[52:53], 8
	ds_bpermute_b32 v142, v231, v223
	ds_bpermute_b32 v138, v141, v134
	ds_bpermute_b32 v139, v141, v135
	ds_bpermute_b32 v140, v141, v136
	ds_bpermute_b32 v141, v141, v137
	s_or_b32 s2, s52, s78
	s_mul_i32 s48, s53, 0x210
	s_mul_hi_u32 s52, s2, 0x210
	s_add_i32 s48, s52, s48
	s_mulk_i32 s2, 0x210
	s_add_u32 s52, s3, s2
	s_addc_u32 s53, s4, s48
	s_and_saveexec_b64 s[56:57], s[8:9]
	s_cbranch_execz .LBB0_1304
	s_waitcnt lgkmcnt(0)
	v_pk_add_f32 v[136:137], v[136:137], v[140:141]
	v_pk_add_f32 v[134:135], v[134:135], v[138:139]
	global_store_dwordx4 v220, v[134:137], s[52:53]
	s_or_b64 exec, exec, s[56:57]
	s_and_saveexec_b64 s[56:57], s[10:11]
	s_cbranch_execz .LBB0_1299
	s_branch .LBB0_1305

; __device__ __forceinline__ void sb_decode_stream(Frame& F, unsigned* qctr, int base, int limit) {
;     ...
;     for (;;) {
;         const int bh = ((it >> 11) << 3) | (it & 7), blk = (it >> 3) & 255, h = it & 7;
;         const unsigned vn = __hip_atomic_fetch_add(qctr, 1u, __ATOMIC_RELAXED, __HIP_MEMORY_SCOPE_AGENT);
;         const float k2 = kin(12)[h] * 1.4426950408889634f;
;         int zi = 0;
;     ...
;         DEC_SCORES(A, 0);
.LBB0_1414:
	s_mov_b64 s[54:55], exec
	v_mbcnt_lo_u32_b32 v134, s54, 0
	v_mbcnt_hi_u32_b32 v134, s55, v134
	v_cmp_eq_u32_e32 vcc, 0, v134
	s_and_saveexec_b64 s[52:53], vcc
	s_cbranch_execz .LBB0_1416
	s_bcnt1_i32_b64 s2, s[54:55]
	v_mov_b32_e32 v135, s2
	global_atomic_add v253, v1, v135, s[38:39] sc0
.LBB0_1416:
	s_or_b64 exec, exec, s[52:53]
	s_waitcnt vmcnt(31)
	v_mul_f32_e32 v131, v131, v3
	v_fmac_f32_e32 v131, v130, v2
	v_mul_f32_e32 v130, v133, v5
	v_fmac_f32_e32 v130, v132, v4
	v_add_f32_e32 v130, v131, v130
	s_waitcnt vmcnt(30)
	v_mul_f32_e32 v127, v127, v3
	v_fmac_f32_e32 v127, v126, v2
	v_add_f32_dpp v130, v130, v130 quad_perm:[1,0,3,2] row_mask:0xf bank_mask:0xf bound_ctrl:1
	v_mul_f32_e32 v126, v129, v5
	v_fmac_f32_e32 v126, v128, v4
	v_add_f32_dpp v130, v130, v130 quad_perm:[2,3,0,1] row_mask:0xf bank_mask:0xf bound_ctrl:1
	s_waitcnt vmcnt(29)
	v_mul_f32_e32 v123, v123, v3
	v_add_f32_e32 v126, v127, v126
	v_add_f32_dpp v130, v130, v130 row_half_mirror row_mask:0xf bank_mask:0xf bound_ctrl:1
	v_fmac_f32_e32 v123, v122, v2
	v_mul_f32_e32 v122, v125, v5
	s_movk_i32 s54, 0x60
	v_add_f32_dpp v131, v130, v130 row_mirror row_mask:0xf bank_mask:0xf bound_ctrl:1
	v_add_f32_dpp v126, v126, v126 quad_perm:[1,0,3,2] row_mask:0xf bank_mask:0xf bound_ctrl:1
	v_fmac_f32_e32 v122, v124, v4
	s_waitcnt vmcnt(28)
	v_mul_f32_e32 v119, v119, v3
	ds_swizzle_b32 v132, v131 offset:swizzle(SWAP,16)
	v_add_f32_dpp v126, v126, v126 quad_perm:[2,3,0,1] row_mask:0xf bank_mask:0xf bound_ctrl:1
	v_add_f32_e32 v122, v123, v122
	v_fmac_f32_e32 v119, v118, v2
	v_mul_f32_e32 v118, v121, v5
	s_load_dwordx2 s[54:55], s[0:1], s54 offset:0x0
	v_add_f32_dpp v126, v126, v126 row_half_mirror row_mask:0xf bank_mask:0xf bound_ctrl:1
	v_add_f32_dpp v122, v122, v122 quad_perm:[1,0,3,2] row_mask:0xf bank_mask:0xf bound_ctrl:1
	v_fmac_f32_e32 v118, v120, v4
	s_waitcnt vmcnt(27)
	v_mul_f32_e32 v115, v115, v3
	v_add_f32_dpp v126, v126, v126 row_mirror row_mask:0xf bank_mask:0xf bound_ctrl:1
	v_add_f32_dpp v122, v122, v122 quad_perm:[2,3,0,1] row_mask:0xf bank_mask:0xf bound_ctrl:1
	v_add_f32_e32 v118, v119, v118
	v_fmac_f32_e32 v115, v114, v2
	v_mul_f32_e32 v114, v117, v5
	s_and_b32 s52, s48, 7
	s_waitcnt vmcnt(1)
	ds_swizzle_b32 v127, v126 offset:swizzle(SWAP,16)
	v_add_f32_dpp v122, v122, v122 row_half_mirror row_mask:0xf bank_mask:0xf bound_ctrl:1
	v_add_f32_dpp v118, v118, v118 quad_perm:[1,0,3,2] row_mask:0xf bank_mask:0xf bound_ctrl:1
	v_fmac_f32_e32 v114, v116, v4
	v_mul_f32_e32 v111, v111, v3
	s_lshl_b32 s2, s52, 2
	v_add_f32_dpp v122, v122, v122 row_mirror row_mask:0xf bank_mask:0xf bound_ctrl:1
	v_add_f32_dpp v118, v118, v118 quad_perm:[2,3,0,1] row_mask:0xf bank_mask:0xf bound_ctrl:1
	v_add_f32_e32 v114, v115, v114
	v_fmac_f32_e32 v111, v110, v2
	v_mul_f32_e32 v110, v113, v5
	v_mov_b32_e32 v130, s2
	s_waitcnt lgkmcnt(0)
	v_add_f32_e32 v131, v131, v132
	ds_swizzle_b32 v123, v122 offset:swizzle(SWAP,16)
	v_add_f32_dpp v118, v118, v118 row_half_mirror row_mask:0xf bank_mask:0xf bound_ctrl:1
	v_add_f32_dpp v114, v114, v114 quad_perm:[1,0,3,2] row_mask:0xf bank_mask:0xf bound_ctrl:1
	v_fmac_f32_e32 v110, v112, v4
	v_mul_f32_e32 v107, v107, v3
	global_load_dword v130, v130, s[54:55]
	v_readlane_b32 s2, v131, 0
	v_readlane_b32 s54, v131, 32
	v_mov_b32_e32 v131, 0
	v_add_f32_dpp v118, v118, v118 row_mirror row_mask:0xf bank_mask:0xf bound_ctrl:1
	v_add_f32_dpp v114, v114, v114 quad_perm:[2,3,0,1] row_mask:0xf bank_mask:0xf bound_ctrl:1
	v_add_f32_e32 v110, v111, v110
	v_fmac_f32_e32 v107, v106, v2
	v_mul_f32_e32 v106, v109, v5
	s_nop 3
	v_writelane_b32 v131, s2, 0
	ds_swizzle_b32 v119, v118 offset:swizzle(SWAP,16)
	v_add_f32_dpp v114, v114, v114 row_half_mirror row_mask:0xf bank_mask:0xf bound_ctrl:1
	v_add_f32_dpp v110, v110, v110 quad_perm:[1,0,3,2] row_mask:0xf bank_mask:0xf bound_ctrl:1
	v_fmac_f32_e32 v106, v108, v4
	v_mul_f32_e32 v103, v103, v3
	v_writelane_b32 v131, s54, 1
	v_add_f32_e32 v126, v126, v127
	v_add_f32_dpp v114, v114, v114 row_mirror row_mask:0xf bank_mask:0xf bound_ctrl:1
	v_add_f32_dpp v110, v110, v110 quad_perm:[2,3,0,1] row_mask:0xf bank_mask:0xf bound_ctrl:1
	v_add_f32_e32 v106, v107, v106
	v_fmac_f32_e32 v103, v102, v2
	v_mul_f32_e32 v102, v105, v5
	v_readlane_b32 s2, v126, 0
	s_nop 3
	v_writelane_b32 v131, s2, 2
	ds_swizzle_b32 v115, v114 offset:swizzle(SWAP,16)
	v_add_f32_dpp v110, v110, v110 row_half_mirror row_mask:0xf bank_mask:0xf bound_ctrl:1
	v_add_f32_dpp v106, v106, v106 quad_perm:[1,0,3,2] row_mask:0xf bank_mask:0xf bound_ctrl:1
	v_fmac_f32_e32 v102, v104, v4
	v_mul_f32_e32 v99, v99, v3
	v_readlane_b32 s54, v126, 32
	v_writelane_b32 v131, s54, 3
	s_waitcnt lgkmcnt(2)
	v_add_f32_e32 v122, v122, v123
	v_add_f32_dpp v110, v110, v110 row_mirror row_mask:0xf bank_mask:0xf bound_ctrl:1
	v_add_f32_dpp v106, v106, v106 quad_perm:[2,3,0,1] row_mask:0xf bank_mask:0xf bound_ctrl:1
	v_add_f32_e32 v102, v103, v102
	v_fmac_f32_e32 v99, v98, v2
	v_mul_f32_e32 v98, v101, v5
	v_readlane_b32 s2, v122, 0
	s_nop 3
	v_writelane_b32 v131, s2, 4
	ds_swizzle_b32 v111, v110 offset:swizzle(SWAP,16)
	v_add_f32_dpp v106, v106, v106 row_half_mirror row_mask:0xf bank_mask:0xf bound_ctrl:1
	v_add_f32_dpp v102, v102, v102 quad_perm:[1,0,3,2] row_mask:0xf bank_mask:0xf bound_ctrl:1
	v_fmac_f32_e32 v98, v100, v4
	v_mul_f32_e32 v95, v95, v3
	v_readlane_b32 s54, v122, 32
	v_writelane_b32 v131, s54, 5
	s_waitcnt lgkmcnt(2)
; __device__ __forceinline__ void sb_decode_stream(Frame& F, unsigned* qctr, int base, int limit) {
;     ...
;         DEC_SCORES(A, 0);
	v_add_f32_e32 v118, v118, v119
	v_add_f32_dpp v106, v106, v106 row_mirror row_mask:0xf bank_mask:0xf bound_ctrl:1
	v_add_f32_dpp v102, v102, v102 quad_perm:[2,3,0,1] row_mask:0xf bank_mask:0xf bound_ctrl:1
	v_add_f32_e32 v98, v99, v98
	v_fmac_f32_e32 v95, v94, v2
	v_mul_f32_e32 v94, v97, v5
	v_readlane_b32 s2, v118, 0
	s_nop 3
	v_writelane_b32 v131, s2, 6
	ds_swizzle_b32 v107, v106 offset:swizzle(SWAP,16)
	v_add_f32_dpp v102, v102, v102 row_half_mirror row_mask:0xf bank_mask:0xf bound_ctrl:1
	v_add_f32_dpp v98, v98, v98 quad_perm:[1,0,3,2] row_mask:0xf bank_mask:0xf bound_ctrl:1
	v_fmac_f32_e32 v94, v96, v4
	v_mul_f32_e32 v91, v91, v3
	v_readlane_b32 s54, v118, 32
	v_writelane_b32 v131, s54, 7
	s_waitcnt lgkmcnt(2)
	v_add_f32_e32 v114, v114, v115
	v_add_f32_dpp v102, v102, v102 row_mirror row_mask:0xf bank_mask:0xf bound_ctrl:1
	v_add_f32_dpp v98, v98, v98 quad_perm:[2,3,0,1] row_mask:0xf bank_mask:0xf bound_ctrl:1
	v_add_f32_e32 v94, v95, v94
	v_fmac_f32_e32 v91, v90, v2
	v_mul_f32_e32 v90, v93, v5
	v_readlane_b32 s2, v114, 0
	s_nop 3
	v_writelane_b32 v131, s2, 8
	ds_swizzle_b32 v103, v102 offset:swizzle(SWAP,16)
	v_add_f32_dpp v98, v98, v98 row_half_mirror row_mask:0xf bank_mask:0xf bound_ctrl:1
	v_add_f32_dpp v94, v94, v94 quad_perm:[1,0,3,2] row_mask:0xf bank_mask:0xf bound_ctrl:1
	v_fmac_f32_e32 v90, v92, v4
	v_mul_f32_e32 v87, v87, v3
	v_readlane_b32 s54, v114, 32
	v_writelane_b32 v131, s54, 9
	s_waitcnt lgkmcnt(2)
	v_add_f32_e32 v110, v110, v111
	v_add_f32_dpp v98, v98, v98 row_mirror row_mask:0xf bank_mask:0xf bound_ctrl:1
	v_add_f32_dpp v94, v94, v94 quad_perm:[2,3,0,1] row_mask:0xf bank_mask:0xf bound_ctrl:1
	v_add_f32_e32 v90, v91, v90
	v_fmac_f32_e32 v87, v86, v2
	v_mul_f32_e32 v86, v89, v5
	v_readlane_b32 s2, v110, 0
	s_nop 3
	v_writelane_b32 v131, s2, 10
	ds_swizzle_b32 v99, v98 offset:swizzle(SWAP,16)
	v_add_f32_dpp v94, v94, v94 row_half_mirror row_mask:0xf bank_mask:0xf bound_ctrl:1
	v_add_f32_dpp v90, v90, v90 quad_perm:[1,0,3,2] row_mask:0xf bank_mask:0xf bound_ctrl:1
	v_fmac_f32_e32 v86, v88, v4
	v_mul_f32_e32 v83, v83, v3
	v_readlane_b32 s54, v110, 32
	v_writelane_b32 v131, s54, 11
	s_waitcnt lgkmcnt(2)
	v_add_f32_e32 v106, v106, v107
	v_add_f32_dpp v94, v94, v94 row_mirror row_mask:0xf bank_mask:0xf bound_ctrl:1
	v_add_f32_dpp v90, v90, v90 quad_perm:[2,3,0,1] row_mask:0xf bank_mask:0xf bound_ctrl:1
	v_add_f32_e32 v86, v87, v86
	v_fmac_f32_e32 v83, v82, v2
	v_mul_f32_e32 v82, v85, v5
	v_readlane_b32 s2, v106, 0
	s_nop 3
	v_writelane_b32 v131, s2, 12
	ds_swizzle_b32 v95, v94 offset:swizzle(SWAP,16)
	v_add_f32_dpp v90, v90, v90 row_half_mirror row_mask:0xf bank_mask:0xf bound_ctrl:1
	v_add_f32_dpp v86, v86, v86 quad_perm:[1,0,3,2] row_mask:0xf bank_mask:0xf bound_ctrl:1
	v_fmac_f32_e32 v82, v84, v4
	v_mul_f32_e32 v75, v75, v3
	v_readlane_b32 s54, v106, 32
	v_writelane_b32 v131, s54, 13
	s_waitcnt lgkmcnt(2)
	v_add_f32_e32 v102, v102, v103
	v_add_f32_dpp v90, v90, v90 row_mirror row_mask:0xf bank_mask:0xf bound_ctrl:1
	v_add_f32_dpp v86, v86, v86 quad_perm:[2,3,0,1] row_mask:0xf bank_mask:0xf bound_ctrl:1
	v_add_f32_e32 v82, v83, v82
	v_fmac_f32_e32 v75, v74, v2
	v_mul_f32_e32 v74, v77, v5
	v_readlane_b32 s2, v102, 0
	s_nop 3
	v_writelane_b32 v131, s2, 14
	ds_swizzle_b32 v91, v90 offset:swizzle(SWAP,16)
	v_add_f32_dpp v86, v86, v86 row_half_mirror row_mask:0xf bank_mask:0xf bound_ctrl:1
	v_add_f32_dpp v82, v82, v82 quad_perm:[1,0,3,2] row_mask:0xf bank_mask:0xf bound_ctrl:1
	v_fmac_f32_e32 v74, v76, v4
	v_mul_f32_e32 v71, v71, v3
	v_readlane_b32 s54, v102, 32
	v_writelane_b32 v131, s54, 15
	s_waitcnt lgkmcnt(2)
	v_add_f32_e32 v98, v98, v99
	v_add_f32_dpp v86, v86, v86 row_mirror row_mask:0xf bank_mask:0xf bound_ctrl:1
	v_add_f32_dpp v82, v82, v82 quad_perm:[2,3,0,1] row_mask:0xf bank_mask:0xf bound_ctrl:1
	v_add_f32_e32 v74, v75, v74
	v_fmac_f32_e32 v71, v70, v2
	v_mul_f32_e32 v70, v73, v5
	v_mul_f32_e32 v63, v63, v3
	v_readlane_b32 s2, v98, 0
	s_nop 3
	v_writelane_b32 v131, s2, 16
	ds_swizzle_b32 v87, v86 offset:swizzle(SWAP,16)
	v_add_f32_dpp v82, v82, v82 row_half_mirror row_mask:0xf bank_mask:0xf bound_ctrl:1
	v_add_f32_dpp v74, v74, v74 quad_perm:[1,0,3,2] row_mask:0xf bank_mask:0xf bound_ctrl:1
	v_fmac_f32_e32 v70, v72, v4
	v_fmac_f32_e32 v63, v62, v2
	v_mul_f32_e32 v62, v65, v5
	v_readlane_b32 s54, v98, 32
	v_writelane_b32 v131, s54, 17
	s_waitcnt lgkmcnt(2)
	v_add_f32_e32 v94, v94, v95
	v_add_f32_dpp v82, v82, v82 row_mirror row_mask:0xf bank_mask:0xf bound_ctrl:1
	v_add_f32_dpp v74, v74, v74 quad_perm:[2,3,0,1] row_mask:0xf bank_mask:0xf bound_ctrl:1
	v_add_f32_e32 v70, v71, v70
	v_fmac_f32_e32 v62, v64, v4
	v_readlane_b32 s2, v94, 0
	s_nop 3
	v_writelane_b32 v131, s2, 18
	ds_swizzle_b32 v83, v82 offset:swizzle(SWAP,16)
	v_add_f32_dpp v74, v74, v74 row_half_mirror row_mask:0xf bank_mask:0xf bound_ctrl:1
	v_add_f32_dpp v70, v70, v70 quad_perm:[1,0,3,2] row_mask:0xf bank_mask:0xf bound_ctrl:1
	v_add_f32_e32 v62, v63, v62
	v_readlane_b32 s54, v94, 32
	v_writelane_b32 v131, s54, 19
	s_waitcnt lgkmcnt(2)
	v_add_f32_e32 v90, v90, v91
	v_add_f32_dpp v74, v74, v74 row_mirror row_mask:0xf bank_mask:0xf bound_ctrl:1
	v_add_f32_dpp v70, v70, v70 quad_perm:[2,3,0,1] row_mask:0xf bank_mask:0xf bound_ctrl:1
	v_add_f32_dpp v62, v62, v62 quad_perm:[1,0,3,2] row_mask:0xf bank_mask:0xf bound_ctrl:1
	v_readlane_b32 s2, v90, 0
	s_nop 3
	v_writelane_b32 v131, s2, 20
	ds_swizzle_b32 v75, v74 offset:swizzle(SWAP,16)
	v_add_f32_dpp v70, v70, v70 row_half_mirror row_mask:0xf bank_mask:0xf bound_ctrl:1
	v_add_f32_dpp v62, v62, v62 quad_perm:[2,3,0,1] row_mask:0xf bank_mask:0xf bound_ctrl:1
	v_readlane_b32 s54, v90, 32
	v_writelane_b32 v131, s54, 21
	s_waitcnt lgkmcnt(2)
; __device__ __forceinline__ void sb_decode_stream(Frame& F, unsigned* qctr, int base, int limit) {
;     ...
;         DEC_SCORES(A, 0);
; #pragma unroll
;         for (int i = 0; i < 16; ++i) A[i] = __builtin_nontemporal_load((const f32x4*)(CV + cb + (size_t)(2 * i) * (NH * HD)));
;         DEC_SCORES(B, 1);
	v_add_f32_e32 v86, v86, v87
	v_add_f32_dpp v70, v70, v70 row_mirror row_mask:0xf bank_mask:0xf bound_ctrl:1
	v_add_f32_dpp v62, v62, v62 row_half_mirror row_mask:0xf bank_mask:0xf bound_ctrl:1
	v_readlane_b32 s2, v86, 0
	s_nop 3
	v_writelane_b32 v131, s2, 22
	ds_swizzle_b32 v71, v70 offset:swizzle(SWAP,16)
	v_add_f32_dpp v62, v62, v62 row_mirror row_mask:0xf bank_mask:0xf bound_ctrl:1
	v_readlane_b32 s54, v86, 32
	v_writelane_b32 v131, s54, 23
	s_waitcnt lgkmcnt(2)
	v_add_f32_e32 v82, v82, v83
	ds_swizzle_b32 v63, v62 offset:swizzle(SWAP,16)
	v_readlane_b32 s2, v82, 0
	s_nop 3
	v_writelane_b32 v131, s2, 24
	v_readlane_b32 s54, v82, 32
	v_writelane_b32 v131, s54, 25
	s_waitcnt lgkmcnt(2)
	v_add_f32_e32 v74, v74, v75
	s_waitcnt lgkmcnt(1)
	v_add_f32_e32 v70, v70, v71
	v_readlane_b32 s2, v74, 0
	s_nop 3
	v_writelane_b32 v131, s2, 26
	v_readlane_b32 s54, v74, 32
	v_writelane_b32 v131, s54, 27
	v_readlane_b32 s2, v70, 0
	v_readlane_b32 s54, v70, 32
	s_nop 3
	v_writelane_b32 v131, s2, 28
	s_waitcnt lgkmcnt(0)
	v_add_f32_e32 v62, v62, v63
	v_lshl_add_u64 v[132:133], v[186:187], 2, s[44:45]
	v_writelane_b32 v131, s54, 29
	v_readlane_b32 s2, v62, 0
	v_readlane_b32 s54, v62, 32
	v_add_co_u32_e32 v62, vcc, s22, v132
	s_nop 3
	v_writelane_b32 v131, s2, 30
	v_mul_f32_e32 v79, v79, v3
	s_nop 0
	v_addc_co_u32_e32 v63, vcc, 0, v133, vcc
	v_writelane_b32 v131, s54, 31
	global_load_dwordx4 v[126:129], v[132:133], off nt
	global_load_dwordx4 v[114:117], v[62:63], off nt
	v_add_co_u32_e32 v62, vcc, s28, v132
	v_fmac_f32_e32 v79, v78, v2
	s_nop 0
	v_addc_co_u32_e32 v63, vcc, 0, v133, vcc
	v_add_co_u32_e32 v64, vcc, s29, v132
	v_mul_f32_e32 v78, v81, v5
	s_nop 0
	v_addc_co_u32_e32 v65, vcc, 0, v133, vcc
	global_load_dwordx4 v[122:125], v[62:63], off nt
	global_load_dwordx4 v[118:121], v[64:65], off nt
	v_add_co_u32_e32 v62, vcc, s30, v132
	v_fmac_f32_e32 v78, v80, v4
	s_nop 0
	v_addc_co_u32_e32 v63, vcc, 0, v133, vcc
	v_add_co_u32_e32 v64, vcc, s31, v132
	v_mul_f32_e32 v67, v67, v3
	s_nop 0
	v_addc_co_u32_e32 v65, vcc, 0, v133, vcc
	global_load_dwordx4 v[102:105], v[62:63], off nt
	global_load_dwordx4 v[106:109], v[64:65], off nt
	v_add_co_u32_e32 v62, vcc, s33, v132
	v_add_f32_e32 v78, v79, v78
	s_nop 0
	v_addc_co_u32_e32 v63, vcc, 0, v133, vcc
	v_add_co_u32_e32 v64, vcc, s35, v132
	v_fmac_f32_e32 v67, v66, v2
	s_nop 0
	v_addc_co_u32_e32 v65, vcc, 0, v133, vcc
	global_load_dwordx4 v[110:113], v[62:63], off nt
	global_load_dwordx4 v[86:89], v[64:65], off nt
	v_add_co_u32_e32 v62, vcc, s36, v132
	v_mul_f32_e32 v66, v69, v5
	s_nop 0
	v_addc_co_u32_e32 v63, vcc, 0, v133, vcc
	v_add_co_u32_e32 v64, vcc, s37, v132
	v_add_f32_dpp v78, v78, v78 quad_perm:[1,0,3,2] row_mask:0xf bank_mask:0xf bound_ctrl:1
	s_nop 0
	v_addc_co_u32_e32 v65, vcc, 0, v133, vcc
	global_load_dwordx4 v[98:101], v[62:63], off nt
	global_load_dwordx4 v[94:97], v[64:65], off nt
	v_add_co_u32_e32 v62, vcc, s41, v132
	v_fmac_f32_e32 v66, v68, v4
	s_nop 0
	v_addc_co_u32_e32 v63, vcc, 0, v133, vcc
	v_add_co_u32_e32 v64, vcc, s58, v132
	v_mul_f32_e32 v59, v59, v3
	s_nop 0
	v_addc_co_u32_e32 v65, vcc, 0, v133, vcc
	v_add_f32_dpp v78, v78, v78 quad_perm:[2,3,0,1] row_mask:0xf bank_mask:0xf bound_ctrl:1
	v_add_f32_e32 v66, v67, v66
	v_fmac_f32_e32 v59, v58, v2
	v_mul_f32_e32 v58, v61, v5
	global_load_dwordx4 v[70:73], v[62:63], off nt
	global_load_dwordx4 v[74:77], v[64:65], off nt
	v_add_co_u32_e32 v62, vcc, s59, v132
	v_add_f32_dpp v78, v78, v78 row_half_mirror row_mask:0xf bank_mask:0xf bound_ctrl:1
	v_add_f32_dpp v66, v66, v66 quad_perm:[1,0,3,2] row_mask:0xf bank_mask:0xf bound_ctrl:1
	v_fmac_f32_e32 v58, v60, v4
	v_mul_f32_e32 v55, v55, v3
	v_addc_co_u32_e32 v63, vcc, 0, v133, vcc
	v_add_f32_dpp v134, v78, v78 row_mirror row_mask:0xf bank_mask:0xf bound_ctrl:1
	v_add_f32_dpp v66, v66, v66 quad_perm:[2,3,0,1] row_mask:0xf bank_mask:0xf bound_ctrl:1
	v_add_f32_e32 v58, v59, v58
	v_fmac_f32_e32 v55, v54, v2
	v_mul_f32_e32 v54, v57, v5
	v_add_co_u32_e32 v64, vcc, s60, v132
	ds_swizzle_b32 v135, v134 offset:swizzle(SWAP,16)
	v_add_f32_dpp v66, v66, v66 row_half_mirror row_mask:0xf bank_mask:0xf bound_ctrl:1
	v_add_f32_dpp v58, v58, v58 quad_perm:[1,0,3,2] row_mask:0xf bank_mask:0xf bound_ctrl:1
	v_fmac_f32_e32 v54, v56, v4
	v_mul_f32_e32 v51, v51, v3
	v_addc_co_u32_e32 v65, vcc, 0, v133, vcc
	v_add_f32_dpp v66, v66, v66 row_mirror row_mask:0xf bank_mask:0xf bound_ctrl:1
	v_add_f32_dpp v58, v58, v58 quad_perm:[2,3,0,1] row_mask:0xf bank_mask:0xf bound_ctrl:1
	v_add_f32_e32 v54, v55, v54
	v_fmac_f32_e32 v51, v50, v2
	v_mul_f32_e32 v50, v53, v5
	v_add_co_u32_e32 v90, vcc, s61, v132
	ds_swizzle_b32 v67, v66 offset:swizzle(SWAP,16)
	v_add_f32_dpp v58, v58, v58 row_half_mirror row_mask:0xf bank_mask:0xf bound_ctrl:1
	v_add_f32_dpp v54, v54, v54 quad_perm:[1,0,3,2] row_mask:0xf bank_mask:0xf bound_ctrl:1
	v_fmac_f32_e32 v50, v52, v4
	v_mul_f32_e32 v47, v47, v3
	v_addc_co_u32_e32 v91, vcc, 0, v133, vcc
	v_add_f32_dpp v58, v58, v58 row_mirror row_mask:0xf bank_mask:0xf bound_ctrl:1
	v_add_f32_dpp v54, v54, v54 quad_perm:[2,3,0,1] row_mask:0xf bank_mask:0xf bound_ctrl:1
	v_add_f32_e32 v50, v51, v50
	v_fmac_f32_e32 v47, v46, v2
	v_mul_f32_e32 v46, v49, v5
	s_ashr_i32 s53, s48, 8
	v_add_co_u32_e32 v78, vcc, s62, v132
	ds_swizzle_b32 v59, v58 offset:swizzle(SWAP,16)
	v_add_f32_dpp v54, v54, v54 row_half_mirror row_mask:0xf bank_mask:0xf bound_ctrl:1
	v_add_f32_dpp v50, v50, v50 quad_perm:[1,0,3,2] row_mask:0xf bank_mask:0xf bound_ctrl:1
	v_fmac_f32_e32 v46, v48, v4
	v_mul_f32_e32 v43, v43, v3
	s_and_b32 s2, s53, -8
	v_addc_co_u32_e32 v79, vcc, 0, v133, vcc
	s_waitcnt lgkmcnt(2)
; __device__ __forceinline__ void sb_decode_stream(Frame& F, unsigned* qctr, int base, int limit) {
;     ...
;         DEC_SCORES(A, 0);
; #pragma unroll
;         for (int i = 0; i < 16; ++i) A[i] = __builtin_nontemporal_load((const f32x4*)(CV + cb + (size_t)(2 * i) * (NH * HD)));
;         DEC_SCORES(B, 1);
	v_add_f32_e32 v134, v134, v135
	v_add_f32_dpp v54, v54, v54 row_mirror row_mask:0xf bank_mask:0xf bound_ctrl:1
	v_add_f32_dpp v50, v50, v50 quad_perm:[2,3,0,1] row_mask:0xf bank_mask:0xf bound_ctrl:1
	v_add_f32_e32 v46, v47, v46
	v_fmac_f32_e32 v43, v42, v2
	v_mul_f32_e32 v42, v45, v5
	global_load_dwordx4 v[82:85], v[62:63], off nt
	s_nop 0
	global_load_dwordx4 v[62:65], v[64:65], off nt
	s_nop 0
	global_load_dwordx4 v[90:93], v[90:91], off nt
	s_nop 0
	global_load_dwordx4 v[78:81], v[78:79], off nt
	s_or_b32 s52, s2, s52
	v_readlane_b32 s2, v134, 0
	s_nop 3
	v_writelane_b32 v131, s2, 32
	ds_swizzle_b32 v55, v54 offset:swizzle(SWAP,16)
	v_add_f32_dpp v50, v50, v50 row_half_mirror row_mask:0xf bank_mask:0xf bound_ctrl:1
	v_add_f32_dpp v46, v46, v46 quad_perm:[1,0,3,2] row_mask:0xf bank_mask:0xf bound_ctrl:1
	v_fmac_f32_e32 v42, v44, v4
	v_mul_f32_e32 v39, v39, v3
	v_readlane_b32 s53, v134, 32
	v_writelane_b32 v131, s53, 33
	s_waitcnt lgkmcnt(2)
	v_add_f32_e32 v66, v66, v67
	v_add_f32_dpp v50, v50, v50 row_mirror row_mask:0xf bank_mask:0xf bound_ctrl:1
	v_add_f32_dpp v46, v46, v46 quad_perm:[2,3,0,1] row_mask:0xf bank_mask:0xf bound_ctrl:1
	v_add_f32_e32 v42, v43, v42
	v_fmac_f32_e32 v39, v38, v2
	v_mul_f32_e32 v38, v41, v5
	v_readlane_b32 s2, v66, 0
	s_nop 3
	v_writelane_b32 v131, s2, 34
	ds_swizzle_b32 v51, v50 offset:swizzle(SWAP,16)
	v_add_f32_dpp v46, v46, v46 row_half_mirror row_mask:0xf bank_mask:0xf bound_ctrl:1
	v_add_f32_dpp v42, v42, v42 quad_perm:[1,0,3,2] row_mask:0xf bank_mask:0xf bound_ctrl:1
	v_fmac_f32_e32 v38, v40, v4
	v_mul_f32_e32 v35, v35, v3
	v_readlane_b32 s53, v66, 32
	v_writelane_b32 v131, s53, 35
	s_waitcnt lgkmcnt(2)
	v_add_f32_e32 v58, v58, v59
	v_add_f32_dpp v46, v46, v46 row_mirror row_mask:0xf bank_mask:0xf bound_ctrl:1
	v_add_f32_dpp v42, v42, v42 quad_perm:[2,3,0,1] row_mask:0xf bank_mask:0xf bound_ctrl:1
	v_add_f32_e32 v38, v39, v38
	v_fmac_f32_e32 v35, v34, v2
	v_mul_f32_e32 v34, v37, v5
	v_readlane_b32 s2, v58, 0
	s_nop 3
	v_writelane_b32 v131, s2, 36
	ds_swizzle_b32 v47, v46 offset:swizzle(SWAP,16)
	v_add_f32_dpp v42, v42, v42 row_half_mirror row_mask:0xf bank_mask:0xf bound_ctrl:1
	v_add_f32_dpp v38, v38, v38 quad_perm:[1,0,3,2] row_mask:0xf bank_mask:0xf bound_ctrl:1
	v_fmac_f32_e32 v34, v36, v4
	v_mul_f32_e32 v31, v31, v3
	v_readlane_b32 s53, v58, 32
	v_writelane_b32 v131, s53, 37
	s_waitcnt lgkmcnt(2)
	v_add_f32_e32 v54, v54, v55
	v_add_f32_dpp v42, v42, v42 row_mirror row_mask:0xf bank_mask:0xf bound_ctrl:1
	v_add_f32_dpp v38, v38, v38 quad_perm:[2,3,0,1] row_mask:0xf bank_mask:0xf bound_ctrl:1
	v_add_f32_e32 v34, v35, v34
	v_fmac_f32_e32 v31, v30, v2
	v_mul_f32_e32 v30, v33, v5
	v_readlane_b32 s2, v54, 0
	s_nop 3
	v_writelane_b32 v131, s2, 38
	ds_swizzle_b32 v43, v42 offset:swizzle(SWAP,16)
	v_add_f32_dpp v38, v38, v38 row_half_mirror row_mask:0xf bank_mask:0xf bound_ctrl:1
	v_add_f32_dpp v34, v34, v34 quad_perm:[1,0,3,2] row_mask:0xf bank_mask:0xf bound_ctrl:1
	v_fmac_f32_e32 v30, v32, v4
	v_mul_f32_e32 v27, v27, v3
	v_readlane_b32 s53, v54, 32
	v_writelane_b32 v131, s53, 39
	s_waitcnt lgkmcnt(2)
	v_add_f32_e32 v50, v50, v51
	v_add_f32_dpp v38, v38, v38 row_mirror row_mask:0xf bank_mask:0xf bound_ctrl:1
	v_add_f32_dpp v34, v34, v34 quad_perm:[2,3,0,1] row_mask:0xf bank_mask:0xf bound_ctrl:1
	v_add_f32_e32 v30, v31, v30
	v_fmac_f32_e32 v27, v26, v2
	v_mul_f32_e32 v26, v29, v5
	v_readlane_b32 s2, v50, 0
	s_nop 3
	v_writelane_b32 v131, s2, 40
	ds_swizzle_b32 v39, v38 offset:swizzle(SWAP,16)
	v_add_f32_dpp v34, v34, v34 row_half_mirror row_mask:0xf bank_mask:0xf bound_ctrl:1
	v_add_f32_dpp v30, v30, v30 quad_perm:[1,0,3,2] row_mask:0xf bank_mask:0xf bound_ctrl:1
	v_fmac_f32_e32 v26, v28, v4
	v_mul_f32_e32 v23, v23, v3
	v_readlane_b32 s53, v50, 32
	v_writelane_b32 v131, s53, 41
	s_waitcnt lgkmcnt(2)
	v_add_f32_e32 v46, v46, v47
	v_add_f32_dpp v34, v34, v34 row_mirror row_mask:0xf bank_mask:0xf bound_ctrl:1
	v_add_f32_dpp v30, v30, v30 quad_perm:[2,3,0,1] row_mask:0xf bank_mask:0xf bound_ctrl:1
	v_add_f32_e32 v26, v27, v26
	v_fmac_f32_e32 v23, v22, v2
	v_mul_f32_e32 v22, v25, v5
	v_readlane_b32 s2, v46, 0
	s_nop 3
	v_writelane_b32 v131, s2, 42
	ds_swizzle_b32 v35, v34 offset:swizzle(SWAP,16)
	v_add_f32_dpp v30, v30, v30 row_half_mirror row_mask:0xf bank_mask:0xf bound_ctrl:1
	v_add_f32_dpp v26, v26, v26 quad_perm:[1,0,3,2] row_mask:0xf bank_mask:0xf bound_ctrl:1
	v_fmac_f32_e32 v22, v24, v4
	v_mul_f32_e32 v19, v19, v3
	v_readlane_b32 s53, v46, 32
	v_writelane_b32 v131, s53, 43
	s_waitcnt lgkmcnt(2)
	v_add_f32_e32 v42, v42, v43
	v_add_f32_dpp v30, v30, v30 row_mirror row_mask:0xf bank_mask:0xf bound_ctrl:1
	v_add_f32_dpp v26, v26, v26 quad_perm:[2,3,0,1] row_mask:0xf bank_mask:0xf bound_ctrl:1
	v_add_f32_e32 v22, v23, v22
	v_fmac_f32_e32 v19, v18, v2
	v_mul_f32_e32 v18, v21, v5
	v_readlane_b32 s2, v42, 0
	s_nop 3
	v_writelane_b32 v131, s2, 44
	ds_swizzle_b32 v31, v30 offset:swizzle(SWAP,16)
	v_add_f32_dpp v26, v26, v26 row_half_mirror row_mask:0xf bank_mask:0xf bound_ctrl:1
	v_add_f32_dpp v22, v22, v22 quad_perm:[1,0,3,2] row_mask:0xf bank_mask:0xf bound_ctrl:1
	v_fmac_f32_e32 v18, v20, v4
	v_mul_f32_e32 v15, v15, v3
	v_readlane_b32 s53, v42, 32
	v_writelane_b32 v131, s53, 45
	s_waitcnt lgkmcnt(2)
	v_add_f32_e32 v38, v38, v39
	v_add_f32_dpp v26, v26, v26 row_mirror row_mask:0xf bank_mask:0xf bound_ctrl:1
	v_add_f32_dpp v22, v22, v22 quad_perm:[2,3,0,1] row_mask:0xf bank_mask:0xf bound_ctrl:1
	v_add_f32_e32 v18, v19, v18
	v_fmac_f32_e32 v15, v14, v2
	v_mul_f32_e32 v14, v17, v5
	v_mul_f32_e32 v11, v11, v3
	v_readlane_b32 s2, v38, 0
	s_nop 3
	v_writelane_b32 v131, s2, 46
	ds_swizzle_b32 v27, v26 offset:swizzle(SWAP,16)
	v_add_f32_dpp v22, v22, v22 row_half_mirror row_mask:0xf bank_mask:0xf bound_ctrl:1
	v_add_f32_dpp v18, v18, v18 quad_perm:[1,0,3,2] row_mask:0xf bank_mask:0xf bound_ctrl:1
	v_fmac_f32_e32 v14, v16, v4
	v_fmac_f32_e32 v11, v10, v2
	v_mul_f32_e32 v10, v13, v5
	v_readlane_b32 s53, v38, 32
	v_writelane_b32 v131, s53, 47
	s_waitcnt lgkmcnt(2)
; __device__ __forceinline__ void sb_decode_stream(Frame& F, unsigned* qctr, int base, int limit) {
;     ...
;         DEC_SCORES(B, 1);
;     ...
; #pragma unroll
;         for (int i = 0; i < 16; ++i) B[i] = __builtin_nontemporal_load((const f32x4*)(CV + cb + (size_t)(32 + 2 * i) * (NH * HD)));
;         const float z = __builtin_bit_cast(float, zi);
;         const float e = __builtin_amdgcn_exp2f(-(z * k1 + k2));
;         const float be = __builtin_amdgcn_rcpf(1.0f + e), m = 1.0f - be;
;         float s = m;
; #pragma unroll
;         for (int o = 1; o < 64; o <<= 1) { const float t = __shfl_down(s, o); if (lane + o < 64) s *= t; }
;         const float tot = __shfl(s, 0);
;         const float sx = __shfl_down(s, 1);
;         const float a = be * (lane < 63 ? sx : 1.0f);
;         int itn = (int)(__builtin_amdgcn_readfirstlane(vn) >> 6); const bool more = itn < limit; itn = more ? itn + base : it;
;         const int bn = itn >> 11, hn = itn & 7, p0n = ((itn >> 3) & 255) * 64;
;         const int pagen = PT[bn * NPAGES + (p0n >> 7)];
;         const size_t cbn = (((size_t)pagen * PAGE + (p0n & 127)) * NH + hn) * HD + lo;
;         const size_t stepn = more ? (size_t)(NH * HD) : 0;
	v_add_f32_e32 v34, v34, v35
	v_add_f32_dpp v22, v22, v22 row_mirror row_mask:0xf bank_mask:0xf bound_ctrl:1
	v_add_f32_dpp v18, v18, v18 quad_perm:[2,3,0,1] row_mask:0xf bank_mask:0xf bound_ctrl:1
	v_add_f32_e32 v14, v15, v14
	v_fmac_f32_e32 v10, v12, v4
	v_pk_mul_f32 v[4:5], v[8:9], v[4:5]
	v_pk_mul_f32 v[2:3], v[6:7], v[2:3]
	v_readlane_b32 s2, v34, 0
	s_nop 3
	v_writelane_b32 v131, s2, 48
	ds_swizzle_b32 v23, v22 offset:swizzle(SWAP,16)
	v_add_f32_dpp v18, v18, v18 row_half_mirror row_mask:0xf bank_mask:0xf bound_ctrl:1
	v_add_f32_dpp v14, v14, v14 quad_perm:[1,0,3,2] row_mask:0xf bank_mask:0xf bound_ctrl:1
	v_pk_mov_b32 v[6:7], v[2:3], v[4:5] op_sel:[1,0]
	v_mov_b32_e32 v3, v5
	v_readlane_b32 s53, v34, 32
	v_writelane_b32 v131, s53, 49
	s_waitcnt lgkmcnt(2)
	v_add_f32_e32 v30, v30, v31
	v_add_f32_dpp v18, v18, v18 row_mirror row_mask:0xf bank_mask:0xf bound_ctrl:1
	v_add_f32_dpp v14, v14, v14 quad_perm:[2,3,0,1] row_mask:0xf bank_mask:0xf bound_ctrl:1
	v_add_f32_e32 v10, v11, v10
	v_pk_add_f32 v[2:3], v[6:7], v[2:3]
	v_readlane_b32 s2, v30, 0
	s_nop 3
	v_writelane_b32 v131, s2, 50
	ds_swizzle_b32 v19, v18 offset:swizzle(SWAP,16)
	v_add_f32_dpp v14, v14, v14 row_half_mirror row_mask:0xf bank_mask:0xf bound_ctrl:1
	v_add_f32_dpp v10, v10, v10 quad_perm:[1,0,3,2] row_mask:0xf bank_mask:0xf bound_ctrl:1
	v_add_f32_e32 v2, v2, v3
	v_readlane_b32 s53, v30, 32
	v_writelane_b32 v131, s53, 51
	s_waitcnt lgkmcnt(2)
	v_add_f32_e32 v26, v26, v27
	v_add_f32_dpp v14, v14, v14 row_mirror row_mask:0xf bank_mask:0xf bound_ctrl:1
	v_add_f32_dpp v10, v10, v10 quad_perm:[2,3,0,1] row_mask:0xf bank_mask:0xf bound_ctrl:1
	v_add_f32_dpp v2, v2, v2 quad_perm:[1,0,3,2] row_mask:0xf bank_mask:0xf bound_ctrl:1
	v_readlane_b32 s2, v26, 0
	s_nop 3
	v_writelane_b32 v131, s2, 52
	ds_swizzle_b32 v15, v14 offset:swizzle(SWAP,16)
	v_add_f32_dpp v10, v10, v10 row_half_mirror row_mask:0xf bank_mask:0xf bound_ctrl:1
	v_add_f32_dpp v2, v2, v2 quad_perm:[2,3,0,1] row_mask:0xf bank_mask:0xf bound_ctrl:1
	v_readlane_b32 s53, v26, 32
	v_writelane_b32 v131, s53, 53
	s_waitcnt lgkmcnt(2)
	v_add_f32_e32 v22, v22, v23
	v_add_f32_dpp v10, v10, v10 row_mirror row_mask:0xf bank_mask:0xf bound_ctrl:1
	v_add_f32_dpp v2, v2, v2 row_half_mirror row_mask:0xf bank_mask:0xf bound_ctrl:1
	v_readlane_b32 s2, v22, 0
	s_nop 3
	v_writelane_b32 v131, s2, 54
	ds_swizzle_b32 v11, v10 offset:swizzle(SWAP,16)
	v_add_f32_dpp v2, v2, v2 row_mirror row_mask:0xf bank_mask:0xf bound_ctrl:1
	v_readlane_b32 s53, v22, 32
	v_writelane_b32 v131, s53, 55
	s_waitcnt lgkmcnt(2)
	v_add_f32_e32 v18, v18, v19
	ds_swizzle_b32 v3, v2 offset:swizzle(SWAP,16)
	v_readlane_b32 s2, v18, 0
	s_nop 3
	v_writelane_b32 v131, s2, 56
	v_readlane_b32 s53, v18, 32
	v_writelane_b32 v131, s53, 57
	s_waitcnt lgkmcnt(2)
	v_add_f32_e32 v14, v14, v15
	s_waitcnt lgkmcnt(1)
	v_add_f32_e32 v10, v10, v11
	v_readlane_b32 s2, v14, 0
	s_nop 3
	v_writelane_b32 v131, s2, 58
	v_readlane_b32 s53, v14, 32
	v_writelane_b32 v131, s53, 59
	v_readlane_b32 s2, v10, 0
	v_readlane_b32 s53, v10, 32
	s_nop 3
	v_writelane_b32 v131, s2, 60
	s_waitcnt lgkmcnt(0)
	v_add_f32_e32 v2, v2, v3
	v_writelane_b32 v131, s53, 61
	s_bfe_u32 s79, s48, 0x80003
	v_readlane_b32 s2, v2, 0
	v_readlane_b32 s53, v2, 32
	v_add_co_u32_e32 v2, vcc, s63, v132
	s_nop 3
	v_writelane_b32 v131, s2, 62
	s_waitcnt vmcnt(17)
	v_readfirstlane_b32 s2, v253
	s_nop 0
	v_addc_co_u32_e32 v3, vcc, 0, v133, vcc
	v_add_co_u32_e32 v4, vcc, s64, v132
	v_writelane_b32 v131, s53, 63
	s_ashr_i32 s80, s2, 6
	s_nop 0
	v_addc_co_u32_e32 v5, vcc, 0, v133, vcc
	global_load_dwordx4 v[18:21], v[2:3], off nt
	global_load_dwordx4 v[6:9], v[4:5], off nt
	v_add_co_u32_e32 v2, vcc, s65, v132
	s_cmpk_lt_i32 s80, 0x2800
	s_nop 0
	v_addc_co_u32_e32 v3, vcc, 0, v133, vcc
	v_add_co_u32_e32 v4, vcc, s66, v132
	s_cselect_b64 s[56:57], -1, 0
	s_nop 0
	v_addc_co_u32_e32 v5, vcc, 0, v133, vcc
	s_cmpk_gt_i32 s80, 0x27ff
	global_load_dwordx4 v[14:17], v[2:3], off nt
	global_load_dwordx4 v[10:13], v[4:5], off nt
	v_add_co_u32_e32 v2, vcc, s67, v132
	s_cselect_b64 s[54:55], -1, 0
	s_addk_i32 s80, 0x1800
	v_addc_co_u32_e32 v3, vcc, 0, v133, vcc
	s_and_b64 s[82:83], s[56:57], exec
	v_add_co_u32_e32 v4, vcc, s68, v132
	s_cselect_b32 s53, s80, s48
	s_nop 0
	v_addc_co_u32_e32 v5, vcc, 0, v133, vcc
	s_ashr_i32 s48, s53, 11
	global_load_dwordx4 v[138:141], v[2:3], off nt
	global_load_dwordx4 v[142:145], v[4:5], off nt
	v_add_co_u32_e32 v2, vcc, s69, v132
	s_lshl_b32 s81, s48, 7
	s_bfe_u32 s82, s53, 0x70004
	v_addc_co_u32_e32 v3, vcc, 0, v133, vcc
	s_or_b32 s82, s81, s82
	v_add_co_u32_e32 v4, vcc, s70, v132
	s_ashr_i32 s83, s82, 31
	s_nop 0
	v_addc_co_u32_e32 v5, vcc, 0, v133, vcc
	s_and_b32 s2, s53, 7
	s_lshl_b64 s[82:83], s[82:83], 2
	global_load_dwordx4 v[146:149], v[2:3], off nt
	global_load_dwordx4 v[134:137], v[4:5], off nt
	s_waitcnt vmcnt(24)
	v_pk_mul_f32 v[4:5], v[130:131], s[50:51]
	s_add_u32 s82, s46, s82
	v_add_f32_e32 v4, v4, v5
	s_addc_u32 s83, s47, s83
	v_exp_f32_e64 v5, -v4
	global_load_dword v4, v1, s[82:83]
	v_add_co_u32_e32 v2, vcc, s71, v132
	v_add_f32_e32 v5, 1.0, v5
	s_nop 0
	v_addc_co_u32_e32 v3, vcc, 0, v133, vcc
	v_rcp_f32_e32 v5, v5
	v_add_co_u32_e32 v22, vcc, s72, v132
	v_and_b32_e32 v24, 63, v222
	s_nop 0
	v_addc_co_u32_e32 v23, vcc, 0, v133, vcc
	v_cmp_ne_u32_e32 vcc, 63, v24
	global_load_dwordx4 v[154:157], v[2:3], off nt
	global_load_dwordx4 v[150:153], v[22:23], off nt
	v_addc_co_u32_e32 v2, vcc, 0, v222, vcc
	v_sub_f32_e32 v22, 1.0, v5
	v_lshlrev_b32_e32 v25, 2, v2
	ds_bpermute_b32 v23, v25, v22
	v_add_co_u32_e32 v2, vcc, s73, v132
	v_and_b32_e32 v231, 64, v222
	s_nop 0
	v_addc_co_u32_e32 v3, vcc, 0, v133, vcc
	s_waitcnt lgkmcnt(0)
; __device__ __forceinline__ void sb_decode_stream(Frame& F, unsigned* qctr, int base, int limit) {
;     ...
;         float s = m;
; #pragma unroll
;         for (int o = 1; o < 64; o <<= 1) { const float t = __shfl_down(s, o); if (lane + o < 64) s *= t; }
;         const float tot = __shfl(s, 0);
;         const float sx = __shfl_down(s, 1);
;         const float a = be * (lane < 63 ? sx : 1.0f);
;         int itn = (int)(__builtin_amdgcn_readfirstlane(vn) >> 6); const bool more = itn < limit; itn = more ? itn + base : it;
;         const int bn = itn >> 11, hn = itn & 7, p0n = ((itn >> 3) & 255) * 64;
;         const int pagen = PT[bn * NPAGES + (p0n >> 7)];
;         const size_t cbn = (((size_t)pagen * PAGE + (p0n & 127)) * NH + hn) * HD + lo;
;         const size_t stepn = more ? (size_t)(NH * HD) : 0;
;         f32x4 o4 = {0.f, 0.f, 0.f, 0.f};
; #pragma unroll
;         for (int i = 0; i < 16; ++i) { const float aj = __shfl(a, 2 * i + half); o4 += aj * A[i]; }
	v_mul_f32_e32 v23, v22, v23
	v_cmp_gt_u32_e32 vcc, 62, v24
	v_cndmask_b32_e64 v26, v22, v23, s[6:7]
	s_lshl_b32 s53, s53, 6
	v_cndmask_b32_e64 v22, 0, 2, vcc
	v_add_lshl_u32 v22, v22, v222, 2
	ds_bpermute_b32 v27, v22, v26
	v_add_co_u32_e32 v22, vcc, s74, v132
	s_and_b32 s53, s53, 0x200
	s_nop 0
	v_addc_co_u32_e32 v23, vcc, 0, v133, vcc
	global_load_dwordx4 v[162:165], v[2:3], off nt
	global_load_dwordx4 v[158:161], v[22:23], off nt
	s_waitcnt lgkmcnt(0)
	v_mul_f32_e32 v2, v26, v27
	v_cmp_gt_u32_e32 vcc, 60, v24
	v_cndmask_b32_e64 v22, v26, v2, s[12:13]
	s_mulk_i32 s48, 0x7040
	v_cndmask_b32_e64 v2, 0, 4, vcc
	v_add_lshl_u32 v2, v2, v222, 2
	ds_bpermute_b32 v23, v2, v22
	v_add_co_u32_e32 v2, vcc, s75, v132
	v_or_b32_e32 v228, v231, v208
	s_nop 0
	v_addc_co_u32_e32 v3, vcc, 0, v133, vcc
	s_waitcnt lgkmcnt(0)
	v_mul_f32_e32 v23, v22, v23
	v_cmp_gt_u32_e32 vcc, 56, v24
	v_cndmask_b32_e64 v26, v22, v23, s[14:15]
	v_lshlrev_b32_e32 v228, 2, v228
	v_cndmask_b32_e64 v22, 0, 8, vcc
	v_add_lshl_u32 v22, v22, v222, 2
	ds_bpermute_b32 v27, v22, v26
	v_add_co_u32_e32 v22, vcc, s76, v132
	v_or_b32_e32 v230, v231, v209
	s_nop 0
	v_addc_co_u32_e32 v23, vcc, 0, v133, vcc
	global_load_dwordx4 v[170:173], v[2:3], off nt
	global_load_dwordx4 v[166:169], v[22:23], off nt
	s_waitcnt lgkmcnt(0)
	v_mul_f32_e32 v2, v26, v27
	v_cmp_gt_u32_e32 vcc, 48, v24
	v_cndmask_b32_e64 v22, v26, v2, s[16:17]
	v_lshlrev_b32_e32 v230, 2, v230
	v_cndmask_b32_e64 v2, 0, 16, vcc
	v_add_lshl_u32 v2, v2, v222, 2
	ds_bpermute_b32 v23, v2, v22
	v_add_co_u32_e32 v2, vcc, s77, v132
	v_or_b32_e32 v232, v231, v210
	s_nop 0
	v_addc_co_u32_e32 v3, vcc, 0, v133, vcc
	s_waitcnt lgkmcnt(0)
	v_mul_f32_e32 v23, v22, v23
	v_cndmask_b32_e64 v24, v22, v23, s[18:19]
	ds_bpermute_b32 v26, v223, v24
	v_add_co_u32_e32 v22, vcc, s78, v132
	v_lshlrev_b32_e32 v232, 2, v232
	s_nop 0
	v_addc_co_u32_e32 v23, vcc, 0, v133, vcc
	s_waitcnt lgkmcnt(0)
	v_mul_f32_e32 v26, v24, v26
	v_cndmask_b32_e64 v229, v24, v26, s[20:21]
	ds_bpermute_b32 v24, v25, v229
	global_load_dwordx4 v[178:181], v[2:3], off nt
	global_load_dwordx4 v[174:177], v[22:23], off nt
	v_or_b32_e32 v22, v231, v188
	v_lshlrev_b32_e32 v22, 2, v22
	v_or_b32_e32 v23, v231, v189
	s_waitcnt lgkmcnt(0)
	v_cndmask_b32_e64 v2, 1.0, v24, s[6:7]
	v_mul_f32_e32 v234, v5, v2
	s_waitcnt vmcnt(8)
	v_ashrrev_i32_e32 v5, 31, v4
	v_lshlrev_b64 v[2:3], 10, v[4:5]
	v_or_b32_e32 v4, v231, v183
	v_lshlrev_b32_e32 v4, 2, v4
	ds_bpermute_b32 v4, v4, v234
	ds_bpermute_b32 v22, v22, v234
	v_or_b32_e32 v2, s53, v2
	v_or_b32_e32 v2, s2, v2
	v_lshlrev_b32_e32 v23, 2, v23
	v_lshlrev_b64 v[2:3], 7, v[2:3]
	ds_bpermute_b32 v24, v23, v234
	v_or_b32_e32 v23, v231, v190
	v_lshl_add_u64 v[186:187], v[2:3], 0, v[184:185]
	s_waitcnt lgkmcnt(2)
	v_pk_fma_f32 v[2:3], v[126:127], v[4:5], 0 op_sel_hi:[1,0,0]
	v_pk_fma_f32 v[4:5], v[128:129], v[4:5], 0 op_sel_hi:[1,0,0]
	v_lshlrev_b32_e32 v23, 2, v23
	s_waitcnt lgkmcnt(1)
	v_pk_fma_f32 v[4:5], v[116:117], v[22:23], v[4:5] op_sel_hi:[1,0,1]
	v_pk_fma_f32 v[2:3], v[114:115], v[22:23], v[2:3] op_sel_hi:[1,0,1]
	v_or_b32_e32 v22, v231, v191
	ds_bpermute_b32 v26, v23, v234
	v_lshlrev_b32_e32 v22, 2, v22
	ds_bpermute_b32 v22, v22, v234
	v_or_b32_e32 v23, v231, v192
	v_lshlrev_b32_e32 v23, 2, v23
	s_waitcnt lgkmcnt(2)
	v_pk_fma_f32 v[2:3], v[122:123], v[24:25], v[2:3] op_sel_hi:[1,0,1]
	v_pk_fma_f32 v[4:5], v[124:125], v[24:25], v[4:5] op_sel_hi:[1,0,1]
	ds_bpermute_b32 v24, v23, v234
	v_or_b32_e32 v23, v231, v193
	s_waitcnt lgkmcnt(2)
	v_pk_fma_f32 v[4:5], v[120:121], v[26:27], v[4:5] op_sel_hi:[1,0,1]
	v_pk_fma_f32 v[2:3], v[118:119], v[26:27], v[2:3] op_sel_hi:[1,0,1]
	v_lshlrev_b32_e32 v23, 2, v23
	s_waitcnt lgkmcnt(1)
	v_pk_fma_f32 v[2:3], v[102:103], v[22:23], v[2:3] op_sel_hi:[1,0,1]
	v_pk_fma_f32 v[4:5], v[104:105], v[22:23], v[4:5] op_sel_hi:[1,0,1]
	v_or_b32_e32 v22, v231, v194
	ds_bpermute_b32 v26, v23, v234
	v_lshlrev_b32_e32 v22, 2, v22
	ds_bpermute_b32 v22, v22, v234
	v_or_b32_e32 v23, v231, v195
	v_lshlrev_b32_e32 v23, 2, v23
	s_waitcnt lgkmcnt(2)
	v_pk_fma_f32 v[4:5], v[108:109], v[24:25], v[4:5] op_sel_hi:[1,0,1]
	v_pk_fma_f32 v[2:3], v[106:107], v[24:25], v[2:3] op_sel_hi:[1,0,1]
	ds_bpermute_b32 v24, v23, v234
	v_or_b32_e32 v23, v231, v196
	s_waitcnt lgkmcnt(2)
	v_pk_fma_f32 v[2:3], v[110:111], v[26:27], v[2:3] op_sel_hi:[1,0,1]
	v_pk_fma_f32 v[4:5], v[112:113], v[26:27], v[4:5] op_sel_hi:[1,0,1]
	v_lshlrev_b32_e32 v23, 2, v23
	s_waitcnt lgkmcnt(1)
	v_pk_fma_f32 v[4:5], v[88:89], v[22:23], v[4:5] op_sel_hi:[1,0,1]
	v_pk_fma_f32 v[2:3], v[86:87], v[22:23], v[2:3] op_sel_hi:[1,0,1]
	v_or_b32_e32 v22, v231, v197
	ds_bpermute_b32 v26, v23, v234
	v_lshlrev_b32_e32 v22, 2, v22
	ds_bpermute_b32 v22, v22, v234
	v_or_b32_e32 v23, v231, v198
	v_lshlrev_b32_e32 v23, 2, v23
	s_waitcnt lgkmcnt(2)
	v_pk_fma_f32 v[2:3], v[98:99], v[24:25], v[2:3] op_sel_hi:[1,0,1]
	v_pk_fma_f32 v[4:5], v[100:101], v[24:25], v[4:5] op_sel_hi:[1,0,1]
	ds_bpermute_b32 v24, v23, v234
	v_or_b32_e32 v23, v231, v200
	v_lshlrev_b32_e32 v23, 2, v23
	s_waitcnt lgkmcnt(2)
	v_pk_fma_f32 v[4:5], v[96:97], v[26:27], v[4:5] op_sel_hi:[1,0,1]
	v_pk_fma_f32 v[2:3], v[94:95], v[26:27], v[2:3] op_sel_hi:[1,0,1]
	ds_bpermute_b32 v26, v23, v234
	s_waitcnt lgkmcnt(2)
	v_pk_fma_f32 v[2:3], v[70:71], v[22:23], v[2:3] op_sel_hi:[1,0,1]
	v_pk_fma_f32 v[4:5], v[72:73], v[22:23], v[4:5] op_sel_hi:[1,0,1]
	v_or_b32_e32 v22, v231, v201
	v_or_b32_e32 v23, v231, v202
	v_lshlrev_b32_e32 v22, 2, v22
	v_lshlrev_b32_e32 v23, 2, v23
	s_waitcnt lgkmcnt(1)
; __device__ __forceinline__ void sb_decode_stream(Frame& F, unsigned* qctr, int base, int limit) {
;     ...
;         for (int i = 0; i < 16; ++i) { const float aj = __shfl(a, 2 * i + half); o4 += aj * A[i]; }
;         const f32x4 q4n = *(const f32x4*)(SSP(S_PROJ) + (size_t)bn * IN_COLS + hn * HD + 4 * l32);
; #pragma unroll
;         for (int i = 0; i < 16; ++i) A[i] = __builtin_nontemporal_load((const f32x4*)(CK + cbn + (size_t)(2 * i) * stepn));
; #pragma unroll
;         for (int i = 0; i < 16; ++i) { const float aj = __shfl(a, 32 + 2 * i + half); o4 += aj * B[i]; }
; #pragma unroll
;         for (int i = 0; i < 16; ++i) B[i] = __builtin_nontemporal_load((const f32x4*)(CK + cbn + (size_t)(32 + 2 * i) * stepn));
	v_pk_fma_f32 v[4:5], v[76:77], v[24:25], v[4:5] op_sel_hi:[1,0,1]
	v_pk_fma_f32 v[2:3], v[74:75], v[24:25], v[2:3] op_sel_hi:[1,0,1]
	ds_bpermute_b32 v22, v22, v234
	ds_bpermute_b32 v24, v23, v234
	v_or_b32_e32 v23, v231, v203
	v_lshlrev_b32_e32 v23, 2, v23
	s_ashr_i32 s53, s48, 31
	s_waitcnt lgkmcnt(2)
	v_pk_fma_f32 v[2:3], v[82:83], v[26:27], v[2:3] op_sel_hi:[1,0,1]
	v_pk_fma_f32 v[4:5], v[84:85], v[26:27], v[4:5] op_sel_hi:[1,0,1]
	ds_bpermute_b32 v26, v23, v234
	s_add_u32 s48, s3, s48
	s_addc_u32 s53, s4, s53
	s_lshl_b32 s2, s2, 9
	s_add_u32 s82, s48, s2
	s_waitcnt lgkmcnt(2)
	v_pk_fma_f32 v[4:5], v[64:65], v[22:23], v[4:5] op_sel_hi:[1,0,1]
	v_pk_fma_f32 v[2:3], v[62:63], v[22:23], v[2:3] op_sel_hi:[1,0,1]
	s_addc_u32 s83, s53, 0
	s_waitcnt lgkmcnt(1)
	v_pk_fma_f32 v[2:3], v[90:91], v[24:25], v[2:3] op_sel_hi:[1,0,1]
	v_pk_fma_f32 v[4:5], v[92:93], v[24:25], v[4:5] op_sel_hi:[1,0,1]
	s_and_b64 s[56:57], s[56:57], exec
	s_waitcnt lgkmcnt(0)
	v_pk_fma_f32 v[22:23], v[80:81], v[26:27], v[4:5] op_sel_hi:[1,0,1]
	v_pk_fma_f32 v[24:25], v[78:79], v[26:27], v[2:3] op_sel_hi:[1,0,1]
	v_lshl_add_u64 v[26:27], v[186:187], 2, s[42:43]
	s_cselect_b32 s48, 0x2000, 0
	v_lshl_add_u64 v[28:29], v[26:27], 0, s[48:49]
	global_load_dwordx4 v[2:5], v221, s[82:83]
	global_load_dwordx4 v[130:133], v[26:27], off nt
	global_load_dwordx4 v[126:129], v[28:29], off nt
	v_lshl_add_u64 v[26:27], v[28:29], 0, s[48:49]
	v_lshl_add_u64 v[28:29], v[26:27], 0, s[48:49]
	global_load_dwordx4 v[122:125], v[26:27], off nt
	global_load_dwordx4 v[118:121], v[28:29], off nt
	v_lshl_add_u64 v[26:27], v[28:29], 0, s[48:49]
	v_lshl_add_u64 v[28:29], v[26:27], 0, s[48:49]
	global_load_dwordx4 v[114:117], v[26:27], off nt
	global_load_dwordx4 v[110:113], v[28:29], off nt
	v_lshl_add_u64 v[26:27], v[28:29], 0, s[48:49]
	v_lshl_add_u64 v[28:29], v[26:27], 0, s[48:49]
	global_load_dwordx4 v[106:109], v[26:27], off nt
	global_load_dwordx4 v[102:105], v[28:29], off nt
	v_lshl_add_u64 v[26:27], v[28:29], 0, s[48:49]
	v_or_b32_e32 v28, v231, v204
	v_lshlrev_b32_e32 v28, 2, v28
	ds_bpermute_b32 v28, v28, v234
	global_load_dwordx4 v[98:101], v[26:27], off nt
	v_lshl_add_u64 v[26:27], v[26:27], 0, s[48:49]
	global_load_dwordx4 v[94:97], v[26:27], off nt
	v_lshl_add_u64 v[26:27], v[26:27], 0, s[48:49]
	s_waitcnt lgkmcnt(0)
	v_pk_fma_f32 v[20:21], v[20:21], v[28:29], v[22:23] op_sel_hi:[1,0,1]
	v_or_b32_e32 v22, v231, v205
	v_or_b32_e32 v23, v231, v206
	v_lshlrev_b32_e32 v22, 2, v22
	v_lshlrev_b32_e32 v23, 2, v23
	v_pk_fma_f32 v[18:19], v[18:19], v[28:29], v[24:25] op_sel_hi:[1,0,1]
	ds_bpermute_b32 v22, v22, v234
	ds_bpermute_b32 v24, v23, v234
	v_or_b32_e32 v23, v231, v207
	v_lshlrev_b32_e32 v23, 2, v23
	global_load_dwordx4 v[90:93], v[26:27], off nt
	v_lshl_add_u64 v[26:27], v[26:27], 0, s[48:49]
	ds_bpermute_b32 v28, v23, v234
	global_load_dwordx4 v[86:89], v[26:27], off nt
	v_lshl_add_u64 v[26:27], v[26:27], 0, s[48:49]
	global_load_dwordx4 v[82:85], v[26:27], off nt
	v_lshl_add_u64 v[26:27], v[26:27], 0, s[48:49]
	global_load_dwordx4 v[74:77], v[26:27], off nt
	v_lshl_add_u64 v[26:27], v[26:27], 0, s[48:49]
	s_waitcnt lgkmcnt(2)
	v_pk_fma_f32 v[6:7], v[6:7], v[22:23], v[18:19] op_sel_hi:[1,0,1]
	global_load_dwordx4 v[70:73], v[26:27], off nt
	v_lshl_add_u64 v[26:27], v[26:27], 0, s[48:49]
	s_waitcnt lgkmcnt(1)
	v_pk_fma_f32 v[6:7], v[14:15], v[24:25], v[6:7] op_sel_hi:[1,0,1]
	v_pk_fma_f32 v[8:9], v[8:9], v[22:23], v[20:21] op_sel_hi:[1,0,1]
	s_waitcnt lgkmcnt(0)
	v_pk_fma_f32 v[226:227], v[10:11], v[28:29], v[6:7] op_sel_hi:[1,0,1]
	v_lshl_add_u64 v[6:7], v[26:27], 0, s[48:49]
	global_load_dwordx4 v[78:81], v[6:7], off nt
	v_lshl_add_u64 v[6:7], v[6:7], 0, s[48:49]
	global_load_dwordx4 v[66:69], v[6:7], off nt
	v_lshl_add_u64 v[6:7], v[6:7], 0, s[48:49]
	global_load_dwordx4 v[58:61], v[6:7], off nt
	v_lshl_add_u64 v[6:7], v[6:7], 0, s[48:49]
	global_load_dwordx4 v[54:57], v[6:7], off nt
	v_lshl_add_u64 v[6:7], v[6:7], 0, s[48:49]
	global_load_dwordx4 v[50:53], v[6:7], off nt
	v_lshl_add_u64 v[6:7], v[6:7], 0, s[48:49]
	global_load_dwordx4 v[46:49], v[6:7], off nt
	v_lshl_add_u64 v[6:7], v[6:7], 0, s[48:49]
	global_load_dwordx4 v[42:45], v[6:7], off nt
	v_lshl_add_u64 v[6:7], v[6:7], 0, s[48:49]
	global_load_dwordx4 v[38:41], v[6:7], off nt
	v_lshl_add_u64 v[6:7], v[6:7], 0, s[48:49]
	global_load_dwordx4 v[34:37], v[6:7], off nt
	v_lshl_add_u64 v[6:7], v[6:7], 0, s[48:49]
	v_pk_fma_f32 v[8:9], v[16:17], v[24:25], v[8:9] op_sel_hi:[1,0,1]
	global_load_dwordx4 v[30:33], v[6:7], off nt
	v_lshl_add_u64 v[6:7], v[6:7], 0, s[48:49]
	global_load_dwordx4 v[62:65], v[26:27], off nt
	v_pk_fma_f32 v[224:225], v[12:13], v[28:29], v[8:9] op_sel_hi:[1,0,1]
	global_load_dwordx4 v[26:29], v[6:7], off nt
	v_lshl_add_u64 v[6:7], v[6:7], 0, s[48:49]
	global_load_dwordx4 v[22:25], v[6:7], off nt
	v_lshl_add_u64 v[6:7], v[6:7], 0, s[48:49]
	global_load_dwordx4 v[18:21], v[6:7], off nt
	v_lshl_add_u64 v[6:7], v[6:7], 0, s[48:49]
	global_load_dwordx4 v[14:17], v[6:7], off nt
	v_lshl_add_u64 v[6:7], v[6:7], 0, s[48:49]
	global_load_dwordx4 v[10:13], v[6:7], off nt
	v_lshl_add_u64 v[6:7], v[6:7], 0, s[48:49]
	global_load_dwordx4 v[6:9], v[6:7], off nt
	ds_bpermute_b32 v228, v228, v234
	ds_bpermute_b32 v230, v230, v234
	ds_bpermute_b32 v232, v232, v234
	v_lshlrev_b32_e32 v233, 2, v231
	s_ashr_i32 s53, s52, 31
	s_waitcnt lgkmcnt(2)
; __device__ __forceinline__ void sb_decode_stream(Frame& F, unsigned* qctr, int base, int limit) {
;     ...
;         for (int i = 0; i < 16; ++i) { const float aj = __shfl(a, 32 + 2 * i + half); o4 += aj * B[i]; }
; #pragma unroll
;         for (int i = 0; i < 16; ++i) B[i] = __builtin_nontemporal_load((const f32x4*)(CK + cbn + (size_t)(32 + 2 * i) * stepn));
;         o4.x += __shfl_xor(o4.x, 32); o4.y += __shfl_xor(o4.y, 32); o4.z += __shfl_xor(o4.z, 32); o4.w += __shfl_xor(o4.w, 32);
;         float* P = SSP(S_PART) + ((size_t)bh * DSEG + blk) * DPART;
;         if (half == 0) *(f32x4*)(P + 4 * l32) = o4; if (lane == 0) P[128] = tot;
;         if (!more) break;
;         it = itn; cb = cbn; q4 = q4n;
	v_pk_fma_f32 v[138:139], v[138:139], v[228:229], v[226:227] op_sel_hi:[1,0,1]
	v_pk_fma_f32 v[140:141], v[140:141], v[228:229], v[224:225] op_sel_hi:[1,0,1]
	s_waitcnt lgkmcnt(1)
	v_pk_fma_f32 v[138:139], v[142:143], v[230:231], v[138:139] op_sel_hi:[1,0,1]
	v_or_b32_e32 v142, v231, v211
	v_lshlrev_b32_e32 v142, 2, v142
	ds_bpermute_b32 v142, v142, v234
	v_or_b32_e32 v143, v231, v212
	v_lshlrev_b32_e32 v143, 2, v143
	v_pk_fma_f32 v[140:141], v[144:145], v[230:231], v[140:141] op_sel_hi:[1,0,1]
	ds_bpermute_b32 v144, v143, v234
	v_or_b32_e32 v143, v231, v213
	s_waitcnt lgkmcnt(2)
	v_pk_fma_f32 v[138:139], v[146:147], v[232:233], v[138:139] op_sel_hi:[1,0,1]
	v_lshlrev_b32_e32 v143, 2, v143
	s_waitcnt lgkmcnt(1)
	v_pk_fma_f32 v[134:135], v[134:135], v[142:143], v[138:139] op_sel_hi:[1,0,1]
	v_or_b32_e32 v138, v231, v214
	ds_bpermute_b32 v146, v143, v234
	v_lshlrev_b32_e32 v138, 2, v138
	ds_bpermute_b32 v138, v138, v234
	v_pk_fma_f32 v[140:141], v[148:149], v[232:233], v[140:141] op_sel_hi:[1,0,1]
	v_or_b32_e32 v139, v231, v215
	v_pk_fma_f32 v[136:137], v[136:137], v[142:143], v[140:141] op_sel_hi:[1,0,1]
	v_lshlrev_b32_e32 v139, 2, v139
	s_waitcnt vmcnt(40) lgkmcnt(2)
	v_pk_fma_f32 v[134:135], v[154:155], v[144:145], v[134:135] op_sel_hi:[1,0,1]
	v_pk_fma_f32 v[136:137], v[156:157], v[144:145], v[136:137] op_sel_hi:[1,0,1]
	ds_bpermute_b32 v140, v139, v234
	v_or_b32_e32 v139, v231, v216
	s_waitcnt vmcnt(39) lgkmcnt(2)
	v_pk_fma_f32 v[136:137], v[152:153], v[146:147], v[136:137] op_sel_hi:[1,0,1]
	v_pk_fma_f32 v[134:135], v[150:151], v[146:147], v[134:135] op_sel_hi:[1,0,1]
	v_lshlrev_b32_e32 v139, 2, v139
	ds_bpermute_b32 v142, v139, v234
	s_waitcnt vmcnt(38) lgkmcnt(2)
	v_pk_fma_f32 v[134:135], v[162:163], v[138:139], v[134:135] op_sel_hi:[1,0,1]
	v_pk_fma_f32 v[136:137], v[164:165], v[138:139], v[136:137] op_sel_hi:[1,0,1]
	v_or_b32_e32 v138, v231, v218
	v_lshlrev_b32_e32 v138, 2, v138
	v_or_b32_e32 v139, v231, v219
	ds_bpermute_b32 v138, v138, v234
	v_lshlrev_b32_e32 v139, 2, v139
	s_waitcnt vmcnt(37) lgkmcnt(2)
	v_pk_fma_f32 v[136:137], v[160:161], v[140:141], v[136:137] op_sel_hi:[1,0,1]
	v_pk_fma_f32 v[134:135], v[158:159], v[140:141], v[134:135] op_sel_hi:[1,0,1]
	ds_bpermute_b32 v140, v139, v234
	v_or_b32_e32 v139, v231, v220
	v_lshlrev_b32_e32 v139, 2, v139
	s_waitcnt vmcnt(36) lgkmcnt(2)
	v_pk_fma_f32 v[134:135], v[170:171], v[142:143], v[134:135] op_sel_hi:[1,0,1]
	v_pk_fma_f32 v[136:137], v[172:173], v[142:143], v[136:137] op_sel_hi:[1,0,1]
	ds_bpermute_b32 v142, v139, v234
	s_waitcnt vmcnt(35) lgkmcnt(2)
	v_pk_fma_f32 v[136:137], v[168:169], v[138:139], v[136:137] op_sel_hi:[1,0,1]
	v_pk_fma_f32 v[134:135], v[166:167], v[138:139], v[134:135] op_sel_hi:[1,0,1]
	v_xor_b32_e32 v138, 32, v222
	v_add_u32_e32 v139, 64, v231
	v_cmp_lt_i32_e32 vcc, v138, v139
	s_waitcnt vmcnt(34) lgkmcnt(1)
	v_pk_fma_f32 v[134:135], v[178:179], v[140:141], v[134:135] op_sel_hi:[1,0,1]
	v_pk_fma_f32 v[136:137], v[180:181], v[140:141], v[136:137] op_sel_hi:[1,0,1]
	v_cndmask_b32_e32 v138, v222, v138, vcc
	s_waitcnt vmcnt(33) lgkmcnt(0)
	v_pk_fma_f32 v[136:137], v[176:177], v[142:143], v[136:137] op_sel_hi:[1,0,1]
	v_pk_fma_f32 v[134:135], v[174:175], v[142:143], v[134:135] op_sel_hi:[1,0,1]
	v_lshlrev_b32_e32 v141, 2, v138
	s_lshl_b64 s[52:53], s[52:53], 8
	ds_bpermute_b32 v142, v233, v229
	ds_bpermute_b32 v138, v141, v134
	ds_bpermute_b32 v139, v141, v135
	ds_bpermute_b32 v140, v141, v136
	ds_bpermute_b32 v141, v141, v137
	s_or_b32 s2, s52, s79
	s_mul_i32 s48, s53, 0x210
	s_mul_hi_u32 s52, s2, 0x210
	s_add_i32 s48, s52, s48
	s_mulk_i32 s2, 0x210
	s_add_u32 s52, s5, s2
	s_addc_u32 s53, s23, s48
	s_and_saveexec_b64 s[56:57], s[8:9]
	s_cbranch_execz .LBB0_1418
	s_waitcnt lgkmcnt(0)
	v_pk_add_f32 v[136:137], v[136:137], v[140:141]
	v_pk_add_f32 v[134:135], v[134:135], v[138:139]
	global_store_dwordx4 v221, v[134:137], s[52:53]
	s_or_b64 exec, exec, s[56:57]
	s_and_saveexec_b64 s[56:57], s[10:11]
	s_cbranch_execz .LBB0_1413
	s_branch .LBB0_1419

; __device__ __forceinline__ void sb_decode_stream(Frame& F, unsigned* qctr, int base, int limit) {
;     ...
;     for (;;) {
;         const int bh = ((it >> 11) << 3) | (it & 7), blk = (it >> 3) & 255, h = it & 7;
;         const unsigned vn = __hip_atomic_fetch_add(qctr, 1u, __ATOMIC_RELAXED, __HIP_MEMORY_SCOPE_AGENT);
;         const float k2 = kin(12)[h] * 1.4426950408889634f;
;         int zi = 0;
;     ...
;         DEC_SCORES(A, 0);
.LBB0_1454:
	s_mov_b64 s[52:53], exec
	v_mbcnt_lo_u32_b32 v134, s52, 0
	v_mbcnt_hi_u32_b32 v134, s53, v134
	v_cmp_eq_u32_e32 vcc, 0, v134
	s_and_saveexec_b64 s[50:51], vcc
	s_cbranch_execz .LBB0_1456
	s_bcnt1_i32_b64 s2, s[52:53]
	v_mov_b32_e32 v135, s2
	global_atomic_add v253, v1, v135, s[38:39] sc0
.LBB0_1456:
	s_or_b64 exec, exec, s[50:51]
	s_waitcnt vmcnt(31)
	v_mul_f32_e32 v131, v131, v3
	v_fmac_f32_e32 v131, v130, v2
	v_mul_f32_e32 v130, v133, v5
	v_fmac_f32_e32 v130, v132, v4
	v_add_f32_e32 v130, v131, v130
	s_waitcnt vmcnt(30)
	v_mul_f32_e32 v127, v127, v3
	v_fmac_f32_e32 v127, v126, v2
	v_add_f32_dpp v130, v130, v130 quad_perm:[1,0,3,2] row_mask:0xf bank_mask:0xf bound_ctrl:1
	v_mul_f32_e32 v126, v129, v5
	v_fmac_f32_e32 v126, v128, v4
	v_add_f32_dpp v130, v130, v130 quad_perm:[2,3,0,1] row_mask:0xf bank_mask:0xf bound_ctrl:1
	s_waitcnt vmcnt(29)
	v_mul_f32_e32 v123, v123, v3
	v_add_f32_e32 v126, v127, v126
	v_add_f32_dpp v130, v130, v130 row_half_mirror row_mask:0xf bank_mask:0xf bound_ctrl:1
	v_fmac_f32_e32 v123, v122, v2
	v_mul_f32_e32 v122, v125, v5
	s_movk_i32 s52, 0x60
	v_add_f32_dpp v131, v130, v130 row_mirror row_mask:0xf bank_mask:0xf bound_ctrl:1
	v_add_f32_dpp v126, v126, v126 quad_perm:[1,0,3,2] row_mask:0xf bank_mask:0xf bound_ctrl:1
	v_fmac_f32_e32 v122, v124, v4
	s_waitcnt vmcnt(28)
	v_mul_f32_e32 v119, v119, v3
	ds_swizzle_b32 v132, v131 offset:swizzle(SWAP,16)
	v_add_f32_dpp v126, v126, v126 quad_perm:[2,3,0,1] row_mask:0xf bank_mask:0xf bound_ctrl:1
	v_add_f32_e32 v122, v123, v122
	v_fmac_f32_e32 v119, v118, v2
	v_mul_f32_e32 v118, v121, v5
	s_load_dwordx2 s[52:53], s[0:1], s52 offset:0x0
	v_add_f32_dpp v126, v126, v126 row_half_mirror row_mask:0xf bank_mask:0xf bound_ctrl:1
	v_add_f32_dpp v122, v122, v122 quad_perm:[1,0,3,2] row_mask:0xf bank_mask:0xf bound_ctrl:1
	v_fmac_f32_e32 v118, v120, v4
	s_waitcnt vmcnt(27)
	v_mul_f32_e32 v115, v115, v3
	v_add_f32_dpp v126, v126, v126 row_mirror row_mask:0xf bank_mask:0xf bound_ctrl:1
	v_add_f32_dpp v122, v122, v122 quad_perm:[2,3,0,1] row_mask:0xf bank_mask:0xf bound_ctrl:1
	v_add_f32_e32 v118, v119, v118
	v_fmac_f32_e32 v115, v114, v2
	v_mul_f32_e32 v114, v117, v5
	s_and_b32 s50, s46, 7
	s_waitcnt vmcnt(1)
	ds_swizzle_b32 v127, v126 offset:swizzle(SWAP,16)
	v_add_f32_dpp v122, v122, v122 row_half_mirror row_mask:0xf bank_mask:0xf bound_ctrl:1
	v_add_f32_dpp v118, v118, v118 quad_perm:[1,0,3,2] row_mask:0xf bank_mask:0xf bound_ctrl:1
	v_fmac_f32_e32 v114, v116, v4
	v_mul_f32_e32 v111, v111, v3
	s_lshl_b32 s2, s50, 2
	v_add_f32_dpp v122, v122, v122 row_mirror row_mask:0xf bank_mask:0xf bound_ctrl:1
	v_add_f32_dpp v118, v118, v118 quad_perm:[2,3,0,1] row_mask:0xf bank_mask:0xf bound_ctrl:1
	v_add_f32_e32 v114, v115, v114
	v_fmac_f32_e32 v111, v110, v2
	v_mul_f32_e32 v110, v113, v5
	v_mov_b32_e32 v130, s2
	s_waitcnt lgkmcnt(0)
	v_add_f32_e32 v131, v131, v132
	ds_swizzle_b32 v123, v122 offset:swizzle(SWAP,16)
	v_add_f32_dpp v118, v118, v118 row_half_mirror row_mask:0xf bank_mask:0xf bound_ctrl:1
	v_add_f32_dpp v114, v114, v114 quad_perm:[1,0,3,2] row_mask:0xf bank_mask:0xf bound_ctrl:1
	v_fmac_f32_e32 v110, v112, v4
	v_mul_f32_e32 v107, v107, v3
	global_load_dword v130, v130, s[52:53]
	v_readlane_b32 s2, v131, 0
	v_readlane_b32 s52, v131, 32
	v_mov_b32_e32 v131, 0
	v_add_f32_dpp v118, v118, v118 row_mirror row_mask:0xf bank_mask:0xf bound_ctrl:1
	v_add_f32_dpp v114, v114, v114 quad_perm:[2,3,0,1] row_mask:0xf bank_mask:0xf bound_ctrl:1
	v_add_f32_e32 v110, v111, v110
	v_fmac_f32_e32 v107, v106, v2
	v_mul_f32_e32 v106, v109, v5
	s_nop 3
	v_writelane_b32 v131, s2, 0
	ds_swizzle_b32 v119, v118 offset:swizzle(SWAP,16)
	v_add_f32_dpp v114, v114, v114 row_half_mirror row_mask:0xf bank_mask:0xf bound_ctrl:1
	v_add_f32_dpp v110, v110, v110 quad_perm:[1,0,3,2] row_mask:0xf bank_mask:0xf bound_ctrl:1
	v_fmac_f32_e32 v106, v108, v4
	v_mul_f32_e32 v103, v103, v3
	v_writelane_b32 v131, s52, 1
	v_add_f32_e32 v126, v126, v127
	v_add_f32_dpp v114, v114, v114 row_mirror row_mask:0xf bank_mask:0xf bound_ctrl:1
	v_add_f32_dpp v110, v110, v110 quad_perm:[2,3,0,1] row_mask:0xf bank_mask:0xf bound_ctrl:1
	v_add_f32_e32 v106, v107, v106
	v_fmac_f32_e32 v103, v102, v2
	v_mul_f32_e32 v102, v105, v5
	v_readlane_b32 s2, v126, 0
	s_nop 3
	v_writelane_b32 v131, s2, 2
	ds_swizzle_b32 v115, v114 offset:swizzle(SWAP,16)
	v_add_f32_dpp v110, v110, v110 row_half_mirror row_mask:0xf bank_mask:0xf bound_ctrl:1
	v_add_f32_dpp v106, v106, v106 quad_perm:[1,0,3,2] row_mask:0xf bank_mask:0xf bound_ctrl:1
	v_fmac_f32_e32 v102, v104, v4
	v_mul_f32_e32 v99, v99, v3
	v_readlane_b32 s52, v126, 32
	v_writelane_b32 v131, s52, 3
	s_waitcnt lgkmcnt(2)
	v_add_f32_e32 v122, v122, v123
	v_add_f32_dpp v110, v110, v110 row_mirror row_mask:0xf bank_mask:0xf bound_ctrl:1
	v_add_f32_dpp v106, v106, v106 quad_perm:[2,3,0,1] row_mask:0xf bank_mask:0xf bound_ctrl:1
	v_add_f32_e32 v102, v103, v102
	v_fmac_f32_e32 v99, v98, v2
	v_mul_f32_e32 v98, v101, v5
	v_readlane_b32 s2, v122, 0
	s_nop 3
	v_writelane_b32 v131, s2, 4
	ds_swizzle_b32 v111, v110 offset:swizzle(SWAP,16)
	v_add_f32_dpp v106, v106, v106 row_half_mirror row_mask:0xf bank_mask:0xf bound_ctrl:1
	v_add_f32_dpp v102, v102, v102 quad_perm:[1,0,3,2] row_mask:0xf bank_mask:0xf bound_ctrl:1
	v_fmac_f32_e32 v98, v100, v4
	v_mul_f32_e32 v95, v95, v3
	v_readlane_b32 s52, v122, 32
	v_writelane_b32 v131, s52, 5
	s_waitcnt lgkmcnt(2)
; __device__ __forceinline__ void sb_decode_stream(Frame& F, unsigned* qctr, int base, int limit) {
;     ...
;         DEC_SCORES(A, 0);
	v_add_f32_e32 v118, v118, v119
	v_add_f32_dpp v106, v106, v106 row_mirror row_mask:0xf bank_mask:0xf bound_ctrl:1
	v_add_f32_dpp v102, v102, v102 quad_perm:[2,3,0,1] row_mask:0xf bank_mask:0xf bound_ctrl:1
	v_add_f32_e32 v98, v99, v98
	v_fmac_f32_e32 v95, v94, v2
	v_mul_f32_e32 v94, v97, v5
	v_readlane_b32 s2, v118, 0
	s_nop 3
	v_writelane_b32 v131, s2, 6
	ds_swizzle_b32 v107, v106 offset:swizzle(SWAP,16)
	v_add_f32_dpp v102, v102, v102 row_half_mirror row_mask:0xf bank_mask:0xf bound_ctrl:1
	v_add_f32_dpp v98, v98, v98 quad_perm:[1,0,3,2] row_mask:0xf bank_mask:0xf bound_ctrl:1
	v_fmac_f32_e32 v94, v96, v4
	v_mul_f32_e32 v91, v91, v3
	v_readlane_b32 s52, v118, 32
	v_writelane_b32 v131, s52, 7
	s_waitcnt lgkmcnt(2)
	v_add_f32_e32 v114, v114, v115
	v_add_f32_dpp v102, v102, v102 row_mirror row_mask:0xf bank_mask:0xf bound_ctrl:1
	v_add_f32_dpp v98, v98, v98 quad_perm:[2,3,0,1] row_mask:0xf bank_mask:0xf bound_ctrl:1
	v_add_f32_e32 v94, v95, v94
	v_fmac_f32_e32 v91, v90, v2
	v_mul_f32_e32 v90, v93, v5
	v_readlane_b32 s2, v114, 0
	s_nop 3
	v_writelane_b32 v131, s2, 8
	ds_swizzle_b32 v103, v102 offset:swizzle(SWAP,16)
	v_add_f32_dpp v98, v98, v98 row_half_mirror row_mask:0xf bank_mask:0xf bound_ctrl:1
	v_add_f32_dpp v94, v94, v94 quad_perm:[1,0,3,2] row_mask:0xf bank_mask:0xf bound_ctrl:1
	v_fmac_f32_e32 v90, v92, v4
	v_mul_f32_e32 v87, v87, v3
	v_readlane_b32 s52, v114, 32
	v_writelane_b32 v131, s52, 9
	s_waitcnt lgkmcnt(2)
	v_add_f32_e32 v110, v110, v111
	v_add_f32_dpp v98, v98, v98 row_mirror row_mask:0xf bank_mask:0xf bound_ctrl:1
	v_add_f32_dpp v94, v94, v94 quad_perm:[2,3,0,1] row_mask:0xf bank_mask:0xf bound_ctrl:1
	v_add_f32_e32 v90, v91, v90
	v_fmac_f32_e32 v87, v86, v2
	v_mul_f32_e32 v86, v89, v5
	v_readlane_b32 s2, v110, 0
	s_nop 3
	v_writelane_b32 v131, s2, 10
	ds_swizzle_b32 v99, v98 offset:swizzle(SWAP,16)
	v_add_f32_dpp v94, v94, v94 row_half_mirror row_mask:0xf bank_mask:0xf bound_ctrl:1
	v_add_f32_dpp v90, v90, v90 quad_perm:[1,0,3,2] row_mask:0xf bank_mask:0xf bound_ctrl:1
	v_fmac_f32_e32 v86, v88, v4
	v_mul_f32_e32 v83, v83, v3
	v_readlane_b32 s52, v110, 32
	v_writelane_b32 v131, s52, 11
	s_waitcnt lgkmcnt(2)
	v_add_f32_e32 v106, v106, v107
	v_add_f32_dpp v94, v94, v94 row_mirror row_mask:0xf bank_mask:0xf bound_ctrl:1
	v_add_f32_dpp v90, v90, v90 quad_perm:[2,3,0,1] row_mask:0xf bank_mask:0xf bound_ctrl:1
	v_add_f32_e32 v86, v87, v86
	v_fmac_f32_e32 v83, v82, v2
	v_mul_f32_e32 v82, v85, v5
	v_readlane_b32 s2, v106, 0
	s_nop 3
	v_writelane_b32 v131, s2, 12
	ds_swizzle_b32 v95, v94 offset:swizzle(SWAP,16)
	v_add_f32_dpp v90, v90, v90 row_half_mirror row_mask:0xf bank_mask:0xf bound_ctrl:1
	v_add_f32_dpp v86, v86, v86 quad_perm:[1,0,3,2] row_mask:0xf bank_mask:0xf bound_ctrl:1
	v_fmac_f32_e32 v82, v84, v4
	v_mul_f32_e32 v75, v75, v3
	v_readlane_b32 s52, v106, 32
	v_writelane_b32 v131, s52, 13
	s_waitcnt lgkmcnt(2)
	v_add_f32_e32 v102, v102, v103
	v_add_f32_dpp v90, v90, v90 row_mirror row_mask:0xf bank_mask:0xf bound_ctrl:1
	v_add_f32_dpp v86, v86, v86 quad_perm:[2,3,0,1] row_mask:0xf bank_mask:0xf bound_ctrl:1
	v_add_f32_e32 v82, v83, v82
	v_fmac_f32_e32 v75, v74, v2
	v_mul_f32_e32 v74, v77, v5
	v_readlane_b32 s2, v102, 0
	s_nop 3
	v_writelane_b32 v131, s2, 14
	ds_swizzle_b32 v91, v90 offset:swizzle(SWAP,16)
	v_add_f32_dpp v86, v86, v86 row_half_mirror row_mask:0xf bank_mask:0xf bound_ctrl:1
	v_add_f32_dpp v82, v82, v82 quad_perm:[1,0,3,2] row_mask:0xf bank_mask:0xf bound_ctrl:1
	v_fmac_f32_e32 v74, v76, v4
	v_mul_f32_e32 v71, v71, v3
	v_readlane_b32 s52, v102, 32
	v_writelane_b32 v131, s52, 15
	s_waitcnt lgkmcnt(2)
	v_add_f32_e32 v98, v98, v99
	v_add_f32_dpp v86, v86, v86 row_mirror row_mask:0xf bank_mask:0xf bound_ctrl:1
	v_add_f32_dpp v82, v82, v82 quad_perm:[2,3,0,1] row_mask:0xf bank_mask:0xf bound_ctrl:1
	v_add_f32_e32 v74, v75, v74
	v_fmac_f32_e32 v71, v70, v2
	v_mul_f32_e32 v70, v73, v5
	v_mul_f32_e32 v63, v63, v3
	v_readlane_b32 s2, v98, 0
	s_nop 3
	v_writelane_b32 v131, s2, 16
	ds_swizzle_b32 v87, v86 offset:swizzle(SWAP,16)
	v_add_f32_dpp v82, v82, v82 row_half_mirror row_mask:0xf bank_mask:0xf bound_ctrl:1
	v_add_f32_dpp v74, v74, v74 quad_perm:[1,0,3,2] row_mask:0xf bank_mask:0xf bound_ctrl:1
	v_fmac_f32_e32 v70, v72, v4
	v_fmac_f32_e32 v63, v62, v2
	v_mul_f32_e32 v62, v65, v5
	v_readlane_b32 s52, v98, 32
	v_writelane_b32 v131, s52, 17
	s_waitcnt lgkmcnt(2)
	v_add_f32_e32 v94, v94, v95
	v_add_f32_dpp v82, v82, v82 row_mirror row_mask:0xf bank_mask:0xf bound_ctrl:1
	v_add_f32_dpp v74, v74, v74 quad_perm:[2,3,0,1] row_mask:0xf bank_mask:0xf bound_ctrl:1
	v_add_f32_e32 v70, v71, v70
	v_fmac_f32_e32 v62, v64, v4
	v_readlane_b32 s2, v94, 0
	s_nop 3
	v_writelane_b32 v131, s2, 18
	ds_swizzle_b32 v83, v82 offset:swizzle(SWAP,16)
	v_add_f32_dpp v74, v74, v74 row_half_mirror row_mask:0xf bank_mask:0xf bound_ctrl:1
	v_add_f32_dpp v70, v70, v70 quad_perm:[1,0,3,2] row_mask:0xf bank_mask:0xf bound_ctrl:1
	v_add_f32_e32 v62, v63, v62
	v_readlane_b32 s52, v94, 32
	v_writelane_b32 v131, s52, 19
	s_waitcnt lgkmcnt(2)
	v_add_f32_e32 v90, v90, v91
	v_add_f32_dpp v74, v74, v74 row_mirror row_mask:0xf bank_mask:0xf bound_ctrl:1
	v_add_f32_dpp v70, v70, v70 quad_perm:[2,3,0,1] row_mask:0xf bank_mask:0xf bound_ctrl:1
	v_add_f32_dpp v62, v62, v62 quad_perm:[1,0,3,2] row_mask:0xf bank_mask:0xf bound_ctrl:1
	v_readlane_b32 s2, v90, 0
	s_nop 3
	v_writelane_b32 v131, s2, 20
	ds_swizzle_b32 v75, v74 offset:swizzle(SWAP,16)
	v_add_f32_dpp v70, v70, v70 row_half_mirror row_mask:0xf bank_mask:0xf bound_ctrl:1
	v_add_f32_dpp v62, v62, v62 quad_perm:[2,3,0,1] row_mask:0xf bank_mask:0xf bound_ctrl:1
	v_readlane_b32 s52, v90, 32
	v_writelane_b32 v131, s52, 21
	s_waitcnt lgkmcnt(2)
; __device__ __forceinline__ void sb_decode_stream(Frame& F, unsigned* qctr, int base, int limit) {
;     ...
;         DEC_SCORES(A, 0);
; #pragma unroll
;         for (int i = 0; i < 16; ++i) A[i] = __builtin_nontemporal_load((const f32x4*)(CV + cb + (size_t)(2 * i) * (NH * HD)));
;         DEC_SCORES(B, 1);
	v_add_f32_e32 v86, v86, v87
	v_add_f32_dpp v70, v70, v70 row_mirror row_mask:0xf bank_mask:0xf bound_ctrl:1
	v_add_f32_dpp v62, v62, v62 row_half_mirror row_mask:0xf bank_mask:0xf bound_ctrl:1
	v_readlane_b32 s2, v86, 0
	s_nop 3
	v_writelane_b32 v131, s2, 22
	ds_swizzle_b32 v71, v70 offset:swizzle(SWAP,16)
	v_add_f32_dpp v62, v62, v62 row_mirror row_mask:0xf bank_mask:0xf bound_ctrl:1
	v_readlane_b32 s52, v86, 32
	v_writelane_b32 v131, s52, 23
	s_waitcnt lgkmcnt(2)
	v_add_f32_e32 v82, v82, v83
	ds_swizzle_b32 v63, v62 offset:swizzle(SWAP,16)
	v_readlane_b32 s2, v82, 0
	s_nop 3
	v_writelane_b32 v131, s2, 24
	v_readlane_b32 s52, v82, 32
	v_writelane_b32 v131, s52, 25
	s_waitcnt lgkmcnt(2)
	v_add_f32_e32 v74, v74, v75
	s_waitcnt lgkmcnt(1)
	v_add_f32_e32 v70, v70, v71
	v_readlane_b32 s2, v74, 0
	s_nop 3
	v_writelane_b32 v131, s2, 26
	v_readlane_b32 s52, v74, 32
	v_writelane_b32 v131, s52, 27
	v_readlane_b32 s2, v70, 0
	v_readlane_b32 s52, v70, 32
	s_nop 3
	v_writelane_b32 v131, s2, 28
	s_waitcnt lgkmcnt(0)
	v_add_f32_e32 v62, v62, v63
	v_lshl_add_u64 v[132:133], v[186:187], 2, s[42:43]
	v_writelane_b32 v131, s52, 29
	v_readlane_b32 s2, v62, 0
	v_readlane_b32 s52, v62, 32
	v_add_co_u32_e32 v62, vcc, s22, v132
	s_nop 3
	v_writelane_b32 v131, s2, 30
	v_mul_f32_e32 v79, v79, v3
	s_nop 0
	v_addc_co_u32_e32 v63, vcc, 0, v133, vcc
	v_writelane_b32 v131, s52, 31
	global_load_dwordx4 v[126:129], v[132:133], off nt
	global_load_dwordx4 v[114:117], v[62:63], off nt
	v_add_co_u32_e32 v62, vcc, s28, v132
	v_fmac_f32_e32 v79, v78, v2
	s_nop 0
	v_addc_co_u32_e32 v63, vcc, 0, v133, vcc
	v_add_co_u32_e32 v64, vcc, s29, v132
	v_mul_f32_e32 v78, v81, v5
	s_nop 0
	v_addc_co_u32_e32 v65, vcc, 0, v133, vcc
	global_load_dwordx4 v[122:125], v[62:63], off nt
	global_load_dwordx4 v[118:121], v[64:65], off nt
	v_add_co_u32_e32 v62, vcc, s30, v132
	v_fmac_f32_e32 v78, v80, v4
	s_nop 0
	v_addc_co_u32_e32 v63, vcc, 0, v133, vcc
	v_add_co_u32_e32 v64, vcc, s31, v132
	v_mul_f32_e32 v67, v67, v3
	s_nop 0
	v_addc_co_u32_e32 v65, vcc, 0, v133, vcc
	global_load_dwordx4 v[102:105], v[62:63], off nt
	global_load_dwordx4 v[106:109], v[64:65], off nt
	v_add_co_u32_e32 v62, vcc, s33, v132
	v_add_f32_e32 v78, v79, v78
	s_nop 0
	v_addc_co_u32_e32 v63, vcc, 0, v133, vcc
	v_add_co_u32_e32 v64, vcc, s35, v132
	v_fmac_f32_e32 v67, v66, v2
	s_nop 0
	v_addc_co_u32_e32 v65, vcc, 0, v133, vcc
	global_load_dwordx4 v[110:113], v[62:63], off nt
	global_load_dwordx4 v[86:89], v[64:65], off nt
	v_add_co_u32_e32 v62, vcc, s36, v132
	v_mul_f32_e32 v66, v69, v5
	s_nop 0
	v_addc_co_u32_e32 v63, vcc, 0, v133, vcc
	v_add_co_u32_e32 v64, vcc, s37, v132
	v_add_f32_dpp v78, v78, v78 quad_perm:[1,0,3,2] row_mask:0xf bank_mask:0xf bound_ctrl:1
	s_nop 0
	v_addc_co_u32_e32 v65, vcc, 0, v133, vcc
	global_load_dwordx4 v[98:101], v[62:63], off nt
	global_load_dwordx4 v[94:97], v[64:65], off nt
	v_add_co_u32_e32 v62, vcc, s56, v132
	v_fmac_f32_e32 v66, v68, v4
	s_nop 0
	v_addc_co_u32_e32 v63, vcc, 0, v133, vcc
	v_add_co_u32_e32 v64, vcc, s57, v132
	v_mul_f32_e32 v59, v59, v3
	s_nop 0
	v_addc_co_u32_e32 v65, vcc, 0, v133, vcc
	v_add_f32_dpp v78, v78, v78 quad_perm:[2,3,0,1] row_mask:0xf bank_mask:0xf bound_ctrl:1
	v_add_f32_e32 v66, v67, v66
	v_fmac_f32_e32 v59, v58, v2
	v_mul_f32_e32 v58, v61, v5
	global_load_dwordx4 v[70:73], v[62:63], off nt
	global_load_dwordx4 v[74:77], v[64:65], off nt
	v_add_co_u32_e32 v62, vcc, s58, v132
	v_add_f32_dpp v78, v78, v78 row_half_mirror row_mask:0xf bank_mask:0xf bound_ctrl:1
	v_add_f32_dpp v66, v66, v66 quad_perm:[1,0,3,2] row_mask:0xf bank_mask:0xf bound_ctrl:1
	v_fmac_f32_e32 v58, v60, v4
	v_mul_f32_e32 v55, v55, v3
	v_addc_co_u32_e32 v63, vcc, 0, v133, vcc
	v_add_f32_dpp v134, v78, v78 row_mirror row_mask:0xf bank_mask:0xf bound_ctrl:1
	v_add_f32_dpp v66, v66, v66 quad_perm:[2,3,0,1] row_mask:0xf bank_mask:0xf bound_ctrl:1
	v_add_f32_e32 v58, v59, v58
	v_fmac_f32_e32 v55, v54, v2
	v_mul_f32_e32 v54, v57, v5
	v_add_co_u32_e32 v64, vcc, s59, v132
	ds_swizzle_b32 v135, v134 offset:swizzle(SWAP,16)
	v_add_f32_dpp v66, v66, v66 row_half_mirror row_mask:0xf bank_mask:0xf bound_ctrl:1
	v_add_f32_dpp v58, v58, v58 quad_perm:[1,0,3,2] row_mask:0xf bank_mask:0xf bound_ctrl:1
	v_fmac_f32_e32 v54, v56, v4
	v_mul_f32_e32 v51, v51, v3
	v_addc_co_u32_e32 v65, vcc, 0, v133, vcc
	v_add_f32_dpp v66, v66, v66 row_mirror row_mask:0xf bank_mask:0xf bound_ctrl:1
	v_add_f32_dpp v58, v58, v58 quad_perm:[2,3,0,1] row_mask:0xf bank_mask:0xf bound_ctrl:1
	v_add_f32_e32 v54, v55, v54
	v_fmac_f32_e32 v51, v50, v2
	v_mul_f32_e32 v50, v53, v5
	v_add_co_u32_e32 v90, vcc, s60, v132
	ds_swizzle_b32 v67, v66 offset:swizzle(SWAP,16)
	v_add_f32_dpp v58, v58, v58 row_half_mirror row_mask:0xf bank_mask:0xf bound_ctrl:1
	v_add_f32_dpp v54, v54, v54 quad_perm:[1,0,3,2] row_mask:0xf bank_mask:0xf bound_ctrl:1
	v_fmac_f32_e32 v50, v52, v4
	v_mul_f32_e32 v47, v47, v3
	v_addc_co_u32_e32 v91, vcc, 0, v133, vcc
	v_add_f32_dpp v58, v58, v58 row_mirror row_mask:0xf bank_mask:0xf bound_ctrl:1
	v_add_f32_dpp v54, v54, v54 quad_perm:[2,3,0,1] row_mask:0xf bank_mask:0xf bound_ctrl:1
	v_add_f32_e32 v50, v51, v50
	v_fmac_f32_e32 v47, v46, v2
	v_mul_f32_e32 v46, v49, v5
	s_ashr_i32 s51, s46, 8
	v_add_co_u32_e32 v78, vcc, s61, v132
	ds_swizzle_b32 v59, v58 offset:swizzle(SWAP,16)
	v_add_f32_dpp v54, v54, v54 row_half_mirror row_mask:0xf bank_mask:0xf bound_ctrl:1
	v_add_f32_dpp v50, v50, v50 quad_perm:[1,0,3,2] row_mask:0xf bank_mask:0xf bound_ctrl:1
	v_fmac_f32_e32 v46, v48, v4
	v_mul_f32_e32 v43, v43, v3
	s_and_b32 s2, s51, -8
	v_addc_co_u32_e32 v79, vcc, 0, v133, vcc
	s_waitcnt lgkmcnt(2)
; __device__ __forceinline__ void sb_decode_stream(Frame& F, unsigned* qctr, int base, int limit) {
;     ...
;         DEC_SCORES(A, 0);
; #pragma unroll
;         for (int i = 0; i < 16; ++i) A[i] = __builtin_nontemporal_load((const f32x4*)(CV + cb + (size_t)(2 * i) * (NH * HD)));
;         DEC_SCORES(B, 1);
	v_add_f32_e32 v134, v134, v135
	v_add_f32_dpp v54, v54, v54 row_mirror row_mask:0xf bank_mask:0xf bound_ctrl:1
	v_add_f32_dpp v50, v50, v50 quad_perm:[2,3,0,1] row_mask:0xf bank_mask:0xf bound_ctrl:1
	v_add_f32_e32 v46, v47, v46
	v_fmac_f32_e32 v43, v42, v2
	v_mul_f32_e32 v42, v45, v5
	global_load_dwordx4 v[82:85], v[62:63], off nt
	s_nop 0
	global_load_dwordx4 v[62:65], v[64:65], off nt
	s_nop 0
	global_load_dwordx4 v[90:93], v[90:91], off nt
	s_nop 0
	global_load_dwordx4 v[78:81], v[78:79], off nt
	s_or_b32 s50, s2, s50
	v_readlane_b32 s2, v134, 0
	s_nop 3
	v_writelane_b32 v131, s2, 32
	ds_swizzle_b32 v55, v54 offset:swizzle(SWAP,16)
	v_add_f32_dpp v50, v50, v50 row_half_mirror row_mask:0xf bank_mask:0xf bound_ctrl:1
	v_add_f32_dpp v46, v46, v46 quad_perm:[1,0,3,2] row_mask:0xf bank_mask:0xf bound_ctrl:1
	v_fmac_f32_e32 v42, v44, v4
	v_mul_f32_e32 v39, v39, v3
	v_readlane_b32 s51, v134, 32
	v_writelane_b32 v131, s51, 33
	s_waitcnt lgkmcnt(2)
	v_add_f32_e32 v66, v66, v67
	v_add_f32_dpp v50, v50, v50 row_mirror row_mask:0xf bank_mask:0xf bound_ctrl:1
	v_add_f32_dpp v46, v46, v46 quad_perm:[2,3,0,1] row_mask:0xf bank_mask:0xf bound_ctrl:1
	v_add_f32_e32 v42, v43, v42
	v_fmac_f32_e32 v39, v38, v2
	v_mul_f32_e32 v38, v41, v5
	v_readlane_b32 s2, v66, 0
	s_nop 3
	v_writelane_b32 v131, s2, 34
	ds_swizzle_b32 v51, v50 offset:swizzle(SWAP,16)
	v_add_f32_dpp v46, v46, v46 row_half_mirror row_mask:0xf bank_mask:0xf bound_ctrl:1
	v_add_f32_dpp v42, v42, v42 quad_perm:[1,0,3,2] row_mask:0xf bank_mask:0xf bound_ctrl:1
	v_fmac_f32_e32 v38, v40, v4
	v_mul_f32_e32 v35, v35, v3
	v_readlane_b32 s51, v66, 32
	v_writelane_b32 v131, s51, 35
	s_waitcnt lgkmcnt(2)
	v_add_f32_e32 v58, v58, v59
	v_add_f32_dpp v46, v46, v46 row_mirror row_mask:0xf bank_mask:0xf bound_ctrl:1
	v_add_f32_dpp v42, v42, v42 quad_perm:[2,3,0,1] row_mask:0xf bank_mask:0xf bound_ctrl:1
	v_add_f32_e32 v38, v39, v38
	v_fmac_f32_e32 v35, v34, v2
	v_mul_f32_e32 v34, v37, v5
	v_readlane_b32 s2, v58, 0
	s_nop 3
	v_writelane_b32 v131, s2, 36
	ds_swizzle_b32 v47, v46 offset:swizzle(SWAP,16)
	v_add_f32_dpp v42, v42, v42 row_half_mirror row_mask:0xf bank_mask:0xf bound_ctrl:1
	v_add_f32_dpp v38, v38, v38 quad_perm:[1,0,3,2] row_mask:0xf bank_mask:0xf bound_ctrl:1
	v_fmac_f32_e32 v34, v36, v4
	v_mul_f32_e32 v31, v31, v3
	v_readlane_b32 s51, v58, 32
	v_writelane_b32 v131, s51, 37
	s_waitcnt lgkmcnt(2)
	v_add_f32_e32 v54, v54, v55
	v_add_f32_dpp v42, v42, v42 row_mirror row_mask:0xf bank_mask:0xf bound_ctrl:1
	v_add_f32_dpp v38, v38, v38 quad_perm:[2,3,0,1] row_mask:0xf bank_mask:0xf bound_ctrl:1
	v_add_f32_e32 v34, v35, v34
	v_fmac_f32_e32 v31, v30, v2
	v_mul_f32_e32 v30, v33, v5
	v_readlane_b32 s2, v54, 0
	s_nop 3
	v_writelane_b32 v131, s2, 38
	ds_swizzle_b32 v43, v42 offset:swizzle(SWAP,16)
	v_add_f32_dpp v38, v38, v38 row_half_mirror row_mask:0xf bank_mask:0xf bound_ctrl:1
	v_add_f32_dpp v34, v34, v34 quad_perm:[1,0,3,2] row_mask:0xf bank_mask:0xf bound_ctrl:1
	v_fmac_f32_e32 v30, v32, v4
	v_mul_f32_e32 v27, v27, v3
	v_readlane_b32 s51, v54, 32
	v_writelane_b32 v131, s51, 39
	s_waitcnt lgkmcnt(2)
	v_add_f32_e32 v50, v50, v51
	v_add_f32_dpp v38, v38, v38 row_mirror row_mask:0xf bank_mask:0xf bound_ctrl:1
	v_add_f32_dpp v34, v34, v34 quad_perm:[2,3,0,1] row_mask:0xf bank_mask:0xf bound_ctrl:1
	v_add_f32_e32 v30, v31, v30
	v_fmac_f32_e32 v27, v26, v2
	v_mul_f32_e32 v26, v29, v5
	v_readlane_b32 s2, v50, 0
	s_nop 3
	v_writelane_b32 v131, s2, 40
	ds_swizzle_b32 v39, v38 offset:swizzle(SWAP,16)
	v_add_f32_dpp v34, v34, v34 row_half_mirror row_mask:0xf bank_mask:0xf bound_ctrl:1
	v_add_f32_dpp v30, v30, v30 quad_perm:[1,0,3,2] row_mask:0xf bank_mask:0xf bound_ctrl:1
	v_fmac_f32_e32 v26, v28, v4
	v_mul_f32_e32 v23, v23, v3
	v_readlane_b32 s51, v50, 32
	v_writelane_b32 v131, s51, 41
	s_waitcnt lgkmcnt(2)
	v_add_f32_e32 v46, v46, v47
	v_add_f32_dpp v34, v34, v34 row_mirror row_mask:0xf bank_mask:0xf bound_ctrl:1
	v_add_f32_dpp v30, v30, v30 quad_perm:[2,3,0,1] row_mask:0xf bank_mask:0xf bound_ctrl:1
	v_add_f32_e32 v26, v27, v26
	v_fmac_f32_e32 v23, v22, v2
	v_mul_f32_e32 v22, v25, v5
	v_readlane_b32 s2, v46, 0
	s_nop 3
	v_writelane_b32 v131, s2, 42
	ds_swizzle_b32 v35, v34 offset:swizzle(SWAP,16)
	v_add_f32_dpp v30, v30, v30 row_half_mirror row_mask:0xf bank_mask:0xf bound_ctrl:1
	v_add_f32_dpp v26, v26, v26 quad_perm:[1,0,3,2] row_mask:0xf bank_mask:0xf bound_ctrl:1
	v_fmac_f32_e32 v22, v24, v4
	v_mul_f32_e32 v19, v19, v3
	v_readlane_b32 s51, v46, 32
	v_writelane_b32 v131, s51, 43
	s_waitcnt lgkmcnt(2)
	v_add_f32_e32 v42, v42, v43
	v_add_f32_dpp v30, v30, v30 row_mirror row_mask:0xf bank_mask:0xf bound_ctrl:1
	v_add_f32_dpp v26, v26, v26 quad_perm:[2,3,0,1] row_mask:0xf bank_mask:0xf bound_ctrl:1
	v_add_f32_e32 v22, v23, v22
	v_fmac_f32_e32 v19, v18, v2
	v_mul_f32_e32 v18, v21, v5
	v_readlane_b32 s2, v42, 0
	s_nop 3
	v_writelane_b32 v131, s2, 44
	ds_swizzle_b32 v31, v30 offset:swizzle(SWAP,16)
	v_add_f32_dpp v26, v26, v26 row_half_mirror row_mask:0xf bank_mask:0xf bound_ctrl:1
	v_add_f32_dpp v22, v22, v22 quad_perm:[1,0,3,2] row_mask:0xf bank_mask:0xf bound_ctrl:1
	v_fmac_f32_e32 v18, v20, v4
	v_mul_f32_e32 v15, v15, v3
	v_readlane_b32 s51, v42, 32
	v_writelane_b32 v131, s51, 45
	s_waitcnt lgkmcnt(2)
	v_add_f32_e32 v38, v38, v39
	v_add_f32_dpp v26, v26, v26 row_mirror row_mask:0xf bank_mask:0xf bound_ctrl:1
	v_add_f32_dpp v22, v22, v22 quad_perm:[2,3,0,1] row_mask:0xf bank_mask:0xf bound_ctrl:1
	v_add_f32_e32 v18, v19, v18
	v_fmac_f32_e32 v15, v14, v2
	v_mul_f32_e32 v14, v17, v5
	v_mul_f32_e32 v11, v11, v3
	v_readlane_b32 s2, v38, 0
	s_nop 3
	v_writelane_b32 v131, s2, 46
	ds_swizzle_b32 v27, v26 offset:swizzle(SWAP,16)
	v_add_f32_dpp v22, v22, v22 row_half_mirror row_mask:0xf bank_mask:0xf bound_ctrl:1
	v_add_f32_dpp v18, v18, v18 quad_perm:[1,0,3,2] row_mask:0xf bank_mask:0xf bound_ctrl:1
	v_fmac_f32_e32 v14, v16, v4
	v_fmac_f32_e32 v11, v10, v2
	v_mul_f32_e32 v10, v13, v5
	v_readlane_b32 s51, v38, 32
	v_writelane_b32 v131, s51, 47
	s_waitcnt lgkmcnt(2)
; __device__ __forceinline__ void sb_decode_stream(Frame& F, unsigned* qctr, int base, int limit) {
;     ...
;         DEC_SCORES(B, 1);
;     ...
; #pragma unroll
;         for (int i = 0; i < 16; ++i) B[i] = __builtin_nontemporal_load((const f32x4*)(CV + cb + (size_t)(32 + 2 * i) * (NH * HD)));
;         const float z = __builtin_bit_cast(float, zi);
;         const float e = __builtin_amdgcn_exp2f(-(z * k1 + k2));
;         const float be = __builtin_amdgcn_rcpf(1.0f + e), m = 1.0f - be;
;         float s = m;
; #pragma unroll
;         for (int o = 1; o < 64; o <<= 1) { const float t = __shfl_down(s, o); if (lane + o < 64) s *= t; }
;         const float tot = __shfl(s, 0);
;         const float sx = __shfl_down(s, 1);
;         const float a = be * (lane < 63 ? sx : 1.0f);
;         int itn = (int)(__builtin_amdgcn_readfirstlane(vn) >> 6); const bool more = itn < limit; itn = more ? itn + base : it;
;         const int bn = itn >> 11, hn = itn & 7, p0n = ((itn >> 3) & 255) * 64;
;         const int pagen = PT[bn * NPAGES + (p0n >> 7)];
;         const size_t cbn = (((size_t)pagen * PAGE + (p0n & 127)) * NH + hn) * HD + lo;
;         const size_t stepn = more ? (size_t)(NH * HD) : 0;
	v_add_f32_e32 v34, v34, v35
	v_add_f32_dpp v22, v22, v22 row_mirror row_mask:0xf bank_mask:0xf bound_ctrl:1
	v_add_f32_dpp v18, v18, v18 quad_perm:[2,3,0,1] row_mask:0xf bank_mask:0xf bound_ctrl:1
	v_add_f32_e32 v14, v15, v14
	v_fmac_f32_e32 v10, v12, v4
	v_pk_mul_f32 v[4:5], v[8:9], v[4:5]
	v_pk_mul_f32 v[2:3], v[6:7], v[2:3]
	v_readlane_b32 s2, v34, 0
	s_nop 3
	v_writelane_b32 v131, s2, 48
	ds_swizzle_b32 v23, v22 offset:swizzle(SWAP,16)
	v_add_f32_dpp v18, v18, v18 row_half_mirror row_mask:0xf bank_mask:0xf bound_ctrl:1
	v_add_f32_dpp v14, v14, v14 quad_perm:[1,0,3,2] row_mask:0xf bank_mask:0xf bound_ctrl:1
	v_pk_mov_b32 v[6:7], v[2:3], v[4:5] op_sel:[1,0]
	v_mov_b32_e32 v3, v5
	v_readlane_b32 s51, v34, 32
	v_writelane_b32 v131, s51, 49
	s_waitcnt lgkmcnt(2)
	v_add_f32_e32 v30, v30, v31
	v_add_f32_dpp v18, v18, v18 row_mirror row_mask:0xf bank_mask:0xf bound_ctrl:1
	v_add_f32_dpp v14, v14, v14 quad_perm:[2,3,0,1] row_mask:0xf bank_mask:0xf bound_ctrl:1
	v_add_f32_e32 v10, v11, v10
	v_pk_add_f32 v[2:3], v[6:7], v[2:3]
	v_readlane_b32 s2, v30, 0
	s_nop 3
	v_writelane_b32 v131, s2, 50
	ds_swizzle_b32 v19, v18 offset:swizzle(SWAP,16)
	v_add_f32_dpp v14, v14, v14 row_half_mirror row_mask:0xf bank_mask:0xf bound_ctrl:1
	v_add_f32_dpp v10, v10, v10 quad_perm:[1,0,3,2] row_mask:0xf bank_mask:0xf bound_ctrl:1
	v_add_f32_e32 v2, v2, v3
	v_readlane_b32 s51, v30, 32
	v_writelane_b32 v131, s51, 51
	s_waitcnt lgkmcnt(2)
	v_add_f32_e32 v26, v26, v27
	v_add_f32_dpp v14, v14, v14 row_mirror row_mask:0xf bank_mask:0xf bound_ctrl:1
	v_add_f32_dpp v10, v10, v10 quad_perm:[2,3,0,1] row_mask:0xf bank_mask:0xf bound_ctrl:1
	v_add_f32_dpp v2, v2, v2 quad_perm:[1,0,3,2] row_mask:0xf bank_mask:0xf bound_ctrl:1
	v_readlane_b32 s2, v26, 0
	s_nop 3
	v_writelane_b32 v131, s2, 52
	ds_swizzle_b32 v15, v14 offset:swizzle(SWAP,16)
	v_add_f32_dpp v10, v10, v10 row_half_mirror row_mask:0xf bank_mask:0xf bound_ctrl:1
	v_add_f32_dpp v2, v2, v2 quad_perm:[2,3,0,1] row_mask:0xf bank_mask:0xf bound_ctrl:1
	v_readlane_b32 s51, v26, 32
	v_writelane_b32 v131, s51, 53
	s_waitcnt lgkmcnt(2)
	v_add_f32_e32 v22, v22, v23
	v_add_f32_dpp v10, v10, v10 row_mirror row_mask:0xf bank_mask:0xf bound_ctrl:1
	v_add_f32_dpp v2, v2, v2 row_half_mirror row_mask:0xf bank_mask:0xf bound_ctrl:1
	v_readlane_b32 s2, v22, 0
	s_nop 3
	v_writelane_b32 v131, s2, 54
	ds_swizzle_b32 v11, v10 offset:swizzle(SWAP,16)
	v_add_f32_dpp v2, v2, v2 row_mirror row_mask:0xf bank_mask:0xf bound_ctrl:1
	v_readlane_b32 s51, v22, 32
	v_writelane_b32 v131, s51, 55
	s_waitcnt lgkmcnt(2)
	v_add_f32_e32 v18, v18, v19
	ds_swizzle_b32 v3, v2 offset:swizzle(SWAP,16)
	v_readlane_b32 s2, v18, 0
	s_nop 3
	v_writelane_b32 v131, s2, 56
	v_readlane_b32 s51, v18, 32
	v_writelane_b32 v131, s51, 57
	s_waitcnt lgkmcnt(2)
	v_add_f32_e32 v14, v14, v15
	s_waitcnt lgkmcnt(1)
	v_add_f32_e32 v10, v10, v11
	v_readlane_b32 s2, v14, 0
	s_nop 3
	v_writelane_b32 v131, s2, 58
	v_readlane_b32 s51, v14, 32
	v_writelane_b32 v131, s51, 59
	v_readlane_b32 s2, v10, 0
	v_readlane_b32 s51, v10, 32
	s_nop 3
	v_writelane_b32 v131, s2, 60
	s_waitcnt lgkmcnt(0)
	v_add_f32_e32 v2, v2, v3
	v_writelane_b32 v131, s51, 61
	s_bfe_u32 s78, s46, 0x80003
	v_readlane_b32 s2, v2, 0
	v_readlane_b32 s51, v2, 32
	v_add_co_u32_e32 v2, vcc, s62, v132
	s_nop 3
	v_writelane_b32 v131, s2, 62
	s_waitcnt vmcnt(17)
	v_readfirstlane_b32 s2, v253
	s_nop 0
	v_addc_co_u32_e32 v3, vcc, 0, v133, vcc
	v_add_co_u32_e32 v4, vcc, s63, v132
	v_writelane_b32 v131, s51, 63
	s_ashr_i32 s79, s2, 6
	s_nop 0
	v_addc_co_u32_e32 v5, vcc, 0, v133, vcc
	global_load_dwordx4 v[18:21], v[2:3], off nt
	global_load_dwordx4 v[6:9], v[4:5], off nt
	v_add_co_u32_e32 v2, vcc, s64, v132
	s_cmpk_lt_i32 s79, 0x2800
	s_nop 0
	v_addc_co_u32_e32 v3, vcc, 0, v133, vcc
	v_add_co_u32_e32 v4, vcc, s65, v132
	s_cselect_b64 s[54:55], -1, 0
	s_nop 0
	v_addc_co_u32_e32 v5, vcc, 0, v133, vcc
	s_cmpk_gt_i32 s79, 0x27ff
	global_load_dwordx4 v[14:17], v[2:3], off nt
	global_load_dwordx4 v[10:13], v[4:5], off nt
	v_add_co_u32_e32 v2, vcc, s66, v132
	s_cselect_b64 s[52:53], -1, 0
	s_addk_i32 s79, 0x1800
	v_addc_co_u32_e32 v3, vcc, 0, v133, vcc
	s_and_b64 s[80:81], s[54:55], exec
	v_add_co_u32_e32 v4, vcc, s67, v132
	s_cselect_b32 s51, s79, s46
	s_nop 0
	v_addc_co_u32_e32 v5, vcc, 0, v133, vcc
	s_ashr_i32 s46, s51, 11
	global_load_dwordx4 v[138:141], v[2:3], off nt
	global_load_dwordx4 v[142:145], v[4:5], off nt
	v_add_co_u32_e32 v2, vcc, s68, v132
	s_lshl_b32 s80, s46, 7
	s_bfe_u32 s81, s51, 0x70004
	v_addc_co_u32_e32 v3, vcc, 0, v133, vcc
	s_or_b32 s80, s80, s81
	v_add_co_u32_e32 v4, vcc, s69, v132
	s_ashr_i32 s81, s80, 31
	s_nop 0
	v_addc_co_u32_e32 v5, vcc, 0, v133, vcc
	s_and_b32 s2, s51, 7
	s_lshl_b64 s[80:81], s[80:81], 2
	global_load_dwordx4 v[146:149], v[2:3], off nt
	global_load_dwordx4 v[134:137], v[4:5], off nt
	s_waitcnt vmcnt(24)
	v_pk_mul_f32 v[4:5], v[130:131], s[48:49]
	s_add_u32 s80, s44, s80
	v_add_f32_e32 v4, v4, v5
	s_addc_u32 s81, s45, s81
	v_exp_f32_e64 v5, -v4
	global_load_dword v4, v1, s[80:81]
	v_add_co_u32_e32 v2, vcc, s70, v132
	v_add_f32_e32 v5, 1.0, v5
	s_nop 0
	v_addc_co_u32_e32 v3, vcc, 0, v133, vcc
	v_rcp_f32_e32 v5, v5
	v_add_co_u32_e32 v22, vcc, s71, v132
	v_and_b32_e32 v24, 63, v222
	s_nop 0
	v_addc_co_u32_e32 v23, vcc, 0, v133, vcc
	v_cmp_ne_u32_e32 vcc, 63, v24
	global_load_dwordx4 v[154:157], v[2:3], off nt
	global_load_dwordx4 v[150:153], v[22:23], off nt
	v_addc_co_u32_e32 v2, vcc, 0, v222, vcc
	v_sub_f32_e32 v22, 1.0, v5
	v_lshlrev_b32_e32 v25, 2, v2
	ds_bpermute_b32 v23, v25, v22
	v_add_co_u32_e32 v2, vcc, s72, v132
	v_and_b32_e32 v231, 64, v222
	s_nop 0
	v_addc_co_u32_e32 v3, vcc, 0, v133, vcc
	s_waitcnt lgkmcnt(0)
; __device__ __forceinline__ void sb_decode_stream(Frame& F, unsigned* qctr, int base, int limit) {
;     ...
;         float s = m;
; #pragma unroll
;         for (int o = 1; o < 64; o <<= 1) { const float t = __shfl_down(s, o); if (lane + o < 64) s *= t; }
;         const float tot = __shfl(s, 0);
;         const float sx = __shfl_down(s, 1);
;         const float a = be * (lane < 63 ? sx : 1.0f);
;         int itn = (int)(__builtin_amdgcn_readfirstlane(vn) >> 6); const bool more = itn < limit; itn = more ? itn + base : it;
;         const int bn = itn >> 11, hn = itn & 7, p0n = ((itn >> 3) & 255) * 64;
;         const int pagen = PT[bn * NPAGES + (p0n >> 7)];
;         const size_t cbn = (((size_t)pagen * PAGE + (p0n & 127)) * NH + hn) * HD + lo;
;         const size_t stepn = more ? (size_t)(NH * HD) : 0;
;         f32x4 o4 = {0.f, 0.f, 0.f, 0.f};
; #pragma unroll
;         for (int i = 0; i < 16; ++i) { const float aj = __shfl(a, 2 * i + half); o4 += aj * A[i]; }
	v_mul_f32_e32 v23, v22, v23
	v_cmp_gt_u32_e32 vcc, 62, v24
	v_cndmask_b32_e64 v26, v22, v23, s[6:7]
	s_lshl_b32 s51, s51, 6
	v_cndmask_b32_e64 v22, 0, 2, vcc
	v_add_lshl_u32 v22, v22, v222, 2
	ds_bpermute_b32 v27, v22, v26
	v_add_co_u32_e32 v22, vcc, s73, v132
	s_and_b32 s51, s51, 0x200
	s_nop 0
	v_addc_co_u32_e32 v23, vcc, 0, v133, vcc
	global_load_dwordx4 v[162:165], v[2:3], off nt
	global_load_dwordx4 v[158:161], v[22:23], off nt
	s_waitcnt lgkmcnt(0)
	v_mul_f32_e32 v2, v26, v27
	v_cmp_gt_u32_e32 vcc, 60, v24
	v_cndmask_b32_e64 v22, v26, v2, s[12:13]
	s_mulk_i32 s46, 0x7040
	v_cndmask_b32_e64 v2, 0, 4, vcc
	v_add_lshl_u32 v2, v2, v222, 2
	ds_bpermute_b32 v23, v2, v22
	v_add_co_u32_e32 v2, vcc, s74, v132
	v_or_b32_e32 v228, v231, v208
	s_nop 0
	v_addc_co_u32_e32 v3, vcc, 0, v133, vcc
	s_waitcnt lgkmcnt(0)
	v_mul_f32_e32 v23, v22, v23
	v_cmp_gt_u32_e32 vcc, 56, v24
	v_cndmask_b32_e64 v26, v22, v23, s[14:15]
	v_lshlrev_b32_e32 v228, 2, v228
	v_cndmask_b32_e64 v22, 0, 8, vcc
	v_add_lshl_u32 v22, v22, v222, 2
	ds_bpermute_b32 v27, v22, v26
	v_add_co_u32_e32 v22, vcc, s75, v132
	v_or_b32_e32 v230, v231, v209
	s_nop 0
	v_addc_co_u32_e32 v23, vcc, 0, v133, vcc
	global_load_dwordx4 v[170:173], v[2:3], off nt
	global_load_dwordx4 v[166:169], v[22:23], off nt
	s_waitcnt lgkmcnt(0)
	v_mul_f32_e32 v2, v26, v27
	v_cmp_gt_u32_e32 vcc, 48, v24
	v_cndmask_b32_e64 v22, v26, v2, s[16:17]
	v_lshlrev_b32_e32 v230, 2, v230
	v_cndmask_b32_e64 v2, 0, 16, vcc
	v_add_lshl_u32 v2, v2, v222, 2
	ds_bpermute_b32 v23, v2, v22
	v_add_co_u32_e32 v2, vcc, s76, v132
	v_or_b32_e32 v232, v231, v210
	s_nop 0
	v_addc_co_u32_e32 v3, vcc, 0, v133, vcc
	s_waitcnt lgkmcnt(0)
	v_mul_f32_e32 v23, v22, v23
	v_cndmask_b32_e64 v24, v22, v23, s[18:19]
	ds_bpermute_b32 v26, v223, v24
	v_add_co_u32_e32 v22, vcc, s77, v132
	v_lshlrev_b32_e32 v232, 2, v232
	s_nop 0
	v_addc_co_u32_e32 v23, vcc, 0, v133, vcc
	s_waitcnt lgkmcnt(0)
	v_mul_f32_e32 v26, v24, v26
	v_cndmask_b32_e64 v229, v24, v26, s[20:21]
	ds_bpermute_b32 v24, v25, v229
	global_load_dwordx4 v[178:181], v[2:3], off nt
	global_load_dwordx4 v[174:177], v[22:23], off nt
	v_or_b32_e32 v22, v231, v188
	v_lshlrev_b32_e32 v22, 2, v22
	v_or_b32_e32 v23, v231, v189
	s_waitcnt lgkmcnt(0)
	v_cndmask_b32_e64 v2, 1.0, v24, s[6:7]
	v_mul_f32_e32 v234, v5, v2
	s_waitcnt vmcnt(8)
	v_ashrrev_i32_e32 v5, 31, v4
	v_lshlrev_b64 v[2:3], 10, v[4:5]
	v_or_b32_e32 v4, v231, v183
	v_lshlrev_b32_e32 v4, 2, v4
	ds_bpermute_b32 v4, v4, v234
	ds_bpermute_b32 v22, v22, v234
	v_or_b32_e32 v2, s51, v2
	v_or_b32_e32 v2, s2, v2
	v_lshlrev_b32_e32 v23, 2, v23
	v_lshlrev_b64 v[2:3], 7, v[2:3]
	ds_bpermute_b32 v24, v23, v234
	v_or_b32_e32 v23, v231, v190
	v_lshl_add_u64 v[186:187], v[2:3], 0, v[184:185]
	s_waitcnt lgkmcnt(2)
	v_pk_fma_f32 v[2:3], v[126:127], v[4:5], 0 op_sel_hi:[1,0,0]
	v_pk_fma_f32 v[4:5], v[128:129], v[4:5], 0 op_sel_hi:[1,0,0]
	v_lshlrev_b32_e32 v23, 2, v23
	s_waitcnt lgkmcnt(1)
	v_pk_fma_f32 v[4:5], v[116:117], v[22:23], v[4:5] op_sel_hi:[1,0,1]
	v_pk_fma_f32 v[2:3], v[114:115], v[22:23], v[2:3] op_sel_hi:[1,0,1]
	v_or_b32_e32 v22, v231, v191
	ds_bpermute_b32 v26, v23, v234
	v_lshlrev_b32_e32 v22, 2, v22
	ds_bpermute_b32 v22, v22, v234
	v_or_b32_e32 v23, v231, v192
	v_lshlrev_b32_e32 v23, 2, v23
	s_waitcnt lgkmcnt(2)
	v_pk_fma_f32 v[2:3], v[122:123], v[24:25], v[2:3] op_sel_hi:[1,0,1]
	v_pk_fma_f32 v[4:5], v[124:125], v[24:25], v[4:5] op_sel_hi:[1,0,1]
	ds_bpermute_b32 v24, v23, v234
	v_or_b32_e32 v23, v231, v193
	s_waitcnt lgkmcnt(2)
	v_pk_fma_f32 v[4:5], v[120:121], v[26:27], v[4:5] op_sel_hi:[1,0,1]
	v_pk_fma_f32 v[2:3], v[118:119], v[26:27], v[2:3] op_sel_hi:[1,0,1]
	v_lshlrev_b32_e32 v23, 2, v23
	s_waitcnt lgkmcnt(1)
	v_pk_fma_f32 v[2:3], v[102:103], v[22:23], v[2:3] op_sel_hi:[1,0,1]
	v_pk_fma_f32 v[4:5], v[104:105], v[22:23], v[4:5] op_sel_hi:[1,0,1]
	v_or_b32_e32 v22, v231, v194
	ds_bpermute_b32 v26, v23, v234
	v_lshlrev_b32_e32 v22, 2, v22
	ds_bpermute_b32 v22, v22, v234
	v_or_b32_e32 v23, v231, v195
	v_lshlrev_b32_e32 v23, 2, v23
	s_waitcnt lgkmcnt(2)
	v_pk_fma_f32 v[4:5], v[108:109], v[24:25], v[4:5] op_sel_hi:[1,0,1]
	v_pk_fma_f32 v[2:3], v[106:107], v[24:25], v[2:3] op_sel_hi:[1,0,1]
	ds_bpermute_b32 v24, v23, v234
	v_or_b32_e32 v23, v231, v196
	s_waitcnt lgkmcnt(2)
	v_pk_fma_f32 v[2:3], v[110:111], v[26:27], v[2:3] op_sel_hi:[1,0,1]
	v_pk_fma_f32 v[4:5], v[112:113], v[26:27], v[4:5] op_sel_hi:[1,0,1]
	v_lshlrev_b32_e32 v23, 2, v23
	s_waitcnt lgkmcnt(1)
	v_pk_fma_f32 v[4:5], v[88:89], v[22:23], v[4:5] op_sel_hi:[1,0,1]
	v_pk_fma_f32 v[2:3], v[86:87], v[22:23], v[2:3] op_sel_hi:[1,0,1]
	v_or_b32_e32 v22, v231, v197
	ds_bpermute_b32 v26, v23, v234
	v_lshlrev_b32_e32 v22, 2, v22
	ds_bpermute_b32 v22, v22, v234
	v_or_b32_e32 v23, v231, v198
	v_lshlrev_b32_e32 v23, 2, v23
	s_waitcnt lgkmcnt(2)
	v_pk_fma_f32 v[2:3], v[98:99], v[24:25], v[2:3] op_sel_hi:[1,0,1]
	v_pk_fma_f32 v[4:5], v[100:101], v[24:25], v[4:5] op_sel_hi:[1,0,1]
	ds_bpermute_b32 v24, v23, v234
	v_or_b32_e32 v23, v231, v200
	v_lshlrev_b32_e32 v23, 2, v23
	s_waitcnt lgkmcnt(2)
	v_pk_fma_f32 v[4:5], v[96:97], v[26:27], v[4:5] op_sel_hi:[1,0,1]
	v_pk_fma_f32 v[2:3], v[94:95], v[26:27], v[2:3] op_sel_hi:[1,0,1]
	ds_bpermute_b32 v26, v23, v234
	s_waitcnt lgkmcnt(2)
	v_pk_fma_f32 v[2:3], v[70:71], v[22:23], v[2:3] op_sel_hi:[1,0,1]
	v_pk_fma_f32 v[4:5], v[72:73], v[22:23], v[4:5] op_sel_hi:[1,0,1]
	v_or_b32_e32 v22, v231, v201
	v_or_b32_e32 v23, v231, v202
	v_lshlrev_b32_e32 v22, 2, v22
	v_lshlrev_b32_e32 v23, 2, v23
	s_waitcnt lgkmcnt(1)
; __device__ __forceinline__ void sb_decode_stream(Frame& F, unsigned* qctr, int base, int limit) {
;     ...
;         for (int i = 0; i < 16; ++i) { const float aj = __shfl(a, 2 * i + half); o4 += aj * A[i]; }
;         const f32x4 q4n = *(const f32x4*)(SSP(S_PROJ) + (size_t)bn * IN_COLS + hn * HD + 4 * l32);
; #pragma unroll
;         for (int i = 0; i < 16; ++i) A[i] = __builtin_nontemporal_load((const f32x4*)(CK + cbn + (size_t)(2 * i) * stepn));
; #pragma unroll
;         for (int i = 0; i < 16; ++i) { const float aj = __shfl(a, 32 + 2 * i + half); o4 += aj * B[i]; }
; #pragma unroll
;         for (int i = 0; i < 16; ++i) B[i] = __builtin_nontemporal_load((const f32x4*)(CK + cbn + (size_t)(32 + 2 * i) * stepn));
	v_pk_fma_f32 v[4:5], v[76:77], v[24:25], v[4:5] op_sel_hi:[1,0,1]
	v_pk_fma_f32 v[2:3], v[74:75], v[24:25], v[2:3] op_sel_hi:[1,0,1]
	ds_bpermute_b32 v22, v22, v234
	ds_bpermute_b32 v24, v23, v234
	v_or_b32_e32 v23, v231, v203
	v_lshlrev_b32_e32 v23, 2, v23
	s_ashr_i32 s51, s46, 31
	s_waitcnt lgkmcnt(2)
	v_pk_fma_f32 v[2:3], v[82:83], v[26:27], v[2:3] op_sel_hi:[1,0,1]
	v_pk_fma_f32 v[4:5], v[84:85], v[26:27], v[4:5] op_sel_hi:[1,0,1]
	ds_bpermute_b32 v26, v23, v234
	s_add_u32 s46, s3, s46
	s_addc_u32 s51, s4, s51
	s_lshl_b32 s2, s2, 9
	s_add_u32 s80, s46, s2
	s_waitcnt lgkmcnt(2)
	v_pk_fma_f32 v[4:5], v[64:65], v[22:23], v[4:5] op_sel_hi:[1,0,1]
	v_pk_fma_f32 v[2:3], v[62:63], v[22:23], v[2:3] op_sel_hi:[1,0,1]
	s_addc_u32 s81, s51, 0
	s_waitcnt lgkmcnt(1)
	v_pk_fma_f32 v[2:3], v[90:91], v[24:25], v[2:3] op_sel_hi:[1,0,1]
	v_pk_fma_f32 v[4:5], v[92:93], v[24:25], v[4:5] op_sel_hi:[1,0,1]
	s_and_b64 s[54:55], s[54:55], exec
	s_waitcnt lgkmcnt(0)
	v_pk_fma_f32 v[22:23], v[80:81], v[26:27], v[4:5] op_sel_hi:[1,0,1]
	v_pk_fma_f32 v[24:25], v[78:79], v[26:27], v[2:3] op_sel_hi:[1,0,1]
	v_lshl_add_u64 v[26:27], v[186:187], 2, s[40:41]
	s_cselect_b32 s46, 0x2000, 0
	v_lshl_add_u64 v[28:29], v[26:27], 0, s[46:47]
	global_load_dwordx4 v[2:5], v221, s[80:81]
	global_load_dwordx4 v[130:133], v[26:27], off nt
	global_load_dwordx4 v[126:129], v[28:29], off nt
	v_lshl_add_u64 v[26:27], v[28:29], 0, s[46:47]
	v_lshl_add_u64 v[28:29], v[26:27], 0, s[46:47]
	global_load_dwordx4 v[122:125], v[26:27], off nt
	global_load_dwordx4 v[118:121], v[28:29], off nt
	v_lshl_add_u64 v[26:27], v[28:29], 0, s[46:47]
	v_lshl_add_u64 v[28:29], v[26:27], 0, s[46:47]
	global_load_dwordx4 v[114:117], v[26:27], off nt
	global_load_dwordx4 v[110:113], v[28:29], off nt
	v_lshl_add_u64 v[26:27], v[28:29], 0, s[46:47]
	v_lshl_add_u64 v[28:29], v[26:27], 0, s[46:47]
	global_load_dwordx4 v[106:109], v[26:27], off nt
	global_load_dwordx4 v[102:105], v[28:29], off nt
	v_lshl_add_u64 v[26:27], v[28:29], 0, s[46:47]
	v_or_b32_e32 v28, v231, v204
	v_lshlrev_b32_e32 v28, 2, v28
	ds_bpermute_b32 v28, v28, v234
	global_load_dwordx4 v[98:101], v[26:27], off nt
	v_lshl_add_u64 v[26:27], v[26:27], 0, s[46:47]
	global_load_dwordx4 v[94:97], v[26:27], off nt
	v_lshl_add_u64 v[26:27], v[26:27], 0, s[46:47]
	s_waitcnt lgkmcnt(0)
	v_pk_fma_f32 v[20:21], v[20:21], v[28:29], v[22:23] op_sel_hi:[1,0,1]
	v_or_b32_e32 v22, v231, v205
	v_or_b32_e32 v23, v231, v206
	v_lshlrev_b32_e32 v22, 2, v22
	v_lshlrev_b32_e32 v23, 2, v23
	v_pk_fma_f32 v[18:19], v[18:19], v[28:29], v[24:25] op_sel_hi:[1,0,1]
	ds_bpermute_b32 v22, v22, v234
	ds_bpermute_b32 v24, v23, v234
	v_or_b32_e32 v23, v231, v207
	v_lshlrev_b32_e32 v23, 2, v23
	global_load_dwordx4 v[90:93], v[26:27], off nt
	v_lshl_add_u64 v[26:27], v[26:27], 0, s[46:47]
	ds_bpermute_b32 v28, v23, v234
	global_load_dwordx4 v[86:89], v[26:27], off nt
	v_lshl_add_u64 v[26:27], v[26:27], 0, s[46:47]
	global_load_dwordx4 v[82:85], v[26:27], off nt
	v_lshl_add_u64 v[26:27], v[26:27], 0, s[46:47]
	global_load_dwordx4 v[74:77], v[26:27], off nt
	v_lshl_add_u64 v[26:27], v[26:27], 0, s[46:47]
	s_waitcnt lgkmcnt(2)
	v_pk_fma_f32 v[6:7], v[6:7], v[22:23], v[18:19] op_sel_hi:[1,0,1]
	global_load_dwordx4 v[70:73], v[26:27], off nt
	v_lshl_add_u64 v[26:27], v[26:27], 0, s[46:47]
	s_waitcnt lgkmcnt(1)
	v_pk_fma_f32 v[6:7], v[14:15], v[24:25], v[6:7] op_sel_hi:[1,0,1]
	v_pk_fma_f32 v[8:9], v[8:9], v[22:23], v[20:21] op_sel_hi:[1,0,1]
	s_waitcnt lgkmcnt(0)
	v_pk_fma_f32 v[226:227], v[10:11], v[28:29], v[6:7] op_sel_hi:[1,0,1]
	v_lshl_add_u64 v[6:7], v[26:27], 0, s[46:47]
	global_load_dwordx4 v[78:81], v[6:7], off nt
	v_lshl_add_u64 v[6:7], v[6:7], 0, s[46:47]
	global_load_dwordx4 v[66:69], v[6:7], off nt
	v_lshl_add_u64 v[6:7], v[6:7], 0, s[46:47]
	global_load_dwordx4 v[58:61], v[6:7], off nt
	v_lshl_add_u64 v[6:7], v[6:7], 0, s[46:47]
	global_load_dwordx4 v[54:57], v[6:7], off nt
	v_lshl_add_u64 v[6:7], v[6:7], 0, s[46:47]
	global_load_dwordx4 v[50:53], v[6:7], off nt
	v_lshl_add_u64 v[6:7], v[6:7], 0, s[46:47]
	global_load_dwordx4 v[46:49], v[6:7], off nt
	v_lshl_add_u64 v[6:7], v[6:7], 0, s[46:47]
	global_load_dwordx4 v[42:45], v[6:7], off nt
	v_lshl_add_u64 v[6:7], v[6:7], 0, s[46:47]
	global_load_dwordx4 v[38:41], v[6:7], off nt
	v_lshl_add_u64 v[6:7], v[6:7], 0, s[46:47]
	global_load_dwordx4 v[34:37], v[6:7], off nt
	v_lshl_add_u64 v[6:7], v[6:7], 0, s[46:47]
	v_pk_fma_f32 v[8:9], v[16:17], v[24:25], v[8:9] op_sel_hi:[1,0,1]
	global_load_dwordx4 v[30:33], v[6:7], off nt
	v_lshl_add_u64 v[6:7], v[6:7], 0, s[46:47]
	global_load_dwordx4 v[62:65], v[26:27], off nt
	v_pk_fma_f32 v[224:225], v[12:13], v[28:29], v[8:9] op_sel_hi:[1,0,1]
	global_load_dwordx4 v[26:29], v[6:7], off nt
	v_lshl_add_u64 v[6:7], v[6:7], 0, s[46:47]
	global_load_dwordx4 v[22:25], v[6:7], off nt
	v_lshl_add_u64 v[6:7], v[6:7], 0, s[46:47]
	global_load_dwordx4 v[18:21], v[6:7], off nt
	v_lshl_add_u64 v[6:7], v[6:7], 0, s[46:47]
	global_load_dwordx4 v[14:17], v[6:7], off nt
	v_lshl_add_u64 v[6:7], v[6:7], 0, s[46:47]
	global_load_dwordx4 v[10:13], v[6:7], off nt
	v_lshl_add_u64 v[6:7], v[6:7], 0, s[46:47]
	global_load_dwordx4 v[6:9], v[6:7], off nt
	ds_bpermute_b32 v228, v228, v234
	ds_bpermute_b32 v230, v230, v234
	ds_bpermute_b32 v232, v232, v234
	v_lshlrev_b32_e32 v233, 2, v231
	s_ashr_i32 s51, s50, 31
	s_waitcnt lgkmcnt(2)
; __device__ __forceinline__ void sb_decode_stream(Frame& F, unsigned* qctr, int base, int limit) {
;     ...
;         for (int i = 0; i < 16; ++i) { const float aj = __shfl(a, 32 + 2 * i + half); o4 += aj * B[i]; }
; #pragma unroll
;         for (int i = 0; i < 16; ++i) B[i] = __builtin_nontemporal_load((const f32x4*)(CK + cbn + (size_t)(32 + 2 * i) * stepn));
;         o4.x += __shfl_xor(o4.x, 32); o4.y += __shfl_xor(o4.y, 32); o4.z += __shfl_xor(o4.z, 32); o4.w += __shfl_xor(o4.w, 32);
;         float* P = SSP(S_PART) + ((size_t)bh * DSEG + blk) * DPART;
;         if (half == 0) *(f32x4*)(P + 4 * l32) = o4; if (lane == 0) P[128] = tot;
;         if (!more) break;
;         it = itn; cb = cbn; q4 = q4n;
	v_pk_fma_f32 v[138:139], v[138:139], v[228:229], v[226:227] op_sel_hi:[1,0,1]
	v_pk_fma_f32 v[140:141], v[140:141], v[228:229], v[224:225] op_sel_hi:[1,0,1]
	s_waitcnt lgkmcnt(1)
	v_pk_fma_f32 v[138:139], v[142:143], v[230:231], v[138:139] op_sel_hi:[1,0,1]
	v_or_b32_e32 v142, v231, v211
	v_lshlrev_b32_e32 v142, 2, v142
	ds_bpermute_b32 v142, v142, v234
	v_or_b32_e32 v143, v231, v212
	v_lshlrev_b32_e32 v143, 2, v143
	v_pk_fma_f32 v[140:141], v[144:145], v[230:231], v[140:141] op_sel_hi:[1,0,1]
	ds_bpermute_b32 v144, v143, v234
	v_or_b32_e32 v143, v231, v213
	s_waitcnt lgkmcnt(2)
	v_pk_fma_f32 v[138:139], v[146:147], v[232:233], v[138:139] op_sel_hi:[1,0,1]
	v_lshlrev_b32_e32 v143, 2, v143
	s_waitcnt lgkmcnt(1)
	v_pk_fma_f32 v[134:135], v[134:135], v[142:143], v[138:139] op_sel_hi:[1,0,1]
	v_or_b32_e32 v138, v231, v214
	ds_bpermute_b32 v146, v143, v234
	v_lshlrev_b32_e32 v138, 2, v138
	ds_bpermute_b32 v138, v138, v234
	v_pk_fma_f32 v[140:141], v[148:149], v[232:233], v[140:141] op_sel_hi:[1,0,1]
	v_or_b32_e32 v139, v231, v215
	v_pk_fma_f32 v[136:137], v[136:137], v[142:143], v[140:141] op_sel_hi:[1,0,1]
	v_lshlrev_b32_e32 v139, 2, v139
	s_waitcnt vmcnt(40) lgkmcnt(2)
	v_pk_fma_f32 v[134:135], v[154:155], v[144:145], v[134:135] op_sel_hi:[1,0,1]
	v_pk_fma_f32 v[136:137], v[156:157], v[144:145], v[136:137] op_sel_hi:[1,0,1]
	ds_bpermute_b32 v140, v139, v234
	v_or_b32_e32 v139, v231, v216
	s_waitcnt vmcnt(39) lgkmcnt(2)
	v_pk_fma_f32 v[136:137], v[152:153], v[146:147], v[136:137] op_sel_hi:[1,0,1]
	v_pk_fma_f32 v[134:135], v[150:151], v[146:147], v[134:135] op_sel_hi:[1,0,1]
	v_lshlrev_b32_e32 v139, 2, v139
	ds_bpermute_b32 v142, v139, v234
	s_waitcnt vmcnt(38) lgkmcnt(2)
	v_pk_fma_f32 v[134:135], v[162:163], v[138:139], v[134:135] op_sel_hi:[1,0,1]
	v_pk_fma_f32 v[136:137], v[164:165], v[138:139], v[136:137] op_sel_hi:[1,0,1]
	v_or_b32_e32 v138, v231, v218
	v_lshlrev_b32_e32 v138, 2, v138
	v_or_b32_e32 v139, v231, v219
	ds_bpermute_b32 v138, v138, v234
	v_lshlrev_b32_e32 v139, 2, v139
	s_waitcnt vmcnt(37) lgkmcnt(2)
	v_pk_fma_f32 v[136:137], v[160:161], v[140:141], v[136:137] op_sel_hi:[1,0,1]
	v_pk_fma_f32 v[134:135], v[158:159], v[140:141], v[134:135] op_sel_hi:[1,0,1]
	ds_bpermute_b32 v140, v139, v234
	v_or_b32_e32 v139, v231, v220
	v_lshlrev_b32_e32 v139, 2, v139
	s_waitcnt vmcnt(36) lgkmcnt(2)
	v_pk_fma_f32 v[134:135], v[170:171], v[142:143], v[134:135] op_sel_hi:[1,0,1]
	v_pk_fma_f32 v[136:137], v[172:173], v[142:143], v[136:137] op_sel_hi:[1,0,1]
	ds_bpermute_b32 v142, v139, v234
	s_waitcnt vmcnt(35) lgkmcnt(2)
	v_pk_fma_f32 v[136:137], v[168:169], v[138:139], v[136:137] op_sel_hi:[1,0,1]
	v_pk_fma_f32 v[134:135], v[166:167], v[138:139], v[134:135] op_sel_hi:[1,0,1]
	v_xor_b32_e32 v138, 32, v222
	v_add_u32_e32 v139, 64, v231
	v_cmp_lt_i32_e32 vcc, v138, v139
	s_waitcnt vmcnt(34) lgkmcnt(1)
	v_pk_fma_f32 v[134:135], v[178:179], v[140:141], v[134:135] op_sel_hi:[1,0,1]
	v_pk_fma_f32 v[136:137], v[180:181], v[140:141], v[136:137] op_sel_hi:[1,0,1]
	v_cndmask_b32_e32 v138, v222, v138, vcc
	s_waitcnt vmcnt(33) lgkmcnt(0)
	v_pk_fma_f32 v[136:137], v[176:177], v[142:143], v[136:137] op_sel_hi:[1,0,1]
	v_pk_fma_f32 v[134:135], v[174:175], v[142:143], v[134:135] op_sel_hi:[1,0,1]
	v_lshlrev_b32_e32 v141, 2, v138
	s_lshl_b64 s[50:51], s[50:51], 8
	ds_bpermute_b32 v142, v233, v229
	ds_bpermute_b32 v138, v141, v134
	ds_bpermute_b32 v139, v141, v135
	ds_bpermute_b32 v140, v141, v136
	ds_bpermute_b32 v141, v141, v137
	s_or_b32 s2, s50, s78
	s_mul_i32 s46, s51, 0x210
	s_mul_hi_u32 s50, s2, 0x210
	s_add_i32 s46, s50, s46
	s_mulk_i32 s2, 0x210
	s_add_u32 s50, s5, s2
	s_addc_u32 s51, s23, s46
	s_and_saveexec_b64 s[54:55], s[8:9]
	s_cbranch_execz .LBB0_1458
	s_waitcnt lgkmcnt(0)
	v_pk_add_f32 v[136:137], v[136:137], v[140:141]
	v_pk_add_f32 v[134:135], v[134:135], v[138:139]
	global_store_dwordx4 v221, v[134:137], s[50:51]
	s_or_b64 exec, exec, s[54:55]
	s_and_saveexec_b64 s[54:55], s[10:11]
	s_cbranch_execz .LBB0_1453
	s_branch .LBB0_1459
